# GEMM load segments: M0 write placed before the address v_lshl_add_u64 so that VALU supplies the M0 wait state and the s_nop 0 is dropped (61 sites)
# baseline (speedup 1.0000x reference)
; #define PG8_STAGE(bufoff, gbase, voff) do { _Pragma("unroll") for (int _i = 0; _i < 2; ++_i) \
;         __builtin_amdgcn_global_load_lds((const unsigned*)((const char*)(gbase) + (voff)[_i]), (PG8_LAS unsigned*)(lds + (bufoff) + ldsw + _i * 8192), 16, 0, 0); } while (0)
; #define PG8_LDA(dst, b, h) do { _Pragma("unroll") for (int m = 0; m < 4; ++m) _Pragma("unroll") for (int k = 0; k < 2; ++k) dst[m][k] = *(const PG8_LAS bf16x8*)(lds + PG8_SA(b, h) + aoff + m * 2048 + k * 1024); } while (0)
; #define PG8_LDB(dst, b, h) do { _Pragma("unroll") for (int n = 0; n < 2; ++n) _Pragma("unroll") for (int k = 0; k < 2; ++k) dst[n][k] = *(const PG8_LAS bf16x8*)(lds + PG8_SB(b, h) + boff + n * 2048 + k * 1024); } while (0)
; #define PG8_MMA(ai, bj, At, Bt) do { __builtin_amdgcn_s_setprio(1); _Pragma("unroll") for (int m = 0; m < 4; ++m) _Pragma("unroll") for (int n = 0; n < 2; ++n) _Pragma("unroll") for (int k = 0; k < 2; ++k) \
;         acc[ai][bj][m][n] = __builtin_amdgcn_mfma_f32_16x16x32_bf16(Bt[n][k], At[m][k], acc[ai][bj][m][n], 0, 0, 0); __builtin_amdgcn_s_setprio(0); } while (0)
; #define PG8_WAIT_V(n) asm volatile("s_waitcnt vmcnt(" #n ")" ::: "memory")
; #define PG8_BAR __builtin_amdgcn_s_barrier()
; template <class Epi, class Sched, bool ALIGN_EPI = false, bool SP2 = false>
; __device__ __forceinline__ void gemm_phase(PG8_LAS unsigned char* lds, const Gemm g, const Sched& S, const Epi& E, const int tid) {
;     ...
;         for (int t = 0; t < nt; t += 2) {
;             const bool last = (t == nt - 2);
;             const char* a1 = cA + (size_t)(t + 1) * kstep;
;             const char* a2 = last ? nA : cA + (size_t)(t + 2) * kstep; const char* b2 = last ? nB : cB + (size_t)(t + 2) * kstep;
;             const char* a3 = a2 + kstep; const char* b3 = b2 + kstep;
;             if (last && has_next) S.a_ready(nxt);
;             if constexpr (SP2) {
;             PG8_LDB(B0, 0, 0); PG8_LDB(B1, 0, 1); PG8_SCHED; PG8_LDA(At, 0, 0); PG8_STAGE(PG8_SA(1, 1), a1 + hstep, voffA);
;             PG8_WAIT_V(8); PG8_WAIT_L(0); PG8_BAR; PG8_MMA(0, 0, At, B0); PG8_MMA(0, 1, At, B1); PG8_BAR; PG8_SCHED;
;             PG8_LDA(At, 0, 1); PG8_STAGE(PG8_SB(0, 0), b2, voffB); PG8_STAGE(PG8_SB(0, 1), b2 + hstep, voffB); PG8_STAGE(PG8_SA(0, 0), a2, voffA);
;             PG8_WAIT_V(8); PG8_WAIT_L(0); PG8_BAR; PG8_MMA(1, 0, At, B0); PG8_MMA(1, 1, At, B1); PG8_BAR; PG8_SCHED;
.LBB0_137:
	s_add_u32 s16, s10, s14
	s_addc_u32 s17, s11, s15
	s_add_u32 s16, s16, 0x100
	s_addc_u32 s17, s17, 0
	s_add_u32 s52, s49, s14
	s_addc_u32 s53, s50, s15
	s_add_i32 s54, 0, 0x10000
	s_cmpk_eq_i32 s14, 0x1500
	s_cselect_b32 s19, s13, s17
	s_cselect_b32 s18, s12, s16
	v_add_u32_e32 v147, s54, v145
	s_cselect_b32 s17, s5, s53
	s_cselect_b32 s16, s4, s52
	s_add_i32 s55, 0, 0x14000
	ds_read_b128 v[148:151], v147
	ds_read_b128 v[152:155], v147 offset:1024
	ds_read_b128 v[160:163], v147 offset:2048
	ds_read_b128 v[164:167], v147 offset:3072
	v_add_u32_e32 v147, s55, v145
	ds_read_b128 v[168:171], v147
	ds_read_b128 v[172:175], v147 offset:1024
	ds_read_b128 v[176:179], v147 offset:2048
	ds_read_b128 v[180:183], v147 offset:3072
	v_lshl_add_u64 v[156:157], v[142:143], 0, s[14:15]
	s_add_i32 m0, s29, 0xc000
	ds_read_b128 v[184:187], v146
	ds_read_b128 v[188:191], v146 offset:1024
	ds_read_b128 v[192:195], v146 offset:2048
	ds_read_b128 v[196:199], v146 offset:3072
	ds_read_b128 v[200:203], v146 offset:4096
	ds_read_b128 v[206:209], v146 offset:5120
	ds_read_b128 v[214:217], v146 offset:6144
	ds_read_b128 v[218:221], v146 offset:7168
	global_load_lds_dwordx4 v[156:157], off
	s_add_i32 m0, s29, 0xe000
	v_lshl_add_u64 v[156:157], v[140:141], 0, s[14:15]
	global_load_lds_dwordx4 v[156:157], off
	s_waitcnt vmcnt(8) lgkmcnt(0)
	s_setprio 1
	s_barrier
	v_mfma_f32_16x16x32_bf16 v[32:35], v[148:151], v[184:187], v[32:35]
	v_mfma_f32_16x16x32_bf16 v[36:39], v[160:163], v[184:187], v[36:39]
	v_mfma_f32_16x16x32_bf16 v[48:51], v[148:151], v[192:195], v[48:51]
	v_mfma_f32_16x16x32_bf16 v[52:55], v[160:163], v[192:195], v[52:55]
	v_mfma_f32_16x16x32_bf16 v[56:59], v[148:151], v[200:203], v[56:59]
	v_mfma_f32_16x16x32_bf16 v[60:63], v[160:163], v[200:203], v[60:63]
	v_mfma_f32_16x16x32_bf16 v[74:77], v[148:151], v[214:217], v[74:77]
	v_mfma_f32_16x16x32_bf16 v[78:81], v[160:163], v[214:217], v[78:81]
	v_mfma_f32_16x16x32_bf16 v[32:35], v[152:155], v[188:191], v[32:35]
	v_mfma_f32_16x16x32_bf16 v[36:39], v[164:167], v[188:191], v[36:39]
	v_mfma_f32_16x16x32_bf16 v[48:51], v[152:155], v[196:199], v[48:51]
	v_mfma_f32_16x16x32_bf16 v[52:55], v[164:167], v[196:199], v[52:55]
	v_mfma_f32_16x16x32_bf16 v[56:59], v[152:155], v[206:209], v[56:59]
	v_mfma_f32_16x16x32_bf16 v[60:63], v[164:167], v[206:209], v[60:63]
	v_mfma_f32_16x16x32_bf16 v[74:77], v[152:155], v[218:221], v[74:77]
	v_mfma_f32_16x16x32_bf16 v[78:81], v[164:167], v[218:221], v[78:81]
	v_mfma_f32_16x16x32_bf16 v[106:109], v[168:171], v[184:187], v[106:109]
	v_mfma_f32_16x16x32_bf16 v[110:113], v[176:179], v[184:187], v[110:113]
	v_mfma_f32_16x16x32_bf16 v[102:105], v[168:171], v[192:195], v[102:105]
	v_mfma_f32_16x16x32_bf16 v[98:101], v[176:179], v[192:195], v[98:101]
	v_mfma_f32_16x16x32_bf16 v[70:73], v[168:171], v[200:203], v[70:73]
	v_mfma_f32_16x16x32_bf16 v[66:69], v[176:179], v[200:203], v[66:69]
	v_mfma_f32_16x16x32_bf16 v[44:47], v[168:171], v[214:217], v[44:47]
	v_mfma_f32_16x16x32_bf16 v[40:43], v[176:179], v[214:217], v[40:43]
	v_mfma_f32_16x16x32_bf16 v[106:109], v[172:175], v[188:191], v[106:109]
	v_mfma_f32_16x16x32_bf16 v[110:113], v[180:183], v[188:191], v[110:113]
	v_mfma_f32_16x16x32_bf16 v[102:105], v[172:175], v[196:199], v[102:105]
	v_mfma_f32_16x16x32_bf16 v[98:101], v[180:183], v[196:199], v[98:101]
	v_mfma_f32_16x16x32_bf16 v[70:73], v[172:175], v[206:209], v[70:73]
	v_mfma_f32_16x16x32_bf16 v[66:69], v[180:183], v[206:209], v[66:69]
	v_mfma_f32_16x16x32_bf16 v[44:47], v[172:175], v[218:221], v[44:47]
	v_mfma_f32_16x16x32_bf16 v[40:43], v[180:183], v[218:221], v[40:43]
	s_barrier
	s_setprio 0
	s_add_i32 s52, s54, s28
	v_lshl_add_u64 v[156:157], s[16:17], 0, v[64:65]
	s_mov_b32 m0, s52
	ds_read_b128 v[184:187], v146 offset:16384
	ds_read_b128 v[188:191], v146 offset:17408
	ds_read_b128 v[192:195], v146 offset:18432
	ds_read_b128 v[196:199], v146 offset:19456
	ds_read_b128 v[200:203], v146 offset:20480
	ds_read_b128 v[206:209], v146 offset:21504
	ds_read_b128 v[214:217], v146 offset:22528
	ds_read_b128 v[218:221], v146 offset:23552
	global_load_lds_dwordx4 v[156:157], off
	s_add_i32 m0, s52, 0x2000
	s_add_u32 s52, s16, 0xb0000
	v_lshl_add_u64 v[210:211], s[16:17], 0, v[130:131]
	s_addc_u32 s53, s17, 0
	s_add_i32 s54, s55, s28
	global_load_lds_dwordx4 v[210:211], off
	v_lshl_add_u64 v[222:223], s[52:53], 0, v[64:65]
	s_mov_b32 m0, s54
	v_lshl_add_u64 v[224:225], s[18:19], 0, v[132:133]
	global_load_lds_dwordx4 v[222:223], off
	s_add_i32 m0, s54, 0x2000
	v_lshl_add_u64 v[222:223], s[52:53], 0, v[130:131]
	global_load_lds_dwordx4 v[222:223], off
	s_mov_b32 m0, s29
	v_lshl_add_u64 v[222:223], s[18:19], 0, v[134:135]
	global_load_lds_dwordx4 v[222:223], off
	s_mov_b32 m0, s30
	s_nop 0
	global_load_lds_dwordx4 v[224:225], off
	s_waitcnt vmcnt(8) lgkmcnt(0)
	s_setprio 1
	s_barrier
; #define PG8_STAGE(bufoff, gbase, voff) do { _Pragma("unroll") for (int _i = 0; _i < 2; ++_i) \
;         __builtin_amdgcn_global_load_lds((const unsigned*)((const char*)(gbase) + (voff)[_i]), (PG8_LAS unsigned*)(lds + (bufoff) + ldsw + _i * 8192), 16, 0, 0); } while (0)
; #define PG8_LDA(dst, b, h) do { _Pragma("unroll") for (int m = 0; m < 4; ++m) _Pragma("unroll") for (int k = 0; k < 2; ++k) dst[m][k] = *(const PG8_LAS bf16x8*)(lds + PG8_SA(b, h) + aoff + m * 2048 + k * 1024); } while (0)
; #define PG8_LDB(dst, b, h) do { _Pragma("unroll") for (int n = 0; n < 2; ++n) _Pragma("unroll") for (int k = 0; k < 2; ++k) dst[n][k] = *(const PG8_LAS bf16x8*)(lds + PG8_SB(b, h) + boff + n * 2048 + k * 1024); } while (0)
; #define PG8_MMA(ai, bj, At, Bt) do { __builtin_amdgcn_s_setprio(1); _Pragma("unroll") for (int m = 0; m < 4; ++m) _Pragma("unroll") for (int n = 0; n < 2; ++n) _Pragma("unroll") for (int k = 0; k < 2; ++k) \
;         acc[ai][bj][m][n] = __builtin_amdgcn_mfma_f32_16x16x32_bf16(Bt[n][k], At[m][k], acc[ai][bj][m][n], 0, 0, 0); __builtin_amdgcn_s_setprio(0); } while (0)
; #define PG8_WAIT_V(n) asm volatile("s_waitcnt vmcnt(" #n ")" ::: "memory")
; #define PG8_WAIT_L(n) asm volatile("s_waitcnt lgkmcnt(" #n ")" ::: "memory")
; #define PG8_BAR __builtin_amdgcn_s_barrier()
; #define PG8_SCHED __builtin_amdgcn_sched_barrier(0)
; template <class Epi, class Sched, bool ALIGN_EPI = false, bool SP2 = false>
; __device__ __forceinline__ void gemm_phase(PG8_LAS unsigned char* lds, const Gemm g, const Sched& S, const Epi& E, const int tid) {
;     ...
;             PG8_WAIT_V(8); PG8_WAIT_L(0); PG8_BAR; PG8_MMA(1, 0, At, B0); PG8_MMA(1, 1, At, B1); PG8_BAR; PG8_SCHED;
;             PG8_LDB(B0, 1, 0); PG8_LDB(B1, 1, 1); PG8_SCHED; PG8_LDA(At, 1, 0); PG8_STAGE(PG8_SA(0, 1), a2 + hstep, voffA);
;             PG8_WAIT_V(8); PG8_WAIT_L(0); PG8_BAR; PG8_MMA(0, 0, At, B0); PG8_MMA(0, 1, At, B1); PG8_BAR; PG8_SCHED;
	v_mfma_f32_16x16x32_bf16 v[82:85], v[148:151], v[184:187], v[82:85]
	v_mfma_f32_16x16x32_bf16 v[86:89], v[160:163], v[184:187], v[86:89]
	v_mfma_f32_16x16x32_bf16 v[90:93], v[148:151], v[192:195], v[90:93]
	v_mfma_f32_16x16x32_bf16 v[94:97], v[160:163], v[192:195], v[94:97]
	v_mfma_f32_16x16x32_bf16 v[114:117], v[148:151], v[200:203], v[114:117]
	v_mfma_f32_16x16x32_bf16 v[118:121], v[160:163], v[200:203], v[118:121]
	v_mfma_f32_16x16x32_bf16 v[122:125], v[148:151], v[214:217], v[122:125]
	v_mfma_f32_16x16x32_bf16 v[126:129], v[160:163], v[214:217], v[126:129]
	v_mfma_f32_16x16x32_bf16 v[82:85], v[152:155], v[188:191], v[82:85]
	v_mfma_f32_16x16x32_bf16 v[86:89], v[164:167], v[188:191], v[86:89]
	v_mfma_f32_16x16x32_bf16 v[90:93], v[152:155], v[196:199], v[90:93]
	v_mfma_f32_16x16x32_bf16 v[94:97], v[164:167], v[196:199], v[94:97]
	v_mfma_f32_16x16x32_bf16 v[114:117], v[152:155], v[206:209], v[114:117]
	v_mfma_f32_16x16x32_bf16 v[118:121], v[164:167], v[206:209], v[118:121]
	v_mfma_f32_16x16x32_bf16 v[122:125], v[152:155], v[218:221], v[122:125]
	v_mfma_f32_16x16x32_bf16 v[126:129], v[164:167], v[218:221], v[126:129]
	v_mfma_f32_16x16x32_bf16 v[28:31], v[168:171], v[184:187], v[28:31]
	v_mfma_f32_16x16x32_bf16 v[24:27], v[176:179], v[184:187], v[24:27]
	v_mfma_f32_16x16x32_bf16 v[20:23], v[168:171], v[192:195], v[20:23]
	v_mfma_f32_16x16x32_bf16 v[16:19], v[176:179], v[192:195], v[16:19]
	v_mfma_f32_16x16x32_bf16 v[12:15], v[168:171], v[200:203], v[12:15]
	v_mfma_f32_16x16x32_bf16 v[8:11], v[176:179], v[200:203], v[8:11]
	v_mfma_f32_16x16x32_bf16 v[4:7], v[168:171], v[214:217], v[4:7]
	v_mfma_f32_16x16x32_bf16 v[0:3], v[176:179], v[214:217], v[0:3]
	v_mfma_f32_16x16x32_bf16 v[28:31], v[172:175], v[188:191], v[28:31]
	v_mfma_f32_16x16x32_bf16 v[24:27], v[180:183], v[188:191], v[24:27]
	v_mfma_f32_16x16x32_bf16 v[20:23], v[172:175], v[196:199], v[20:23]
	v_mfma_f32_16x16x32_bf16 v[16:19], v[180:183], v[196:199], v[16:19]
	v_mfma_f32_16x16x32_bf16 v[12:15], v[172:175], v[206:209], v[12:15]
	v_mfma_f32_16x16x32_bf16 v[8:11], v[180:183], v[206:209], v[8:11]
	v_mfma_f32_16x16x32_bf16 v[4:7], v[172:175], v[218:221], v[4:7]
	v_mfma_f32_16x16x32_bf16 v[0:3], v[180:183], v[218:221], v[0:3]
	s_barrier
	s_setprio 0
	s_add_i32 s52, 0, 0x18000
	v_add_u32_e32 v147, s52, v145
	s_add_i32 s53, 0, 0x1c000
	ds_read_b128 v[148:151], v147
	ds_read_b128 v[152:155], v147 offset:1024
	ds_read_b128 v[160:163], v147 offset:2048
	ds_read_b128 v[164:167], v147 offset:3072
	v_add_u32_e32 v147, s53, v145
	ds_read_b128 v[168:171], v147
	ds_read_b128 v[172:175], v147 offset:1024
	ds_read_b128 v[176:179], v147 offset:2048
	ds_read_b128 v[180:183], v147 offset:3072
	s_add_u32 s18, s18, 0xb0000
	s_addc_u32 s19, s19, 0
	s_mov_b32 m0, s31
	v_lshl_add_u64 v[226:227], s[18:19], 0, v[134:135]
	ds_read_b128 v[184:187], v146 offset:32768
	ds_read_b128 v[188:191], v146 offset:33792
	ds_read_b128 v[192:195], v146 offset:34816
	ds_read_b128 v[196:199], v146 offset:35840
	ds_read_b128 v[200:203], v146 offset:36864
	ds_read_b128 v[206:209], v146 offset:37888
	ds_read_b128 v[214:217], v146 offset:38912
	ds_read_b128 v[218:221], v146 offset:39936
	global_load_lds_dwordx4 v[226:227], off
	s_mov_b32 m0, s34
	v_lshl_add_u64 v[226:227], s[18:19], 0, v[132:133]
	global_load_lds_dwordx4 v[226:227], off
	s_waitcnt vmcnt(8) lgkmcnt(0)
	s_setprio 1
	s_barrier
	v_mfma_f32_16x16x32_bf16 v[32:35], v[148:151], v[184:187], v[32:35]
	v_mfma_f32_16x16x32_bf16 v[36:39], v[160:163], v[184:187], v[36:39]
	v_mfma_f32_16x16x32_bf16 v[48:51], v[148:151], v[192:195], v[48:51]
	v_mfma_f32_16x16x32_bf16 v[52:55], v[160:163], v[192:195], v[52:55]
	v_mfma_f32_16x16x32_bf16 v[56:59], v[148:151], v[200:203], v[56:59]
	v_mfma_f32_16x16x32_bf16 v[60:63], v[160:163], v[200:203], v[60:63]
	v_mfma_f32_16x16x32_bf16 v[74:77], v[148:151], v[214:217], v[74:77]
	v_mfma_f32_16x16x32_bf16 v[78:81], v[160:163], v[214:217], v[78:81]
	v_mfma_f32_16x16x32_bf16 v[32:35], v[152:155], v[188:191], v[32:35]
	v_mfma_f32_16x16x32_bf16 v[36:39], v[164:167], v[188:191], v[36:39]
	v_mfma_f32_16x16x32_bf16 v[48:51], v[152:155], v[196:199], v[48:51]
	v_mfma_f32_16x16x32_bf16 v[52:55], v[164:167], v[196:199], v[52:55]
	v_mfma_f32_16x16x32_bf16 v[56:59], v[152:155], v[206:209], v[56:59]
	v_mfma_f32_16x16x32_bf16 v[60:63], v[164:167], v[206:209], v[60:63]
	v_mfma_f32_16x16x32_bf16 v[74:77], v[152:155], v[218:221], v[74:77]
	v_mfma_f32_16x16x32_bf16 v[78:81], v[164:167], v[218:221], v[78:81]
	v_mfma_f32_16x16x32_bf16 v[106:109], v[168:171], v[184:187], v[106:109]
	v_mfma_f32_16x16x32_bf16 v[110:113], v[176:179], v[184:187], v[110:113]
	v_mfma_f32_16x16x32_bf16 v[102:105], v[168:171], v[192:195], v[102:105]
	v_mfma_f32_16x16x32_bf16 v[98:101], v[176:179], v[192:195], v[98:101]
	v_mfma_f32_16x16x32_bf16 v[70:73], v[168:171], v[200:203], v[70:73]
	v_mfma_f32_16x16x32_bf16 v[66:69], v[176:179], v[200:203], v[66:69]
	v_mfma_f32_16x16x32_bf16 v[44:47], v[168:171], v[214:217], v[44:47]
	v_mfma_f32_16x16x32_bf16 v[40:43], v[176:179], v[214:217], v[40:43]
	v_mfma_f32_16x16x32_bf16 v[106:109], v[172:175], v[188:191], v[106:109]
	v_mfma_f32_16x16x32_bf16 v[110:113], v[180:183], v[188:191], v[110:113]
	v_mfma_f32_16x16x32_bf16 v[102:105], v[172:175], v[196:199], v[102:105]
	v_mfma_f32_16x16x32_bf16 v[98:101], v[180:183], v[196:199], v[98:101]
	v_mfma_f32_16x16x32_bf16 v[70:73], v[172:175], v[206:209], v[70:73]
	v_mfma_f32_16x16x32_bf16 v[66:69], v[180:183], v[206:209], v[66:69]
	v_mfma_f32_16x16x32_bf16 v[44:47], v[172:175], v[218:221], v[44:47]
	v_mfma_f32_16x16x32_bf16 v[40:43], v[180:183], v[218:221], v[40:43]
	s_barrier
; #define PG8_STAGE(bufoff, gbase, voff) do { _Pragma("unroll") for (int _i = 0; _i < 2; ++_i) \
;         __builtin_amdgcn_global_load_lds((const unsigned*)((const char*)(gbase) + (voff)[_i]), (PG8_LAS unsigned*)(lds + (bufoff) + ldsw + _i * 8192), 16, 0, 0); } while (0)
; #define PG8_LDA(dst, b, h) do { _Pragma("unroll") for (int m = 0; m < 4; ++m) _Pragma("unroll") for (int k = 0; k < 2; ++k) dst[m][k] = *(const PG8_LAS bf16x8*)(lds + PG8_SA(b, h) + aoff + m * 2048 + k * 1024); } while (0)
; #define PG8_MMA(ai, bj, At, Bt) do { __builtin_amdgcn_s_setprio(1); _Pragma("unroll") for (int m = 0; m < 4; ++m) _Pragma("unroll") for (int n = 0; n < 2; ++n) _Pragma("unroll") for (int k = 0; k < 2; ++k) \
;         acc[ai][bj][m][n] = __builtin_amdgcn_mfma_f32_16x16x32_bf16(Bt[n][k], At[m][k], acc[ai][bj][m][n], 0, 0, 0); __builtin_amdgcn_s_setprio(0); } while (0)
; #define PG8_WAIT_V(n) asm volatile("s_waitcnt vmcnt(" #n ")" ::: "memory")
; #define PG8_WAIT_L(n) asm volatile("s_waitcnt lgkmcnt(" #n ")" ::: "memory")
; #define PG8_BAR __builtin_amdgcn_s_barrier()
; #define PG8_SCHED __builtin_amdgcn_sched_barrier(0)
; template <class Epi, class Sched, bool ALIGN_EPI = false, bool SP2 = false>
; __device__ __forceinline__ void gemm_phase(PG8_LAS unsigned char* lds, const Gemm g, const Sched& S, const Epi& E, const int tid) {
;     ...
;             PG8_LDA(At, 1, 1); PG8_STAGE(PG8_SB(1, 0), b3, voffB); PG8_STAGE(PG8_SB(1, 1), b3 + hstep, voffB); PG8_STAGE(PG8_SA(1, 0), a3, voffA);
;             PG8_WAIT_V(8); PG8_WAIT_L(0); PG8_BAR; PG8_MMA(1, 0, At, B0); PG8_MMA(1, 1, At, B1); PG8_BAR; PG8_SCHED;
;     ...
;         if (!has_next) break;
; #pragma unroll
;         for (int a = 0; a < 2; ++a)
; #pragma unroll
;             for (int b = 0; b < 2; ++b)
; #pragma unroll
;                 for (int m = 0; m < 4; ++m)
; #pragma unroll
;                     for (int n = 0; n < 2; ++n) acc[a][b][m][n] = (f32x4){0.f, 0.f, 0.f, 0.f};
	s_setprio 0
	s_add_i32 s18, s52, s28
	v_lshl_add_u64 v[156:157], v[156:157], 0, s[94:95]
	s_mov_b32 m0, s18
	ds_read_b128 v[184:187], v146 offset:49152
	ds_read_b128 v[188:191], v146 offset:50176
	ds_read_b128 v[192:195], v146 offset:51200
	ds_read_b128 v[196:199], v146 offset:52224
	ds_read_b128 v[200:203], v146 offset:53248
	ds_read_b128 v[206:209], v146 offset:54272
	ds_read_b128 v[214:217], v146 offset:55296
	ds_read_b128 v[218:221], v146 offset:56320
	global_load_lds_dwordx4 v[156:157], off
	s_add_i32 m0, s18, 0x2000
	s_add_u32 s16, s16, 0xb0080
	v_lshl_add_u64 v[156:157], v[210:211], 0, s[94:95]
	s_addc_u32 s17, s17, 0
	s_add_i32 s18, s53, s28
	global_load_lds_dwordx4 v[156:157], off
	s_mov_b32 m0, s18
	v_lshl_add_u64 v[156:157], s[16:17], 0, v[64:65]
	global_load_lds_dwordx4 v[156:157], off
	s_add_i32 m0, s18, 0x2000
	v_lshl_add_u64 v[156:157], s[16:17], 0, v[130:131]
	global_load_lds_dwordx4 v[156:157], off
	s_mov_b32 m0, s42
	v_lshl_add_u64 v[156:157], v[222:223], 0, s[94:95]
	global_load_lds_dwordx4 v[156:157], off
	s_mov_b32 m0, s44
	v_lshl_add_u64 v[156:157], v[224:225], 0, s[94:95]
	global_load_lds_dwordx4 v[156:157], off
	s_waitcnt vmcnt(8) lgkmcnt(0)
	s_setprio 1
	s_barrier
	v_mfma_f32_16x16x32_bf16 v[82:85], v[148:151], v[184:187], v[82:85]
	v_mfma_f32_16x16x32_bf16 v[86:89], v[160:163], v[184:187], v[86:89]
	v_mfma_f32_16x16x32_bf16 v[90:93], v[148:151], v[192:195], v[90:93]
	v_mfma_f32_16x16x32_bf16 v[94:97], v[160:163], v[192:195], v[94:97]
	v_mfma_f32_16x16x32_bf16 v[114:117], v[148:151], v[200:203], v[114:117]
	v_mfma_f32_16x16x32_bf16 v[118:121], v[160:163], v[200:203], v[118:121]
	v_mfma_f32_16x16x32_bf16 v[122:125], v[148:151], v[214:217], v[122:125]
	v_mfma_f32_16x16x32_bf16 v[126:129], v[160:163], v[214:217], v[126:129]
	v_mfma_f32_16x16x32_bf16 v[82:85], v[152:155], v[188:191], v[82:85]
	v_mfma_f32_16x16x32_bf16 v[86:89], v[164:167], v[188:191], v[86:89]
	v_mfma_f32_16x16x32_bf16 v[90:93], v[152:155], v[196:199], v[90:93]
	v_mfma_f32_16x16x32_bf16 v[94:97], v[164:167], v[196:199], v[94:97]
	v_mfma_f32_16x16x32_bf16 v[114:117], v[152:155], v[206:209], v[114:117]
	v_mfma_f32_16x16x32_bf16 v[118:121], v[164:167], v[206:209], v[118:121]
	v_mfma_f32_16x16x32_bf16 v[122:125], v[152:155], v[218:221], v[122:125]
	v_mfma_f32_16x16x32_bf16 v[126:129], v[164:167], v[218:221], v[126:129]
	v_mfma_f32_16x16x32_bf16 v[28:31], v[168:171], v[184:187], v[28:31]
	v_mfma_f32_16x16x32_bf16 v[24:27], v[176:179], v[184:187], v[24:27]
	v_mfma_f32_16x16x32_bf16 v[20:23], v[168:171], v[192:195], v[20:23]
	v_mfma_f32_16x16x32_bf16 v[16:19], v[176:179], v[192:195], v[16:19]
	v_mfma_f32_16x16x32_bf16 v[12:15], v[168:171], v[200:203], v[12:15]
	v_mfma_f32_16x16x32_bf16 v[8:11], v[176:179], v[200:203], v[8:11]
	v_mfma_f32_16x16x32_bf16 v[4:7], v[168:171], v[214:217], v[4:7]
	v_mfma_f32_16x16x32_bf16 v[0:3], v[176:179], v[214:217], v[0:3]
	v_mfma_f32_16x16x32_bf16 v[28:31], v[172:175], v[188:191], v[28:31]
	v_mfma_f32_16x16x32_bf16 v[24:27], v[180:183], v[188:191], v[24:27]
	v_mfma_f32_16x16x32_bf16 v[20:23], v[172:175], v[196:199], v[20:23]
	v_mfma_f32_16x16x32_bf16 v[16:19], v[180:183], v[196:199], v[16:19]
	v_mfma_f32_16x16x32_bf16 v[12:15], v[172:175], v[206:209], v[12:15]
	v_mfma_f32_16x16x32_bf16 v[8:11], v[180:183], v[206:209], v[8:11]
	v_mfma_f32_16x16x32_bf16 v[4:7], v[172:175], v[218:221], v[4:7]
	v_mfma_f32_16x16x32_bf16 v[0:3], v[180:183], v[218:221], v[0:3]
	s_barrier
	s_setprio 0
	s_add_i32 s51, s51, 2
	s_add_u32 s14, s14, 0x100
	s_addc_u32 s15, s15, 0
	s_cmp_gt_u32 s51, 41
	s_cbranch_scc0 .LBB0_137
	s_add_u32 s14, s49, 0xffffff00
	s_addc_u32 s15, s50, -1
	s_and_b64 vcc, exec, s[2:3]
	s_cbranch_vccnz .LBB0_140
	v_mov_b32_e32 v0, 0
	s_mov_b32 s8, s46
	s_mov_b32 s22, s47
	s_mov_b64 s[10:11], s[12:13]
	s_mov_b32 s45, s48
	v_mov_b32_e32 v1, v0
	v_mov_b32_e32 v2, v0
	v_mov_b32_e32 v3, v0
	v_mov_b32_e32 v4, v0
	v_mov_b32_e32 v5, v0
	v_mov_b32_e32 v6, v0
	v_mov_b32_e32 v7, v0
	v_mov_b32_e32 v8, v0
	v_mov_b32_e32 v9, v0
	v_mov_b32_e32 v10, v0
	v_mov_b32_e32 v11, v0
	v_mov_b32_e32 v12, v0
	v_mov_b32_e32 v13, v0
	v_mov_b32_e32 v14, v0
	v_mov_b32_e32 v15, v0
	v_mov_b32_e32 v16, v0
	v_mov_b32_e32 v17, v0
	v_mov_b32_e32 v18, v0
	v_mov_b32_e32 v19, v0
	v_mov_b32_e32 v20, v0
	v_mov_b32_e32 v21, v0
	v_mov_b32_e32 v22, v0
	v_mov_b32_e32 v23, v0
	v_mov_b32_e32 v24, v0
	v_mov_b32_e32 v25, v0
	v_mov_b32_e32 v26, v0
	v_mov_b32_e32 v27, v0
	v_mov_b32_e32 v28, v0
	v_mov_b32_e32 v29, v0
	v_mov_b32_e32 v30, v0
	v_mov_b32_e32 v31, v0
	v_mov_b32_e32 v126, v0
	v_mov_b32_e32 v127, v0
	v_mov_b32_e32 v128, v0
	v_mov_b32_e32 v129, v0
	v_mov_b32_e32 v122, v0
	v_mov_b32_e32 v123, v0
	v_mov_b32_e32 v124, v0
	v_mov_b32_e32 v125, v0
	v_mov_b32_e32 v118, v0
	v_mov_b32_e32 v119, v0
	v_mov_b32_e32 v120, v0
	v_mov_b32_e32 v121, v0
	v_mov_b32_e32 v114, v0
	v_mov_b32_e32 v115, v0
	v_mov_b32_e32 v116, v0
	v_mov_b32_e32 v117, v0
	v_mov_b32_e32 v94, v0
	v_mov_b32_e32 v95, v0
	v_mov_b32_e32 v96, v0
	v_mov_b32_e32 v97, v0
	v_mov_b32_e32 v90, v0
	v_mov_b32_e32 v91, v0
	v_mov_b32_e32 v92, v0
	v_mov_b32_e32 v93, v0
	v_mov_b32_e32 v86, v0
	v_mov_b32_e32 v87, v0
	v_mov_b32_e32 v88, v0
	v_mov_b32_e32 v89, v0
	v_mov_b32_e32 v82, v0
	v_mov_b32_e32 v83, v0
	v_mov_b32_e32 v84, v0
	v_mov_b32_e32 v85, v0
	v_mov_b32_e32 v40, v0
	v_mov_b32_e32 v41, v0
	v_mov_b32_e32 v42, v0
	v_mov_b32_e32 v43, v0
	v_mov_b32_e32 v44, v0
	v_mov_b32_e32 v45, v0
	v_mov_b32_e32 v46, v0
	v_mov_b32_e32 v47, v0
	v_mov_b32_e32 v66, v0
	v_mov_b32_e32 v67, v0
	v_mov_b32_e32 v68, v0
	v_mov_b32_e32 v69, v0
	v_mov_b32_e32 v70, v0
	v_mov_b32_e32 v71, v0
	v_mov_b32_e32 v72, v0
	v_mov_b32_e32 v73, v0
	v_mov_b32_e32 v98, v0
	v_mov_b32_e32 v99, v0
	v_mov_b32_e32 v100, v0
	v_mov_b32_e32 v101, v0
	v_mov_b32_e32 v102, v0
	v_mov_b32_e32 v103, v0
	v_mov_b32_e32 v104, v0
	v_mov_b32_e32 v105, v0
	v_mov_b32_e32 v110, v0
	v_mov_b32_e32 v111, v0
	v_mov_b32_e32 v112, v0
	v_mov_b32_e32 v113, v0
	v_mov_b32_e32 v106, v0
	v_mov_b32_e32 v107, v0
	v_mov_b32_e32 v108, v0
	v_mov_b32_e32 v109, v0
	v_mov_b32_e32 v78, v0
	v_mov_b32_e32 v79, v0
	v_mov_b32_e32 v80, v0
	v_mov_b32_e32 v81, v0
	v_mov_b32_e32 v74, v0
	v_mov_b32_e32 v75, v0
	v_mov_b32_e32 v76, v0
	v_mov_b32_e32 v77, v0
	v_mov_b32_e32 v60, v0
	v_mov_b32_e32 v61, v0
	v_mov_b32_e32 v62, v0
	v_mov_b32_e32 v63, v0
	v_mov_b32_e32 v56, v0
	v_mov_b32_e32 v57, v0
	v_mov_b32_e32 v58, v0
	v_mov_b32_e32 v59, v0
	v_mov_b32_e32 v52, v0
	v_mov_b32_e32 v53, v0
	v_mov_b32_e32 v54, v0
	v_mov_b32_e32 v55, v0
	v_mov_b32_e32 v48, v0
	v_mov_b32_e32 v49, v0
	v_mov_b32_e32 v50, v0
	v_mov_b32_e32 v51, v0
	v_mov_b32_e32 v36, v0
	v_mov_b32_e32 v37, v0
	v_mov_b32_e32 v38, v0
	v_mov_b32_e32 v39, v0
	v_mov_b32_e32 v32, v0
	v_mov_b32_e32 v33, v0
	v_mov_b32_e32 v34, v0
	v_mov_b32_e32 v35, v0
	s_andn2_b64 vcc, exec, s[0:1]
	s_cbranch_vccnz .LBB0_141
	s_branch .LBB0_142

; #define PG8_STAGE(bufoff, gbase, voff) do { _Pragma("unroll") for (int _i = 0; _i < 2; ++_i) \
;         __builtin_amdgcn_global_load_lds((const unsigned*)((const char*)(gbase) + (voff)[_i]), (PG8_LAS unsigned*)(lds + (bufoff) + ldsw + _i * 8192), 16, 0, 0); } while (0)
; #define PG8_LDA(dst, b, h) do { _Pragma("unroll") for (int m = 0; m < 4; ++m) _Pragma("unroll") for (int k = 0; k < 2; ++k) dst[m][k] = *(const PG8_LAS bf16x8*)(lds + PG8_SA(b, h) + aoff + m * 2048 + k * 1024); } while (0)
; #define PG8_LDB(dst, b, h) do { _Pragma("unroll") for (int n = 0; n < 2; ++n) _Pragma("unroll") for (int k = 0; k < 2; ++k) dst[n][k] = *(const PG8_LAS bf16x8*)(lds + PG8_SB(b, h) + boff + n * 2048 + k * 1024); } while (0)
; #define PG8_MMA(ai, bj, At, Bt) do { __builtin_amdgcn_s_setprio(1); _Pragma("unroll") for (int m = 0; m < 4; ++m) _Pragma("unroll") for (int n = 0; n < 2; ++n) _Pragma("unroll") for (int k = 0; k < 2; ++k) \
;         acc[ai][bj][m][n] = __builtin_amdgcn_mfma_f32_16x16x32_bf16(Bt[n][k], At[m][k], acc[ai][bj][m][n], 0, 0, 0); __builtin_amdgcn_s_setprio(0); } while (0)
; #define PG8_WAIT_V(n) asm volatile("s_waitcnt vmcnt(" #n ")" ::: "memory")
; #define PG8_BAR __builtin_amdgcn_s_barrier()
; template <class Epi, class Sched, bool ALIGN_EPI = false, bool SP2 = false>
; __device__ __forceinline__ void gemm_phase(PG8_LAS unsigned char* lds, const Gemm g, const Sched& S, const Epi& E, const int tid) {
;     ...
;         for (int t = 0; t < nt; t += 2) {
;             const bool last = (t == nt - 2);
;             const char* a1 = cA + (size_t)(t + 1) * kstep;
;             const char* a2 = last ? nA : cA + (size_t)(t + 2) * kstep; const char* b2 = last ? nB : cB + (size_t)(t + 2) * kstep;
;             const char* a3 = a2 + kstep; const char* b3 = b2 + kstep;
;             if (last && has_next) S.a_ready(nxt);
;             if constexpr (SP2) {
;             PG8_LDB(B0, 0, 0); PG8_LDB(B1, 0, 1); PG8_SCHED; PG8_LDA(At, 0, 0); PG8_STAGE(PG8_SA(1, 1), a1 + hstep, voffA);
;             PG8_WAIT_V(8); PG8_WAIT_L(0); PG8_BAR; PG8_MMA(0, 0, At, B0); PG8_MMA(0, 1, At, B1); PG8_BAR; PG8_SCHED;
;             PG8_LDA(At, 0, 1); PG8_STAGE(PG8_SB(0, 0), b2, voffB); PG8_STAGE(PG8_SB(0, 1), b2 + hstep, voffB); PG8_STAGE(PG8_SA(0, 0), a2, voffA);
;             PG8_WAIT_V(8); PG8_WAIT_L(0); PG8_BAR; PG8_MMA(1, 0, At, B0); PG8_MMA(1, 1, At, B1); PG8_BAR; PG8_SCHED;
.LBB0_254:
	s_add_u32 s18, s16, 0xfffc0080
	s_addc_u32 s19, s17, -1
	s_add_i32 s48, 0, 0x10000
	s_cmp_eq_u32 s47, 12
	s_cselect_b32 s21, s11, s19
	s_cselect_b32 s20, s42, s18
	v_add_u32_e32 v64, s48, v143
	s_cselect_b32 s19, s9, s46
	s_cselect_b32 s18, s44, s45
	s_add_i32 s50, 0, 0x14000
	ds_read_b128 v[146:149], v64
	ds_read_b128 v[150:153], v64 offset:1024
	ds_read_b128 v[154:157], v64 offset:2048
	ds_read_b128 v[158:161], v64 offset:3072
	v_add_u32_e32 v64, s50, v143
	ds_read_b128 v[162:165], v64
	ds_read_b128 v[166:169], v64 offset:1024
	ds_read_b128 v[170:173], v64 offset:2048
	ds_read_b128 v[174:177], v64 offset:3072
	v_lshl_add_u64 v[202:203], s[16:17], 0, v[140:141]
	s_add_i32 m0, s25, 0xc000
	ds_read_b128 v[178:181], v145
	ds_read_b128 v[182:185], v145 offset:1024
	ds_read_b128 v[186:189], v145 offset:2048
	ds_read_b128 v[190:193], v145 offset:3072
	ds_read_b128 v[194:197], v145 offset:4096
	ds_read_b128 v[198:201], v145 offset:5120
	ds_read_b128 v[206:209], v145 offset:6144
	ds_read_b128 v[214:217], v145 offset:7168
	global_load_lds_dwordx4 v[202:203], off
	s_add_i32 m0, s25, 0xe000
	v_lshl_add_u64 v[202:203], s[16:17], 0, v[138:139]
	global_load_lds_dwordx4 v[202:203], off
	s_waitcnt vmcnt(8) lgkmcnt(0)
	s_setprio 1
	s_barrier
	v_mfma_f32_16x16x32_bf16 v[126:129], v[146:149], v[178:181], v[126:129]
	v_mfma_f32_16x16x32_bf16 v[122:125], v[154:157], v[178:181], v[122:125]
	v_mfma_f32_16x16x32_bf16 v[110:113], v[146:149], v[186:189], v[110:113]
	v_mfma_f32_16x16x32_bf16 v[106:109], v[154:157], v[186:189], v[106:109]
	v_mfma_f32_16x16x32_bf16 v[94:97], v[146:149], v[194:197], v[94:97]
	v_mfma_f32_16x16x32_bf16 v[90:93], v[154:157], v[194:197], v[90:93]
	v_mfma_f32_16x16x32_bf16 v[78:81], v[146:149], v[206:209], v[78:81]
	v_mfma_f32_16x16x32_bf16 v[74:77], v[154:157], v[206:209], v[74:77]
	v_mfma_f32_16x16x32_bf16 v[126:129], v[150:153], v[182:185], v[126:129]
	v_mfma_f32_16x16x32_bf16 v[122:125], v[158:161], v[182:185], v[122:125]
	v_mfma_f32_16x16x32_bf16 v[110:113], v[150:153], v[190:193], v[110:113]
	v_mfma_f32_16x16x32_bf16 v[106:109], v[158:161], v[190:193], v[106:109]
	v_mfma_f32_16x16x32_bf16 v[94:97], v[150:153], v[198:201], v[94:97]
	v_mfma_f32_16x16x32_bf16 v[90:93], v[158:161], v[198:201], v[90:93]
	v_mfma_f32_16x16x32_bf16 v[78:81], v[150:153], v[214:217], v[78:81]
	v_mfma_f32_16x16x32_bf16 v[74:77], v[158:161], v[214:217], v[74:77]
	v_mfma_f32_16x16x32_bf16 v[118:121], v[162:165], v[178:181], v[118:121]
	v_mfma_f32_16x16x32_bf16 v[114:117], v[170:173], v[178:181], v[114:117]
	v_mfma_f32_16x16x32_bf16 v[102:105], v[162:165], v[186:189], v[102:105]
	v_mfma_f32_16x16x32_bf16 v[98:101], v[170:173], v[186:189], v[98:101]
	v_mfma_f32_16x16x32_bf16 v[86:89], v[162:165], v[194:197], v[86:89]
	v_mfma_f32_16x16x32_bf16 v[82:85], v[170:173], v[194:197], v[82:85]
	v_mfma_f32_16x16x32_bf16 v[70:73], v[162:165], v[206:209], v[70:73]
	v_mfma_f32_16x16x32_bf16 v[66:69], v[170:173], v[206:209], v[66:69]
	v_mfma_f32_16x16x32_bf16 v[118:121], v[166:169], v[182:185], v[118:121]
	v_mfma_f32_16x16x32_bf16 v[114:117], v[174:177], v[182:185], v[114:117]
	v_mfma_f32_16x16x32_bf16 v[102:105], v[166:169], v[190:193], v[102:105]
	v_mfma_f32_16x16x32_bf16 v[98:101], v[174:177], v[190:193], v[98:101]
	v_mfma_f32_16x16x32_bf16 v[86:89], v[166:169], v[198:201], v[86:89]
	v_mfma_f32_16x16x32_bf16 v[82:85], v[174:177], v[198:201], v[82:85]
	v_mfma_f32_16x16x32_bf16 v[70:73], v[166:169], v[214:217], v[70:73]
	v_mfma_f32_16x16x32_bf16 v[66:69], v[174:177], v[214:217], v[66:69]
	s_barrier
	s_setprio 0
	s_add_i32 s48, s48, s24
	v_lshl_add_u64 v[202:203], s[18:19], 0, v[134:135]
	s_mov_b32 m0, s48
	ds_read_b128 v[178:181], v145 offset:16384
	ds_read_b128 v[182:185], v145 offset:17408
	ds_read_b128 v[186:189], v145 offset:18432
	ds_read_b128 v[190:193], v145 offset:19456
	ds_read_b128 v[194:197], v145 offset:20480
	ds_read_b128 v[198:201], v145 offset:21504
	ds_read_b128 v[206:209], v145 offset:22528
	ds_read_b128 v[214:217], v145 offset:23552
	global_load_lds_dwordx4 v[202:203], off
	s_add_i32 m0, s48, 0x2000
	s_add_u32 s48, s18, 0x40000
	v_lshl_add_u64 v[210:211], s[18:19], 0, v[130:131]
	s_addc_u32 s49, s19, 0
	s_add_i32 s50, s50, s24
	global_load_lds_dwordx4 v[210:211], off
	v_lshl_add_u64 v[218:219], s[48:49], 0, v[134:135]
	s_mov_b32 m0, s50
	v_lshl_add_u64 v[220:221], s[20:21], 0, v[132:133]
	global_load_lds_dwordx4 v[218:219], off
	s_add_i32 m0, s50, 0x2000
	v_lshl_add_u64 v[218:219], s[48:49], 0, v[130:131]
	global_load_lds_dwordx4 v[218:219], off
	s_mov_b32 m0, s25
	v_lshl_add_u64 v[218:219], s[20:21], 0, v[136:137]
	global_load_lds_dwordx4 v[218:219], off
	s_mov_b32 m0, s26
	s_nop 0
	global_load_lds_dwordx4 v[220:221], off
	s_waitcnt vmcnt(8) lgkmcnt(0)
	s_setprio 1
	s_barrier
; #define PG8_STAGE(bufoff, gbase, voff) do { _Pragma("unroll") for (int _i = 0; _i < 2; ++_i) \
;         __builtin_amdgcn_global_load_lds((const unsigned*)((const char*)(gbase) + (voff)[_i]), (PG8_LAS unsigned*)(lds + (bufoff) + ldsw + _i * 8192), 16, 0, 0); } while (0)
; #define PG8_LDA(dst, b, h) do { _Pragma("unroll") for (int m = 0; m < 4; ++m) _Pragma("unroll") for (int k = 0; k < 2; ++k) dst[m][k] = *(const PG8_LAS bf16x8*)(lds + PG8_SA(b, h) + aoff + m * 2048 + k * 1024); } while (0)
; #define PG8_LDB(dst, b, h) do { _Pragma("unroll") for (int n = 0; n < 2; ++n) _Pragma("unroll") for (int k = 0; k < 2; ++k) dst[n][k] = *(const PG8_LAS bf16x8*)(lds + PG8_SB(b, h) + boff + n * 2048 + k * 1024); } while (0)
; #define PG8_MMA(ai, bj, At, Bt) do { __builtin_amdgcn_s_setprio(1); _Pragma("unroll") for (int m = 0; m < 4; ++m) _Pragma("unroll") for (int n = 0; n < 2; ++n) _Pragma("unroll") for (int k = 0; k < 2; ++k) \
;         acc[ai][bj][m][n] = __builtin_amdgcn_mfma_f32_16x16x32_bf16(Bt[n][k], At[m][k], acc[ai][bj][m][n], 0, 0, 0); __builtin_amdgcn_s_setprio(0); } while (0)
; #define PG8_WAIT_V(n) asm volatile("s_waitcnt vmcnt(" #n ")" ::: "memory")
; #define PG8_WAIT_L(n) asm volatile("s_waitcnt lgkmcnt(" #n ")" ::: "memory")
; #define PG8_BAR __builtin_amdgcn_s_barrier()
; #define PG8_SCHED __builtin_amdgcn_sched_barrier(0)
; template <class Epi, class Sched, bool ALIGN_EPI = false, bool SP2 = false>
; __device__ __forceinline__ void gemm_phase(PG8_LAS unsigned char* lds, const Gemm g, const Sched& S, const Epi& E, const int tid) {
;     ...
;             PG8_WAIT_V(8); PG8_WAIT_L(0); PG8_BAR; PG8_MMA(1, 0, At, B0); PG8_MMA(1, 1, At, B1); PG8_BAR; PG8_SCHED;
;             PG8_LDB(B0, 1, 0); PG8_LDB(B1, 1, 1); PG8_SCHED; PG8_LDA(At, 1, 0); PG8_STAGE(PG8_SA(0, 1), a2 + hstep, voffA);
;             PG8_WAIT_V(8); PG8_WAIT_L(0); PG8_BAR; PG8_MMA(0, 0, At, B0); PG8_MMA(0, 1, At, B1); PG8_BAR; PG8_SCHED;
	v_mfma_f32_16x16x32_bf16 v[60:63], v[146:149], v[178:181], v[60:63]
	v_mfma_f32_16x16x32_bf16 v[56:59], v[154:157], v[178:181], v[56:59]
	v_mfma_f32_16x16x32_bf16 v[44:47], v[146:149], v[186:189], v[44:47]
	v_mfma_f32_16x16x32_bf16 v[40:43], v[154:157], v[186:189], v[40:43]
	v_mfma_f32_16x16x32_bf16 v[28:31], v[146:149], v[194:197], v[28:31]
	v_mfma_f32_16x16x32_bf16 v[24:27], v[154:157], v[194:197], v[24:27]
	v_mfma_f32_16x16x32_bf16 v[12:15], v[146:149], v[206:209], v[12:15]
	v_mfma_f32_16x16x32_bf16 v[8:11], v[154:157], v[206:209], v[8:11]
	v_mfma_f32_16x16x32_bf16 v[60:63], v[150:153], v[182:185], v[60:63]
	v_mfma_f32_16x16x32_bf16 v[56:59], v[158:161], v[182:185], v[56:59]
	v_mfma_f32_16x16x32_bf16 v[44:47], v[150:153], v[190:193], v[44:47]
	v_mfma_f32_16x16x32_bf16 v[40:43], v[158:161], v[190:193], v[40:43]
	v_mfma_f32_16x16x32_bf16 v[28:31], v[150:153], v[198:201], v[28:31]
	v_mfma_f32_16x16x32_bf16 v[24:27], v[158:161], v[198:201], v[24:27]
	v_mfma_f32_16x16x32_bf16 v[12:15], v[150:153], v[214:217], v[12:15]
	v_mfma_f32_16x16x32_bf16 v[8:11], v[158:161], v[214:217], v[8:11]
	v_mfma_f32_16x16x32_bf16 v[52:55], v[162:165], v[178:181], v[52:55]
	v_mfma_f32_16x16x32_bf16 v[48:51], v[170:173], v[178:181], v[48:51]
	v_mfma_f32_16x16x32_bf16 v[36:39], v[162:165], v[186:189], v[36:39]
	v_mfma_f32_16x16x32_bf16 v[32:35], v[170:173], v[186:189], v[32:35]
	v_mfma_f32_16x16x32_bf16 v[20:23], v[162:165], v[194:197], v[20:23]
	v_mfma_f32_16x16x32_bf16 v[16:19], v[170:173], v[194:197], v[16:19]
	v_mfma_f32_16x16x32_bf16 v[4:7], v[162:165], v[206:209], v[4:7]
	v_mfma_f32_16x16x32_bf16 v[0:3], v[170:173], v[206:209], v[0:3]
	v_mfma_f32_16x16x32_bf16 v[52:55], v[166:169], v[182:185], v[52:55]
	v_mfma_f32_16x16x32_bf16 v[48:51], v[174:177], v[182:185], v[48:51]
	v_mfma_f32_16x16x32_bf16 v[36:39], v[166:169], v[190:193], v[36:39]
	v_mfma_f32_16x16x32_bf16 v[32:35], v[174:177], v[190:193], v[32:35]
	v_mfma_f32_16x16x32_bf16 v[20:23], v[166:169], v[198:201], v[20:23]
	v_mfma_f32_16x16x32_bf16 v[16:19], v[174:177], v[198:201], v[16:19]
	v_mfma_f32_16x16x32_bf16 v[4:7], v[166:169], v[214:217], v[4:7]
	v_mfma_f32_16x16x32_bf16 v[0:3], v[174:177], v[214:217], v[0:3]
	s_barrier
	s_setprio 0
	s_add_i32 s48, 0, 0x18000
	v_add_u32_e32 v64, s48, v143
	s_add_i32 s49, 0, 0x1c000
	ds_read_b128 v[146:149], v64
	ds_read_b128 v[150:153], v64 offset:1024
	ds_read_b128 v[154:157], v64 offset:2048
	ds_read_b128 v[158:161], v64 offset:3072
	v_add_u32_e32 v64, s49, v143
	ds_read_b128 v[162:165], v64
	ds_read_b128 v[166:169], v64 offset:1024
	ds_read_b128 v[170:173], v64 offset:2048
	ds_read_b128 v[174:177], v64 offset:3072
	s_add_u32 s20, s20, 0x40000
	s_addc_u32 s21, s21, 0
	s_mov_b32 m0, s27
	v_lshl_add_u64 v[222:223], s[20:21], 0, v[136:137]
	ds_read_b128 v[178:181], v145 offset:32768
	ds_read_b128 v[182:185], v145 offset:33792
	ds_read_b128 v[186:189], v145 offset:34816
	ds_read_b128 v[190:193], v145 offset:35840
	ds_read_b128 v[194:197], v145 offset:36864
	ds_read_b128 v[198:201], v145 offset:37888
	ds_read_b128 v[206:209], v145 offset:38912
	ds_read_b128 v[214:217], v145 offset:39936
	global_load_lds_dwordx4 v[222:223], off
	s_mov_b32 m0, s28
	v_lshl_add_u64 v[222:223], s[20:21], 0, v[132:133]
	global_load_lds_dwordx4 v[222:223], off
	s_waitcnt vmcnt(8) lgkmcnt(0)
	s_setprio 1
	s_barrier
	v_mfma_f32_16x16x32_bf16 v[126:129], v[146:149], v[178:181], v[126:129]
	v_mfma_f32_16x16x32_bf16 v[122:125], v[154:157], v[178:181], v[122:125]
	v_mfma_f32_16x16x32_bf16 v[110:113], v[146:149], v[186:189], v[110:113]
	v_mfma_f32_16x16x32_bf16 v[106:109], v[154:157], v[186:189], v[106:109]
	v_mfma_f32_16x16x32_bf16 v[94:97], v[146:149], v[194:197], v[94:97]
	v_mfma_f32_16x16x32_bf16 v[90:93], v[154:157], v[194:197], v[90:93]
	v_mfma_f32_16x16x32_bf16 v[78:81], v[146:149], v[206:209], v[78:81]
	v_mfma_f32_16x16x32_bf16 v[74:77], v[154:157], v[206:209], v[74:77]
	v_mfma_f32_16x16x32_bf16 v[126:129], v[150:153], v[182:185], v[126:129]
	v_mfma_f32_16x16x32_bf16 v[122:125], v[158:161], v[182:185], v[122:125]
	v_mfma_f32_16x16x32_bf16 v[110:113], v[150:153], v[190:193], v[110:113]
	v_mfma_f32_16x16x32_bf16 v[106:109], v[158:161], v[190:193], v[106:109]
	v_mfma_f32_16x16x32_bf16 v[94:97], v[150:153], v[198:201], v[94:97]
	v_mfma_f32_16x16x32_bf16 v[90:93], v[158:161], v[198:201], v[90:93]
	v_mfma_f32_16x16x32_bf16 v[78:81], v[150:153], v[214:217], v[78:81]
	v_mfma_f32_16x16x32_bf16 v[74:77], v[158:161], v[214:217], v[74:77]
	v_mfma_f32_16x16x32_bf16 v[118:121], v[162:165], v[178:181], v[118:121]
	v_mfma_f32_16x16x32_bf16 v[114:117], v[170:173], v[178:181], v[114:117]
	v_mfma_f32_16x16x32_bf16 v[102:105], v[162:165], v[186:189], v[102:105]
	v_mfma_f32_16x16x32_bf16 v[98:101], v[170:173], v[186:189], v[98:101]
	v_mfma_f32_16x16x32_bf16 v[86:89], v[162:165], v[194:197], v[86:89]
	v_mfma_f32_16x16x32_bf16 v[82:85], v[170:173], v[194:197], v[82:85]
	v_mfma_f32_16x16x32_bf16 v[70:73], v[162:165], v[206:209], v[70:73]
	v_mfma_f32_16x16x32_bf16 v[66:69], v[170:173], v[206:209], v[66:69]
	v_mfma_f32_16x16x32_bf16 v[118:121], v[166:169], v[182:185], v[118:121]
	v_mfma_f32_16x16x32_bf16 v[114:117], v[174:177], v[182:185], v[114:117]
	v_mfma_f32_16x16x32_bf16 v[102:105], v[166:169], v[190:193], v[102:105]
	v_mfma_f32_16x16x32_bf16 v[98:101], v[174:177], v[190:193], v[98:101]
	v_mfma_f32_16x16x32_bf16 v[86:89], v[166:169], v[198:201], v[86:89]
	v_mfma_f32_16x16x32_bf16 v[82:85], v[174:177], v[198:201], v[82:85]
	v_mfma_f32_16x16x32_bf16 v[70:73], v[166:169], v[214:217], v[70:73]
	v_mfma_f32_16x16x32_bf16 v[66:69], v[174:177], v[214:217], v[66:69]
	s_barrier
; #define PG8_STAGE(bufoff, gbase, voff) do { _Pragma("unroll") for (int _i = 0; _i < 2; ++_i) \
;         __builtin_amdgcn_global_load_lds((const unsigned*)((const char*)(gbase) + (voff)[_i]), (PG8_LAS unsigned*)(lds + (bufoff) + ldsw + _i * 8192), 16, 0, 0); } while (0)
; #define PG8_LDA(dst, b, h) do { _Pragma("unroll") for (int m = 0; m < 4; ++m) _Pragma("unroll") for (int k = 0; k < 2; ++k) dst[m][k] = *(const PG8_LAS bf16x8*)(lds + PG8_SA(b, h) + aoff + m * 2048 + k * 1024); } while (0)
; #define PG8_MMA(ai, bj, At, Bt) do { __builtin_amdgcn_s_setprio(1); _Pragma("unroll") for (int m = 0; m < 4; ++m) _Pragma("unroll") for (int n = 0; n < 2; ++n) _Pragma("unroll") for (int k = 0; k < 2; ++k) \
;         acc[ai][bj][m][n] = __builtin_amdgcn_mfma_f32_16x16x32_bf16(Bt[n][k], At[m][k], acc[ai][bj][m][n], 0, 0, 0); __builtin_amdgcn_s_setprio(0); } while (0)
; #define PG8_WAIT_V(n) asm volatile("s_waitcnt vmcnt(" #n ")" ::: "memory")
; #define PG8_WAIT_L(n) asm volatile("s_waitcnt lgkmcnt(" #n ")" ::: "memory")
; #define PG8_BAR __builtin_amdgcn_s_barrier()
; #define PG8_SCHED __builtin_amdgcn_sched_barrier(0)
; template <class Epi, class Sched, bool ALIGN_EPI = false, bool SP2 = false>
; __device__ __forceinline__ void gemm_phase(PG8_LAS unsigned char* lds, const Gemm g, const Sched& S, const Epi& E, const int tid) {
;     ...
;         for (int t = 0; t < nt; t += 2) {
;     ...
;             PG8_LDA(At, 1, 1); PG8_STAGE(PG8_SB(1, 0), b3, voffB); PG8_STAGE(PG8_SB(1, 1), b3 + hstep, voffB); PG8_STAGE(PG8_SA(1, 0), a3, voffA);
;             PG8_WAIT_V(8); PG8_WAIT_L(0); PG8_BAR; PG8_MMA(1, 0, At, B0); PG8_MMA(1, 1, At, B1); PG8_BAR; PG8_SCHED;
;     ...
;         if constexpr (ALIGN_EPI) { if (wr == 0) PG8_BAR; }
	s_setprio 0
	s_add_i32 s20, s48, s24
	v_lshl_add_u64 v[202:203], v[202:203], 0, s[94:95]
	s_mov_b32 m0, s20
	ds_read_b128 v[178:181], v145 offset:49152
	ds_read_b128 v[182:185], v145 offset:50176
	ds_read_b128 v[186:189], v145 offset:51200
	ds_read_b128 v[190:193], v145 offset:52224
	ds_read_b128 v[194:197], v145 offset:53248
	ds_read_b128 v[198:201], v145 offset:54272
	ds_read_b128 v[206:209], v145 offset:55296
	ds_read_b128 v[214:217], v145 offset:56320
	global_load_lds_dwordx4 v[202:203], off
	s_add_i32 m0, s20, 0x2000
	s_add_u32 s18, s18, 0x40080
	v_lshl_add_u64 v[202:203], v[210:211], 0, s[94:95]
	s_addc_u32 s19, s19, 0
	s_add_i32 s20, s49, s24
	global_load_lds_dwordx4 v[202:203], off
	s_mov_b32 m0, s20
	v_lshl_add_u64 v[202:203], s[18:19], 0, v[134:135]
	global_load_lds_dwordx4 v[202:203], off
	s_add_i32 m0, s20, 0x2000
	v_lshl_add_u64 v[202:203], s[18:19], 0, v[130:131]
	global_load_lds_dwordx4 v[202:203], off
	s_mov_b32 m0, s29
	v_lshl_add_u64 v[202:203], v[218:219], 0, s[94:95]
	global_load_lds_dwordx4 v[202:203], off
	s_mov_b32 m0, s30
	v_lshl_add_u64 v[202:203], v[220:221], 0, s[94:95]
	global_load_lds_dwordx4 v[202:203], off
	s_waitcnt vmcnt(8) lgkmcnt(0)
	s_setprio 1
	s_barrier
	v_mfma_f32_16x16x32_bf16 v[60:63], v[146:149], v[178:181], v[60:63]
	v_mfma_f32_16x16x32_bf16 v[56:59], v[154:157], v[178:181], v[56:59]
	v_mfma_f32_16x16x32_bf16 v[44:47], v[146:149], v[186:189], v[44:47]
	v_mfma_f32_16x16x32_bf16 v[40:43], v[154:157], v[186:189], v[40:43]
	v_mfma_f32_16x16x32_bf16 v[28:31], v[146:149], v[194:197], v[28:31]
	v_mfma_f32_16x16x32_bf16 v[24:27], v[154:157], v[194:197], v[24:27]
	v_mfma_f32_16x16x32_bf16 v[12:15], v[146:149], v[206:209], v[12:15]
	v_mfma_f32_16x16x32_bf16 v[8:11], v[154:157], v[206:209], v[8:11]
	v_mfma_f32_16x16x32_bf16 v[60:63], v[150:153], v[182:185], v[60:63]
	v_mfma_f32_16x16x32_bf16 v[56:59], v[158:161], v[182:185], v[56:59]
	v_mfma_f32_16x16x32_bf16 v[44:47], v[150:153], v[190:193], v[44:47]
	v_mfma_f32_16x16x32_bf16 v[40:43], v[158:161], v[190:193], v[40:43]
	v_mfma_f32_16x16x32_bf16 v[28:31], v[150:153], v[198:201], v[28:31]
	v_mfma_f32_16x16x32_bf16 v[24:27], v[158:161], v[198:201], v[24:27]
	v_mfma_f32_16x16x32_bf16 v[12:15], v[150:153], v[214:217], v[12:15]
	v_mfma_f32_16x16x32_bf16 v[8:11], v[158:161], v[214:217], v[8:11]
	v_mfma_f32_16x16x32_bf16 v[52:55], v[162:165], v[178:181], v[52:55]
	v_mfma_f32_16x16x32_bf16 v[48:51], v[170:173], v[178:181], v[48:51]
	v_mfma_f32_16x16x32_bf16 v[36:39], v[162:165], v[186:189], v[36:39]
	v_mfma_f32_16x16x32_bf16 v[32:35], v[170:173], v[186:189], v[32:35]
	v_mfma_f32_16x16x32_bf16 v[20:23], v[162:165], v[194:197], v[20:23]
	v_mfma_f32_16x16x32_bf16 v[16:19], v[170:173], v[194:197], v[16:19]
	v_mfma_f32_16x16x32_bf16 v[4:7], v[162:165], v[206:209], v[4:7]
	v_mfma_f32_16x16x32_bf16 v[0:3], v[170:173], v[206:209], v[0:3]
	v_mfma_f32_16x16x32_bf16 v[52:55], v[166:169], v[182:185], v[52:55]
	v_mfma_f32_16x16x32_bf16 v[48:51], v[174:177], v[182:185], v[48:51]
	v_mfma_f32_16x16x32_bf16 v[36:39], v[166:169], v[190:193], v[36:39]
	v_mfma_f32_16x16x32_bf16 v[32:35], v[174:177], v[190:193], v[32:35]
	v_mfma_f32_16x16x32_bf16 v[20:23], v[166:169], v[198:201], v[20:23]
	v_mfma_f32_16x16x32_bf16 v[16:19], v[174:177], v[198:201], v[16:19]
	v_mfma_f32_16x16x32_bf16 v[4:7], v[166:169], v[214:217], v[4:7]
	v_mfma_f32_16x16x32_bf16 v[0:3], v[174:177], v[214:217], v[0:3]
	s_barrier
	s_setprio 0
	s_add_i32 s47, s47, 2
	s_add_u32 s45, s45, 0x100
	s_addc_u32 s46, s46, 0
	s_add_u32 s16, s16, 0x100
	s_addc_u32 s17, s17, 0
	s_cmp_gt_u32 s47, 13
	s_cbranch_scc0 .LBB0_254
	s_and_b64 vcc, exec, s[4:5]
	s_cbranch_vccz .LBB0_257
	s_barrier

; #define PG8_STAGE(bufoff, gbase, voff) do { _Pragma("unroll") for (int _i = 0; _i < 2; ++_i) \
;         __builtin_amdgcn_global_load_lds((const unsigned*)((const char*)(gbase) + (voff)[_i]), (PG8_LAS unsigned*)(lds + (bufoff) + ldsw + _i * 8192), 16, 0, 0); } while (0)
; #define PG8_LDA(dst, b, h) do { _Pragma("unroll") for (int m = 0; m < 4; ++m) _Pragma("unroll") for (int k = 0; k < 2; ++k) dst[m][k] = *(const PG8_LAS bf16x8*)(lds + PG8_SA(b, h) + aoff + m * 2048 + k * 1024); } while (0)
; #define PG8_LDB(dst, b, h) do { _Pragma("unroll") for (int n = 0; n < 2; ++n) _Pragma("unroll") for (int k = 0; k < 2; ++k) dst[n][k] = *(const PG8_LAS bf16x8*)(lds + PG8_SB(b, h) + boff + n * 2048 + k * 1024); } while (0)
; #define PG8_MMA(ai, bj, At, Bt) do { __builtin_amdgcn_s_setprio(1); _Pragma("unroll") for (int m = 0; m < 4; ++m) _Pragma("unroll") for (int n = 0; n < 2; ++n) _Pragma("unroll") for (int k = 0; k < 2; ++k) \
;         acc[ai][bj][m][n] = __builtin_amdgcn_mfma_f32_16x16x32_bf16(Bt[n][k], At[m][k], acc[ai][bj][m][n], 0, 0, 0); __builtin_amdgcn_s_setprio(0); } while (0)
; #define PG8_WAIT_V(n) asm volatile("s_waitcnt vmcnt(" #n ")" ::: "memory")
; #define PG8_BAR __builtin_amdgcn_s_barrier()
; template <class Epi, class Sched, bool ALIGN_EPI = false, bool SP2 = false>
; __device__ __forceinline__ void gemm_phase(PG8_LAS unsigned char* lds, const Gemm g, const Sched& S, const Epi& E, const int tid) {
;     ...
;         for (int t = 0; t < nt; t += 2) {
;             const bool last = (t == nt - 2);
;             const char* a1 = cA + (size_t)(t + 1) * kstep;
;             const char* a2 = last ? nA : cA + (size_t)(t + 2) * kstep; const char* b2 = last ? nB : cB + (size_t)(t + 2) * kstep;
;             const char* a3 = a2 + kstep; const char* b3 = b2 + kstep;
;             if (last && has_next) S.a_ready(nxt);
;             if constexpr (SP2) {
;             PG8_LDB(B0, 0, 0); PG8_LDB(B1, 0, 1); PG8_SCHED; PG8_LDA(At, 0, 0); PG8_STAGE(PG8_SA(1, 1), a1 + hstep, voffA);
;             PG8_WAIT_V(8); PG8_WAIT_L(0); PG8_BAR; PG8_MMA(0, 0, At, B0); PG8_MMA(0, 1, At, B1); PG8_BAR; PG8_SCHED;
;             PG8_LDA(At, 0, 1); PG8_STAGE(PG8_SB(0, 0), b2, voffB); PG8_STAGE(PG8_SB(0, 1), b2 + hstep, voffB); PG8_STAGE(PG8_SA(0, 0), a2, voffA);
;             PG8_WAIT_V(8); PG8_WAIT_L(0); PG8_BAR; PG8_MMA(1, 0, At, B0); PG8_MMA(1, 1, At, B1); PG8_BAR; PG8_SCHED;
.LBB0_286:
	s_add_u32 s20, s8, s18
	s_addc_u32 s21, s9, s19
	s_add_u32 s20, s20, 0x100
	s_addc_u32 s21, s21, 0
	s_add_u32 s54, s49, s18
	s_addc_u32 s55, s50, s19
	s_add_i32 s56, 0, 0x10000
	s_cmpk_eq_i32 s18, 0x700
	s_cselect_b32 s23, s13, s21
	s_cselect_b32 s22, s51, s20
	s_cselect_b32 s21, s11, s55
	s_cselect_b32 s20, s52, s54
	s_add_i32 s57, 0, 0x14000
	v_add_u32_e32 v86, s56, v72
	v_add_u32_e32 v110, s57, v72
	ds_read_b128 v[74:77], v86
	ds_read_b128 v[78:81], v86 offset:1024
	ds_read_b128 v[82:85], v86 offset:2048
	ds_read_b128 v[86:89], v86 offset:3072
	ds_read_b128 v[90:93], v110
	ds_read_b128 v[94:97], v110 offset:1024
	ds_read_b128 v[106:109], v110 offset:2048
	ds_read_b128 v[110:113], v110 offset:3072
	v_lshl_add_u64 v[202:203], v[70:71], 0, s[18:19]
	s_add_i32 m0, s31, 0xc000
	ds_read_b128 v[114:117], v73
	ds_read_b128 v[118:121], v73 offset:1024
	ds_read_b128 v[122:125], v73 offset:2048
	ds_read_b128 v[126:129], v73 offset:3072
	ds_read_b128 v[194:197], v73 offset:4096
	ds_read_b128 v[198:201], v73 offset:5120
	ds_read_b128 v[206:209], v73 offset:6144
	ds_read_b128 v[214:217], v73 offset:7168
	global_load_lds_dwordx4 v[202:203], off
	s_add_i32 m0, s31, 0xe000
	v_lshl_add_u64 v[202:203], v[68:69], 0, s[18:19]
	global_load_lds_dwordx4 v[202:203], off
	s_waitcnt vmcnt(8) lgkmcnt(0)
	s_setprio 1
	s_barrier
	v_mfma_f32_16x16x32_bf16 v[190:193], v[74:77], v[114:117], v[190:193]
	v_mfma_f32_16x16x32_bf16 v[186:189], v[82:85], v[114:117], v[186:189]
	v_mfma_f32_16x16x32_bf16 v[182:185], v[74:77], v[122:125], v[182:185]
	v_mfma_f32_16x16x32_bf16 v[178:181], v[82:85], v[122:125], v[178:181]
	v_mfma_f32_16x16x32_bf16 v[174:177], v[74:77], v[194:197], v[174:177]
	v_mfma_f32_16x16x32_bf16 v[170:173], v[82:85], v[194:197], v[170:173]
	v_mfma_f32_16x16x32_bf16 v[166:169], v[74:77], v[206:209], v[166:169]
	v_mfma_f32_16x16x32_bf16 v[162:165], v[82:85], v[206:209], v[162:165]
	v_mfma_f32_16x16x32_bf16 v[190:193], v[78:81], v[118:121], v[190:193]
	v_mfma_f32_16x16x32_bf16 v[186:189], v[86:89], v[118:121], v[186:189]
	v_mfma_f32_16x16x32_bf16 v[182:185], v[78:81], v[126:129], v[182:185]
	v_mfma_f32_16x16x32_bf16 v[178:181], v[86:89], v[126:129], v[178:181]
	v_mfma_f32_16x16x32_bf16 v[174:177], v[78:81], v[198:201], v[174:177]
	v_mfma_f32_16x16x32_bf16 v[170:173], v[86:89], v[198:201], v[170:173]
	v_mfma_f32_16x16x32_bf16 v[166:169], v[78:81], v[214:217], v[166:169]
	v_mfma_f32_16x16x32_bf16 v[162:165], v[86:89], v[214:217], v[162:165]
	v_mfma_f32_16x16x32_bf16 v[102:105], v[90:93], v[114:117], v[102:105]
	v_mfma_f32_16x16x32_bf16 v[98:101], v[106:109], v[114:117], v[98:101]
	v_mfma_f32_16x16x32_bf16 v[56:59], v[90:93], v[122:125], v[56:59]
	v_mfma_f32_16x16x32_bf16 v[48:51], v[106:109], v[122:125], v[48:51]
	v_mfma_f32_16x16x32_bf16 v[44:47], v[90:93], v[194:197], v[44:47]
	v_mfma_f32_16x16x32_bf16 v[40:43], v[106:109], v[194:197], v[40:43]
	v_mfma_f32_16x16x32_bf16 v[36:39], v[90:93], v[206:209], v[36:39]
	v_mfma_f32_16x16x32_bf16 v[32:35], v[106:109], v[206:209], v[32:35]
	v_mfma_f32_16x16x32_bf16 v[102:105], v[94:97], v[118:121], v[102:105]
	v_mfma_f32_16x16x32_bf16 v[98:101], v[110:113], v[118:121], v[98:101]
	v_mfma_f32_16x16x32_bf16 v[56:59], v[94:97], v[126:129], v[56:59]
	v_mfma_f32_16x16x32_bf16 v[48:51], v[110:113], v[126:129], v[48:51]
	v_mfma_f32_16x16x32_bf16 v[44:47], v[94:97], v[198:201], v[44:47]
	v_mfma_f32_16x16x32_bf16 v[40:43], v[110:113], v[198:201], v[40:43]
	v_mfma_f32_16x16x32_bf16 v[36:39], v[94:97], v[214:217], v[36:39]
	v_mfma_f32_16x16x32_bf16 v[32:35], v[110:113], v[214:217], v[32:35]
	s_barrier
	s_setprio 0
	s_add_i32 s54, s56, s30
	v_lshl_add_u64 v[202:203], s[20:21], 0, v[64:65]
	s_mov_b32 m0, s54
	ds_read_b128 v[114:117], v73 offset:16384
	ds_read_b128 v[118:121], v73 offset:17408
	ds_read_b128 v[122:125], v73 offset:18432
	ds_read_b128 v[126:129], v73 offset:19456
	ds_read_b128 v[194:197], v73 offset:20480
	ds_read_b128 v[198:201], v73 offset:21504
	ds_read_b128 v[206:209], v73 offset:22528
	ds_read_b128 v[214:217], v73 offset:23552
	global_load_lds_dwordx4 v[202:203], off
	s_add_i32 m0, s54, 0x2000
	s_add_u32 s54, s20, 0x40000
	v_lshl_add_u64 v[210:211], s[20:21], 0, v[52:53]
	s_addc_u32 s55, s21, 0
	s_add_i32 s56, s57, s30
	global_load_lds_dwordx4 v[210:211], off
	v_lshl_add_u64 v[218:219], s[54:55], 0, v[64:65]
	s_mov_b32 m0, s56
	v_lshl_add_u64 v[226:227], s[22:23], 0, v[60:61]
	global_load_lds_dwordx4 v[218:219], off
	v_lshl_add_u64 v[218:219], s[54:55], 0, v[52:53]
	s_add_i32 m0, s56, 0x2000
	v_lshl_add_u64 v[228:229], s[22:23], 0, v[54:55]
	global_load_lds_dwordx4 v[218:219], off
	s_mov_b32 m0, s31
	s_nop 0
	global_load_lds_dwordx4 v[226:227], off
	s_mov_b32 m0, s35
	s_nop 0
	global_load_lds_dwordx4 v[228:229], off
	s_waitcnt vmcnt(8) lgkmcnt(0)
	s_setprio 1
	s_barrier
; #define PG8_STAGE(bufoff, gbase, voff) do { _Pragma("unroll") for (int _i = 0; _i < 2; ++_i) \
;         __builtin_amdgcn_global_load_lds((const unsigned*)((const char*)(gbase) + (voff)[_i]), (PG8_LAS unsigned*)(lds + (bufoff) + ldsw + _i * 8192), 16, 0, 0); } while (0)
; #define PG8_LDA(dst, b, h) do { _Pragma("unroll") for (int m = 0; m < 4; ++m) _Pragma("unroll") for (int k = 0; k < 2; ++k) dst[m][k] = *(const PG8_LAS bf16x8*)(lds + PG8_SA(b, h) + aoff + m * 2048 + k * 1024); } while (0)
; #define PG8_LDB(dst, b, h) do { _Pragma("unroll") for (int n = 0; n < 2; ++n) _Pragma("unroll") for (int k = 0; k < 2; ++k) dst[n][k] = *(const PG8_LAS bf16x8*)(lds + PG8_SB(b, h) + boff + n * 2048 + k * 1024); } while (0)
; #define PG8_MMA(ai, bj, At, Bt) do { __builtin_amdgcn_s_setprio(1); _Pragma("unroll") for (int m = 0; m < 4; ++m) _Pragma("unroll") for (int n = 0; n < 2; ++n) _Pragma("unroll") for (int k = 0; k < 2; ++k) \
;         acc[ai][bj][m][n] = __builtin_amdgcn_mfma_f32_16x16x32_bf16(Bt[n][k], At[m][k], acc[ai][bj][m][n], 0, 0, 0); __builtin_amdgcn_s_setprio(0); } while (0)
; #define PG8_WAIT_V(n) asm volatile("s_waitcnt vmcnt(" #n ")" ::: "memory")
; #define PG8_WAIT_L(n) asm volatile("s_waitcnt lgkmcnt(" #n ")" ::: "memory")
; #define PG8_BAR __builtin_amdgcn_s_barrier()
; #define PG8_SCHED __builtin_amdgcn_sched_barrier(0)
; template <class Epi, class Sched, bool ALIGN_EPI = false, bool SP2 = false>
; __device__ __forceinline__ void gemm_phase(PG8_LAS unsigned char* lds, const Gemm g, const Sched& S, const Epi& E, const int tid) {
;     ...
;             PG8_WAIT_V(8); PG8_WAIT_L(0); PG8_BAR; PG8_MMA(1, 0, At, B0); PG8_MMA(1, 1, At, B1); PG8_BAR; PG8_SCHED;
;             PG8_LDB(B0, 1, 0); PG8_LDB(B1, 1, 1); PG8_SCHED; PG8_LDA(At, 1, 0); PG8_STAGE(PG8_SA(0, 1), a2 + hstep, voffA);
;             PG8_WAIT_V(8); PG8_WAIT_L(0); PG8_BAR; PG8_MMA(0, 0, At, B0); PG8_MMA(0, 1, At, B1); PG8_BAR; PG8_SCHED;
	v_mfma_f32_16x16x32_bf16 v[158:161], v[74:77], v[114:117], v[158:161]
	v_mfma_f32_16x16x32_bf16 v[154:157], v[82:85], v[114:117], v[154:157]
	v_mfma_f32_16x16x32_bf16 v[150:153], v[74:77], v[122:125], v[150:153]
	v_mfma_f32_16x16x32_bf16 v[146:149], v[82:85], v[122:125], v[146:149]
	v_mfma_f32_16x16x32_bf16 v[142:145], v[74:77], v[194:197], v[142:145]
	v_mfma_f32_16x16x32_bf16 v[138:141], v[82:85], v[194:197], v[138:141]
	v_mfma_f32_16x16x32_bf16 v[74:77], v[74:77], v[206:209], v[134:137]
	v_mfma_f32_16x16x32_bf16 v[158:161], v[78:81], v[118:121], v[158:161]
	v_mfma_f32_16x16x32_bf16 v[154:157], v[86:89], v[118:121], v[154:157]
	v_mfma_f32_16x16x32_bf16 v[150:153], v[78:81], v[126:129], v[150:153]
	v_mfma_f32_16x16x32_bf16 v[146:149], v[86:89], v[126:129], v[146:149]
	v_mfma_f32_16x16x32_bf16 v[142:145], v[78:81], v[198:201], v[142:145]
	v_mfma_f32_16x16x32_bf16 v[138:141], v[86:89], v[198:201], v[138:141]
	v_mfma_f32_16x16x32_bf16 v[74:77], v[78:81], v[214:217], v[74:77]
	v_mfma_f32_16x16x32_bf16 v[78:81], v[82:85], v[206:209], v[130:133]
	v_mfma_f32_16x16x32_bf16 v[78:81], v[86:89], v[214:217], v[78:81]
	v_mfma_f32_16x16x32_bf16 v[28:31], v[90:93], v[114:117], v[28:31]
	v_mfma_f32_16x16x32_bf16 v[24:27], v[106:109], v[114:117], v[24:27]
	v_mfma_f32_16x16x32_bf16 v[20:23], v[90:93], v[122:125], v[20:23]
	v_mfma_f32_16x16x32_bf16 v[16:19], v[106:109], v[122:125], v[16:19]
	v_mfma_f32_16x16x32_bf16 v[12:15], v[90:93], v[194:197], v[12:15]
	v_mfma_f32_16x16x32_bf16 v[8:11], v[106:109], v[194:197], v[8:11]
	v_mfma_f32_16x16x32_bf16 v[4:7], v[90:93], v[206:209], v[4:7]
	v_mfma_f32_16x16x32_bf16 v[0:3], v[106:109], v[206:209], v[0:3]
	v_mfma_f32_16x16x32_bf16 v[28:31], v[94:97], v[118:121], v[28:31]
	v_mfma_f32_16x16x32_bf16 v[24:27], v[110:113], v[118:121], v[24:27]
	v_mfma_f32_16x16x32_bf16 v[20:23], v[94:97], v[126:129], v[20:23]
	v_mfma_f32_16x16x32_bf16 v[16:19], v[110:113], v[126:129], v[16:19]
	v_mfma_f32_16x16x32_bf16 v[12:15], v[94:97], v[198:201], v[12:15]
	v_mfma_f32_16x16x32_bf16 v[8:11], v[110:113], v[198:201], v[8:11]
	v_mfma_f32_16x16x32_bf16 v[4:7], v[94:97], v[214:217], v[4:7]
	v_mfma_f32_16x16x32_bf16 v[0:3], v[110:113], v[214:217], v[0:3]
	s_barrier
	s_setprio 0
	s_add_i32 s54, 0, 0x18000
	s_add_i32 s55, 0, 0x1c000
	v_add_u32_e32 v94, s54, v72
	v_add_u32_e32 v118, s55, v72
	ds_read_b128 v[82:85], v94
	ds_read_b128 v[86:89], v94 offset:1024
	ds_read_b128 v[90:93], v94 offset:2048
	ds_read_b128 v[94:97], v94 offset:3072
	ds_read_b128 v[106:109], v118
	ds_read_b128 v[110:113], v118 offset:1024
	ds_read_b128 v[114:117], v118 offset:2048
	ds_read_b128 v[118:121], v118 offset:3072
	s_add_u32 s22, s22, 0x40000
	s_addc_u32 s23, s23, 0
	s_mov_b32 m0, s42
	v_lshl_add_u64 v[218:219], s[22:23], 0, v[60:61]
	ds_read_b128 v[122:125], v73 offset:32768
	ds_read_b128 v[126:129], v73 offset:33792
	ds_read_b128 v[130:133], v73 offset:34816
	ds_read_b128 v[134:137], v73 offset:35840
	ds_read_b128 v[194:197], v73 offset:36864
	ds_read_b128 v[198:201], v73 offset:37888
	ds_read_b128 v[206:209], v73 offset:38912
	ds_read_b128 v[214:217], v73 offset:39936
	global_load_lds_dwordx4 v[218:219], off
	s_mov_b32 m0, s44
	v_lshl_add_u64 v[218:219], s[22:23], 0, v[54:55]
	global_load_lds_dwordx4 v[218:219], off
	s_waitcnt vmcnt(8) lgkmcnt(0)
	s_setprio 1
	s_barrier
	v_mfma_f32_16x16x32_bf16 v[190:193], v[82:85], v[122:125], v[190:193]
	v_mfma_f32_16x16x32_bf16 v[186:189], v[90:93], v[122:125], v[186:189]
	v_mfma_f32_16x16x32_bf16 v[182:185], v[82:85], v[130:133], v[182:185]
	v_mfma_f32_16x16x32_bf16 v[178:181], v[90:93], v[130:133], v[178:181]
	v_mfma_f32_16x16x32_bf16 v[174:177], v[82:85], v[194:197], v[174:177]
	v_mfma_f32_16x16x32_bf16 v[170:173], v[90:93], v[194:197], v[170:173]
	v_mfma_f32_16x16x32_bf16 v[166:169], v[82:85], v[206:209], v[166:169]
	v_mfma_f32_16x16x32_bf16 v[162:165], v[90:93], v[206:209], v[162:165]
	v_mfma_f32_16x16x32_bf16 v[190:193], v[86:89], v[126:129], v[190:193]
	v_mfma_f32_16x16x32_bf16 v[186:189], v[94:97], v[126:129], v[186:189]
	v_mfma_f32_16x16x32_bf16 v[182:185], v[86:89], v[134:137], v[182:185]
	v_mfma_f32_16x16x32_bf16 v[178:181], v[94:97], v[134:137], v[178:181]
	v_mfma_f32_16x16x32_bf16 v[174:177], v[86:89], v[198:201], v[174:177]
	v_mfma_f32_16x16x32_bf16 v[170:173], v[94:97], v[198:201], v[170:173]
	v_mfma_f32_16x16x32_bf16 v[166:169], v[86:89], v[214:217], v[166:169]
	v_mfma_f32_16x16x32_bf16 v[162:165], v[94:97], v[214:217], v[162:165]
	v_mfma_f32_16x16x32_bf16 v[102:105], v[106:109], v[122:125], v[102:105]
	v_mfma_f32_16x16x32_bf16 v[98:101], v[114:117], v[122:125], v[98:101]
	v_mfma_f32_16x16x32_bf16 v[56:59], v[106:109], v[130:133], v[56:59]
	v_mfma_f32_16x16x32_bf16 v[48:51], v[114:117], v[130:133], v[48:51]
	v_mfma_f32_16x16x32_bf16 v[44:47], v[106:109], v[194:197], v[44:47]
	v_mfma_f32_16x16x32_bf16 v[40:43], v[114:117], v[194:197], v[40:43]
	v_mfma_f32_16x16x32_bf16 v[36:39], v[106:109], v[206:209], v[36:39]
	v_mfma_f32_16x16x32_bf16 v[32:35], v[114:117], v[206:209], v[32:35]
	v_mfma_f32_16x16x32_bf16 v[102:105], v[110:113], v[126:129], v[102:105]
	v_mfma_f32_16x16x32_bf16 v[98:101], v[118:121], v[126:129], v[98:101]
	v_mfma_f32_16x16x32_bf16 v[56:59], v[110:113], v[134:137], v[56:59]
	v_mfma_f32_16x16x32_bf16 v[48:51], v[118:121], v[134:137], v[48:51]
	v_mfma_f32_16x16x32_bf16 v[44:47], v[110:113], v[198:201], v[44:47]
	v_mfma_f32_16x16x32_bf16 v[40:43], v[118:121], v[198:201], v[40:43]
	v_mfma_f32_16x16x32_bf16 v[36:39], v[110:113], v[214:217], v[36:39]
	v_mfma_f32_16x16x32_bf16 v[32:35], v[118:121], v[214:217], v[32:35]
	s_barrier
; #define PG8_STAGE(bufoff, gbase, voff) do { _Pragma("unroll") for (int _i = 0; _i < 2; ++_i) \
;         __builtin_amdgcn_global_load_lds((const unsigned*)((const char*)(gbase) + (voff)[_i]), (PG8_LAS unsigned*)(lds + (bufoff) + ldsw + _i * 8192), 16, 0, 0); } while (0)
; #define PG8_LDA(dst, b, h) do { _Pragma("unroll") for (int m = 0; m < 4; ++m) _Pragma("unroll") for (int k = 0; k < 2; ++k) dst[m][k] = *(const PG8_LAS bf16x8*)(lds + PG8_SA(b, h) + aoff + m * 2048 + k * 1024); } while (0)
; #define PG8_MMA(ai, bj, At, Bt) do { __builtin_amdgcn_s_setprio(1); _Pragma("unroll") for (int m = 0; m < 4; ++m) _Pragma("unroll") for (int n = 0; n < 2; ++n) _Pragma("unroll") for (int k = 0; k < 2; ++k) \
;         acc[ai][bj][m][n] = __builtin_amdgcn_mfma_f32_16x16x32_bf16(Bt[n][k], At[m][k], acc[ai][bj][m][n], 0, 0, 0); __builtin_amdgcn_s_setprio(0); } while (0)
; #define PG8_WAIT_V(n) asm volatile("s_waitcnt vmcnt(" #n ")" ::: "memory")
; #define PG8_WAIT_L(n) asm volatile("s_waitcnt lgkmcnt(" #n ")" ::: "memory")
; #define PG8_BAR __builtin_amdgcn_s_barrier()
; #define PG8_SCHED __builtin_amdgcn_sched_barrier(0)
; template <class Epi, class Sched, bool ALIGN_EPI = false, bool SP2 = false>
; __device__ __forceinline__ void gemm_phase(PG8_LAS unsigned char* lds, const Gemm g, const Sched& S, const Epi& E, const int tid) {
;     ...
;             PG8_LDA(At, 1, 1); PG8_STAGE(PG8_SB(1, 0), b3, voffB); PG8_STAGE(PG8_SB(1, 1), b3 + hstep, voffB); PG8_STAGE(PG8_SA(1, 0), a3, voffA);
;             PG8_WAIT_V(8); PG8_WAIT_L(0); PG8_BAR; PG8_MMA(1, 0, At, B0); PG8_MMA(1, 1, At, B1); PG8_BAR; PG8_SCHED;
;     ...
;         for (int a = 0; a < 2; ++a)
; #pragma unroll
;             for (int b = 0; b < 2; ++b)
; #pragma unroll
;                 for (int m = 0; m < 4; ++m)
; #pragma unroll
;                     for (int n = 0; n < 2; ++n) acc[a][b][m][n] = (f32x4){0.f, 0.f, 0.f, 0.f};
	s_setprio 0
	s_add_i32 s22, s54, s30
	v_lshl_add_u64 v[130:131], v[202:203], 0, s[94:95]
	s_mov_b32 m0, s22
	ds_read_b128 v[122:125], v73 offset:49152
	ds_read_b128 v[126:129], v73 offset:50176
	ds_read_b128 v[194:197], v73 offset:51200
	ds_read_b128 v[198:201], v73 offset:52224
	ds_read_b128 v[206:209], v73 offset:53248
	ds_read_b128 v[214:217], v73 offset:54272
	ds_read_b128 v[218:221], v73 offset:55296
	ds_read_b128 v[222:225], v73 offset:56320
	global_load_lds_dwordx4 v[130:131], off
	s_add_i32 m0, s22, 0x2000
	s_add_u32 s20, s20, 0x40080
	v_lshl_add_u64 v[130:131], v[210:211], 0, s[94:95]
	s_addc_u32 s21, s21, 0
	s_add_i32 s22, s55, s30
	global_load_lds_dwordx4 v[130:131], off
	s_mov_b32 m0, s22
	v_lshl_add_u64 v[130:131], s[20:21], 0, v[64:65]
	global_load_lds_dwordx4 v[130:131], off
	s_add_i32 m0, s22, 0x2000
	v_lshl_add_u64 v[130:131], s[20:21], 0, v[52:53]
	global_load_lds_dwordx4 v[130:131], off
	s_mov_b32 m0, s45
	v_lshl_add_u64 v[130:131], v[226:227], 0, s[94:95]
	global_load_lds_dwordx4 v[130:131], off
	s_mov_b32 m0, s46
	v_lshl_add_u64 v[130:131], v[228:229], 0, s[94:95]
	global_load_lds_dwordx4 v[130:131], off
	s_waitcnt vmcnt(8) lgkmcnt(0)
	s_setprio 1
	s_barrier
	v_mfma_f32_16x16x32_bf16 v[130:133], v[82:85], v[122:125], v[158:161]
	v_mfma_f32_16x16x32_bf16 v[158:161], v[86:89], v[126:129], v[130:133]
	v_mfma_f32_16x16x32_bf16 v[130:133], v[90:93], v[122:125], v[154:157]
	v_mfma_f32_16x16x32_bf16 v[154:157], v[94:97], v[126:129], v[130:133]
	v_mfma_f32_16x16x32_bf16 v[130:133], v[82:85], v[194:197], v[150:153]
	v_mfma_f32_16x16x32_bf16 v[150:153], v[86:89], v[198:201], v[130:133]
	v_mfma_f32_16x16x32_bf16 v[130:133], v[90:93], v[194:197], v[146:149]
	v_mfma_f32_16x16x32_bf16 v[146:149], v[94:97], v[198:201], v[130:133]
	v_mfma_f32_16x16x32_bf16 v[130:133], v[82:85], v[206:209], v[142:145]
	v_mfma_f32_16x16x32_bf16 v[74:77], v[82:85], v[218:221], v[74:77]
	v_mfma_f32_16x16x32_bf16 v[142:145], v[86:89], v[214:217], v[130:133]
	v_mfma_f32_16x16x32_bf16 v[130:133], v[90:93], v[206:209], v[138:141]
	v_mfma_f32_16x16x32_bf16 v[134:137], v[86:89], v[222:225], v[74:77]
	v_mfma_f32_16x16x32_bf16 v[74:77], v[90:93], v[218:221], v[78:81]
	v_mfma_f32_16x16x32_bf16 v[138:141], v[94:97], v[214:217], v[130:133]
	v_mfma_f32_16x16x32_bf16 v[130:133], v[94:97], v[222:225], v[74:77]
	v_mfma_f32_16x16x32_bf16 v[28:31], v[106:109], v[122:125], v[28:31]
	v_mfma_f32_16x16x32_bf16 v[24:27], v[114:117], v[122:125], v[24:27]
	v_mfma_f32_16x16x32_bf16 v[20:23], v[106:109], v[194:197], v[20:23]
	v_mfma_f32_16x16x32_bf16 v[16:19], v[114:117], v[194:197], v[16:19]
	v_mfma_f32_16x16x32_bf16 v[12:15], v[106:109], v[206:209], v[12:15]
	v_mfma_f32_16x16x32_bf16 v[8:11], v[114:117], v[206:209], v[8:11]
	v_mfma_f32_16x16x32_bf16 v[4:7], v[106:109], v[218:221], v[4:7]
	v_mfma_f32_16x16x32_bf16 v[0:3], v[114:117], v[218:221], v[0:3]
	v_mfma_f32_16x16x32_bf16 v[28:31], v[110:113], v[126:129], v[28:31]
	v_mfma_f32_16x16x32_bf16 v[24:27], v[118:121], v[126:129], v[24:27]
	v_mfma_f32_16x16x32_bf16 v[20:23], v[110:113], v[198:201], v[20:23]
	v_mfma_f32_16x16x32_bf16 v[16:19], v[118:121], v[198:201], v[16:19]
	v_mfma_f32_16x16x32_bf16 v[12:15], v[110:113], v[214:217], v[12:15]
	v_mfma_f32_16x16x32_bf16 v[8:11], v[118:121], v[214:217], v[8:11]
	v_mfma_f32_16x16x32_bf16 v[4:7], v[110:113], v[222:225], v[4:7]
	v_mfma_f32_16x16x32_bf16 v[0:3], v[118:121], v[222:225], v[0:3]
	s_barrier
	s_setprio 0
	s_add_i32 s53, s53, 2
	s_add_u32 s18, s18, 0x100
	s_addc_u32 s19, s19, 0
	s_cmp_gt_u32 s53, 13
	s_cbranch_scc0 .LBB0_286
	s_add_u32 s18, s49, 0xffffff00
	s_addc_u32 s19, s50, -1
	s_andn2_b64 vcc, exec, s[2:3]
	s_cbranch_vccnz .LBB0_289
	v_mov_b32_e32 v0, 0
	s_mov_b32 s4, s10
	s_mov_b32 s24, s12
	s_mov_b64 s[8:9], s[16:17]
	s_mov_b32 s47, s48
	v_mov_b32_e32 v1, v0
	v_mov_b32_e32 v2, v0
	v_mov_b32_e32 v3, v0
	v_mov_b32_e32 v4, v0
	v_mov_b32_e32 v5, v0
	v_mov_b32_e32 v6, v0
	v_mov_b32_e32 v7, v0
	v_mov_b32_e32 v8, v0
	v_mov_b32_e32 v9, v0
	v_mov_b32_e32 v10, v0
	v_mov_b32_e32 v11, v0
	v_mov_b32_e32 v12, v0
	v_mov_b32_e32 v13, v0
	v_mov_b32_e32 v14, v0
	v_mov_b32_e32 v15, v0
	v_mov_b32_e32 v16, v0
	v_mov_b32_e32 v17, v0
	v_mov_b32_e32 v18, v0
	v_mov_b32_e32 v19, v0
	v_mov_b32_e32 v20, v0
	v_mov_b32_e32 v21, v0
	v_mov_b32_e32 v22, v0
	v_mov_b32_e32 v23, v0
	v_mov_b32_e32 v24, v0
	v_mov_b32_e32 v25, v0
	v_mov_b32_e32 v26, v0
	v_mov_b32_e32 v27, v0
	v_mov_b32_e32 v28, v0
	v_mov_b32_e32 v29, v0
	v_mov_b32_e32 v30, v0
	v_mov_b32_e32 v31, v0
	v_mov_b32_e32 v130, v0
	v_mov_b32_e32 v131, v0
	v_mov_b32_e32 v132, v0
	v_mov_b32_e32 v133, v0
	v_mov_b32_e32 v134, v0
	v_mov_b32_e32 v135, v0
	v_mov_b32_e32 v136, v0
	v_mov_b32_e32 v137, v0
	v_mov_b32_e32 v138, v0
	v_mov_b32_e32 v139, v0
	v_mov_b32_e32 v140, v0
	v_mov_b32_e32 v141, v0
	v_mov_b32_e32 v142, v0
	v_mov_b32_e32 v143, v0
	v_mov_b32_e32 v144, v0
	v_mov_b32_e32 v145, v0
	v_mov_b32_e32 v146, v0
	v_mov_b32_e32 v147, v0
	v_mov_b32_e32 v148, v0
	v_mov_b32_e32 v149, v0
	v_mov_b32_e32 v150, v0
	v_mov_b32_e32 v151, v0
	v_mov_b32_e32 v152, v0
	v_mov_b32_e32 v153, v0
	v_mov_b32_e32 v154, v0
	v_mov_b32_e32 v155, v0
	v_mov_b32_e32 v156, v0
	v_mov_b32_e32 v157, v0
	v_mov_b32_e32 v158, v0
	v_mov_b32_e32 v159, v0
	v_mov_b32_e32 v160, v0
	v_mov_b32_e32 v161, v0
	v_mov_b32_e32 v32, v0
	v_mov_b32_e32 v33, v0
	v_mov_b32_e32 v34, v0
	v_mov_b32_e32 v35, v0
	v_mov_b32_e32 v36, v0
	v_mov_b32_e32 v37, v0
	v_mov_b32_e32 v38, v0
	v_mov_b32_e32 v39, v0
	v_mov_b32_e32 v40, v0
	v_mov_b32_e32 v41, v0
	v_mov_b32_e32 v42, v0
	v_mov_b32_e32 v43, v0
	v_mov_b32_e32 v44, v0
	v_mov_b32_e32 v45, v0
	v_mov_b32_e32 v46, v0
	v_mov_b32_e32 v47, v0
	v_mov_b32_e32 v48, v0
	v_mov_b32_e32 v49, v0
	v_mov_b32_e32 v50, v0
	v_mov_b32_e32 v51, v0
	v_mov_b32_e32 v56, v0
	v_mov_b32_e32 v57, v0
	v_mov_b32_e32 v58, v0
	v_mov_b32_e32 v59, v0
	v_mov_b32_e32 v98, v0
	v_mov_b32_e32 v99, v0
	v_mov_b32_e32 v100, v0
	v_mov_b32_e32 v101, v0
	v_mov_b32_e32 v102, v0
	v_mov_b32_e32 v103, v0
	v_mov_b32_e32 v104, v0
	v_mov_b32_e32 v105, v0
	v_mov_b32_e32 v162, v0
	v_mov_b32_e32 v163, v0
	v_mov_b32_e32 v164, v0
	v_mov_b32_e32 v165, v0
	v_mov_b32_e32 v166, v0
	v_mov_b32_e32 v167, v0
	v_mov_b32_e32 v168, v0
	v_mov_b32_e32 v169, v0
	v_mov_b32_e32 v170, v0
	v_mov_b32_e32 v171, v0
	v_mov_b32_e32 v172, v0
	v_mov_b32_e32 v173, v0
	v_mov_b32_e32 v174, v0
	v_mov_b32_e32 v175, v0
	v_mov_b32_e32 v176, v0
	v_mov_b32_e32 v177, v0
	v_mov_b32_e32 v178, v0
	v_mov_b32_e32 v179, v0
	v_mov_b32_e32 v180, v0
	v_mov_b32_e32 v181, v0
	v_mov_b32_e32 v182, v0
	v_mov_b32_e32 v183, v0
	v_mov_b32_e32 v184, v0
	v_mov_b32_e32 v185, v0
	v_mov_b32_e32 v186, v0
	v_mov_b32_e32 v187, v0
	v_mov_b32_e32 v188, v0
	v_mov_b32_e32 v189, v0
	v_mov_b32_e32 v190, v0
	v_mov_b32_e32 v191, v0
	v_mov_b32_e32 v192, v0
	v_mov_b32_e32 v193, v0
	s_andn2_b64 vcc, exec, s[0:1]
	s_cbranch_vccnz .LBB0_290
	s_branch .LBB0_291

; #define PG8_STAGE(bufoff, gbase, voff) do { _Pragma("unroll") for (int _i = 0; _i < 2; ++_i) \
;         __builtin_amdgcn_global_load_lds((const unsigned*)((const char*)(gbase) + (voff)[_i]), (PG8_LAS unsigned*)(lds + (bufoff) + ldsw + _i * 8192), 16, 0, 0); } while (0)
; #define PG8_LDA(dst, b, h) do { _Pragma("unroll") for (int m = 0; m < 4; ++m) _Pragma("unroll") for (int k = 0; k < 2; ++k) dst[m][k] = *(const PG8_LAS bf16x8*)(lds + PG8_SA(b, h) + aoff + m * 2048 + k * 1024); } while (0)
; #define PG8_LDB(dst, b, h) do { _Pragma("unroll") for (int n = 0; n < 2; ++n) _Pragma("unroll") for (int k = 0; k < 2; ++k) dst[n][k] = *(const PG8_LAS bf16x8*)(lds + PG8_SB(b, h) + boff + n * 2048 + k * 1024); } while (0)
; #define PG8_WAIT_V(n) asm volatile("s_waitcnt vmcnt(" #n ")" ::: "memory")
; #define PG8_WAIT_L(n) asm volatile("s_waitcnt lgkmcnt(" #n ")" ::: "memory")
; #define PG8_BAR __builtin_amdgcn_s_barrier()
; template <class Epi, class Sched, bool ALIGN_EPI = false, bool SP2 = false>
; __device__ __forceinline__ void gemm_phase(PG8_LAS unsigned char* lds, const Gemm g, const Sched& S, const Epi& E, const int tid) {
;     ...
;     f32x4 acc[2][2][4][2];
; #pragma unroll
;     for (int a = 0; a < 2; ++a)
; #pragma unroll
;         for (int b = 0; b < 2; ++b)
; #pragma unroll
;             for (int m = 0; m < 4; ++m)
; #pragma unroll
;                 for (int n = 0; n < 2; ++n) acc[a][b][m][n] = (f32x4){0.f, 0.f, 0.f, 0.f};
;     ...
;         for (int t = 0; t < nt; t += 2) {
;             const bool last = (t == nt - 2);
;             const char* a1 = cA + (size_t)(t + 1) * kstep;
;             const char* a2 = last ? nA : cA + (size_t)(t + 2) * kstep; const char* b2 = last ? nB : cB + (size_t)(t + 2) * kstep;
;             const char* a3 = a2 + kstep; const char* b3 = b2 + kstep;
;             if (last && has_next) S.a_ready(nxt);
;             if constexpr (SP2) {
;             PG8_LDB(B0, 0, 0); PG8_LDB(B1, 0, 1); PG8_SCHED; PG8_LDA(At, 0, 0); PG8_STAGE(PG8_SA(1, 1), a1 + hstep, voffA);
;             PG8_WAIT_V(8); PG8_WAIT_L(0); PG8_BAR; PG8_MMA(0, 0, At, B0); PG8_MMA(0, 1, At, B1); PG8_BAR; PG8_SCHED;
;             PG8_LDA(At, 0, 1); PG8_STAGE(PG8_SB(0, 0), b2, voffB); PG8_STAGE(PG8_SB(0, 1), b2 + hstep, voffB); PG8_STAGE(PG8_SA(0, 0), a2, voffA);
;             PG8_WAIT_V(8); PG8_WAIT_L(0); PG8_BAR; PG8_MMA(1, 0, At, B0); PG8_MMA(1, 1, At, B1); PG8_BAR; PG8_SCHED;
.LBB0_348:
	s_add_i32 s47, 0, 0x10000
	s_add_i32 s45, 0, 0x14000
	v_add_u32_e32 v8, s47, v141
	v_add_u32_e32 v9, s45, v141
	ds_read_b128 v[10:13], v8
	ds_read_b128 v[14:17], v8 offset:1024
	ds_read_b128 v[18:21], v8 offset:2048
	ds_read_b128 v[22:25], v8 offset:3072
	ds_read_b128 v[26:29], v9
	ds_read_b128 v[30:33], v9 offset:1024
	ds_read_b128 v[34:37], v9 offset:2048
	ds_read_b128 v[38:41], v9 offset:3072
	s_add_u32 s2, s14, 0x18080
	s_addc_u32 s3, s15, 0
	s_add_i32 s50, s23, 0xc000
	v_lshl_add_u64 v[62:63], s[2:3], 0, v[136:137]
	s_mov_b32 m0, s50
	ds_read_b128 v[0:3], v142
	ds_read_b128 v[4:7], v142 offset:1024
	ds_read_b128 v[42:45], v142 offset:2048
	ds_read_b128 v[46:49], v142 offset:3072
	ds_read_b128 v[50:53], v142 offset:4096
	ds_read_b128 v[54:57], v142 offset:5120
	ds_read_b128 v[58:61], v142 offset:6144
	ds_read_b128 v[66:69], v142 offset:7168
	global_load_lds_dwordx4 v[62:63], off
	v_lshl_add_u64 v[62:63], s[2:3], 0, v[132:133]
	s_add_i32 s2, s23, 0xe000
	s_mov_b32 m0, s2
	s_nop 0
	global_load_lds_dwordx4 v[62:63], off
	s_waitcnt vmcnt(8) lgkmcnt(0)
	s_setprio 1
	s_barrier
	v_mfma_f32_16x16x32_bf16 v[70:73], v[10:13], v[0:3], 0
	v_mfma_f32_16x16x32_bf16 v[74:77], v[18:21], v[0:3], 0
	v_mfma_f32_16x16x32_bf16 v[78:81], v[10:13], v[42:45], 0
	v_mfma_f32_16x16x32_bf16 v[82:85], v[18:21], v[42:45], 0
	v_mfma_f32_16x16x32_bf16 v[86:89], v[10:13], v[50:53], 0
	v_mfma_f32_16x16x32_bf16 v[90:93], v[18:21], v[50:53], 0
	v_mfma_f32_16x16x32_bf16 v[94:97], v[10:13], v[58:61], 0
	v_mfma_f32_16x16x32_bf16 v[98:101], v[18:21], v[58:61], 0
	v_mfma_f32_16x16x32_bf16 v[70:73], v[14:17], v[4:7], v[70:73]
	v_mfma_f32_16x16x32_bf16 v[74:77], v[22:25], v[4:7], v[74:77]
	v_mfma_f32_16x16x32_bf16 v[78:81], v[14:17], v[46:49], v[78:81]
	v_mfma_f32_16x16x32_bf16 v[82:85], v[22:25], v[46:49], v[82:85]
	v_mfma_f32_16x16x32_bf16 v[86:89], v[14:17], v[54:57], v[86:89]
	v_mfma_f32_16x16x32_bf16 v[90:93], v[22:25], v[54:57], v[90:93]
	v_mfma_f32_16x16x32_bf16 v[94:97], v[14:17], v[66:69], v[94:97]
	v_mfma_f32_16x16x32_bf16 v[98:101], v[22:25], v[66:69], v[98:101]
	v_mfma_f32_16x16x32_bf16 v[102:105], v[26:29], v[0:3], 0
	v_mfma_f32_16x16x32_bf16 v[0:3], v[34:37], v[0:3], 0
	v_mfma_f32_16x16x32_bf16 v[106:109], v[38:41], v[4:7], v[0:3]
	v_mfma_f32_16x16x32_bf16 v[0:3], v[26:29], v[42:45], 0
	v_mfma_f32_16x16x32_bf16 v[110:113], v[30:33], v[46:49], v[0:3]
	v_mfma_f32_16x16x32_bf16 v[0:3], v[34:37], v[42:45], 0
	v_mfma_f32_16x16x32_bf16 v[42:45], v[38:41], v[46:49], v[0:3]
	v_mfma_f32_16x16x32_bf16 v[0:3], v[26:29], v[50:53], 0
	v_mfma_f32_16x16x32_bf16 v[46:49], v[30:33], v[54:57], v[0:3]
	v_mfma_f32_16x16x32_bf16 v[0:3], v[34:37], v[50:53], 0
	v_mfma_f32_16x16x32_bf16 v[50:53], v[38:41], v[54:57], v[0:3]
	v_mfma_f32_16x16x32_bf16 v[0:3], v[26:29], v[58:61], 0
	v_mfma_f32_16x16x32_bf16 v[54:57], v[30:33], v[66:69], v[0:3]
	v_mfma_f32_16x16x32_bf16 v[0:3], v[34:37], v[58:61], 0
	v_mfma_f32_16x16x32_bf16 v[102:105], v[30:33], v[4:7], v[102:105]
	v_mfma_f32_16x16x32_bf16 v[58:61], v[38:41], v[66:69], v[0:3]
	s_barrier
	s_setprio 0
	s_nop 3
	v_lshl_add_u64 v[0:1], s[16:17], 0, v[134:135]
	s_mov_b64 s[52:53], 0x100
	s_add_i32 s47, s47, s22
	v_lshl_add_u64 v[2:3], v[0:1], 0, s[52:53]
	s_mov_b32 m0, s47
	s_add_i32 s3, s47, 0x2000
	ds_read_b128 v[66:69], v142 offset:16384
	ds_read_b128 v[114:117], v142 offset:17408
	ds_read_b128 v[118:121], v142 offset:18432
	ds_read_b128 v[122:125], v142 offset:19456
	ds_read_b128 v[126:129], v142 offset:20480
	ds_read_b128 v[144:147], v142 offset:21504
	ds_read_b128 v[148:151], v142 offset:22528
	ds_read_b128 v[152:155], v142 offset:23552
	global_load_lds_dwordx4 v[2:3], off
	v_lshl_add_u64 v[2:3], s[16:17], 0, v[130:131]
	s_add_u32 s48, s16, 0x18100
	v_lshl_add_u64 v[4:5], v[2:3], 0, s[52:53]
	s_mov_b32 m0, s3
	s_addc_u32 s49, s17, 0
	s_add_i32 s45, s45, s22
	global_load_lds_dwordx4 v[4:5], off
	v_lshl_add_u64 v[4:5], s[48:49], 0, v[134:135]
	s_mov_b32 m0, s45
	s_add_i32 s46, s45, 0x2000
	global_load_lds_dwordx4 v[4:5], off
	s_mov_b32 m0, s46
	v_lshl_add_u64 v[4:5], s[48:49], 0, v[130:131]
	global_load_lds_dwordx4 v[4:5], off
	v_lshl_add_u64 v[4:5], s[14:15], 0, v[136:137]
	s_mov_b32 m0, s23
	v_lshl_add_u64 v[6:7], v[4:5], 0, s[52:53]
	global_load_lds_dwordx4 v[6:7], off
	v_lshl_add_u64 v[6:7], s[14:15], 0, v[132:133]
	s_mov_b32 m0, s24
	v_lshl_add_u64 v[62:63], v[6:7], 0, s[52:53]
	global_load_lds_dwordx4 v[62:63], off
	s_waitcnt vmcnt(8) lgkmcnt(0)
	s_setprio 1
	s_barrier
	v_mfma_f32_16x16x32_bf16 v[156:159], v[10:13], v[66:69], 0
	v_mfma_f32_16x16x32_bf16 v[164:167], v[10:13], v[118:121], 0
	v_mfma_f32_16x16x32_bf16 v[172:175], v[10:13], v[126:129], 0
	v_mfma_f32_16x16x32_bf16 v[10:13], v[10:13], v[148:151], 0
	v_mfma_f32_16x16x32_bf16 v[156:159], v[14:17], v[114:117], v[156:159]
	v_mfma_f32_16x16x32_bf16 v[160:163], v[18:21], v[66:69], 0
	v_mfma_f32_16x16x32_bf16 v[164:167], v[14:17], v[122:125], v[164:167]
	v_mfma_f32_16x16x32_bf16 v[168:171], v[18:21], v[118:121], 0
	v_mfma_f32_16x16x32_bf16 v[172:175], v[14:17], v[144:147], v[172:175]
	v_mfma_f32_16x16x32_bf16 v[176:179], v[18:21], v[126:129], 0
	v_mfma_f32_16x16x32_bf16 v[12:15], v[14:17], v[152:155], v[10:13]
	v_mfma_f32_16x16x32_bf16 v[16:19], v[18:21], v[148:151], 0
	v_mfma_f32_16x16x32_bf16 v[16:19], v[22:25], v[152:155], v[16:19]
	v_mfma_f32_16x16x32_bf16 v[160:163], v[22:25], v[114:117], v[160:163]
	v_mfma_f32_16x16x32_bf16 v[168:171], v[22:25], v[122:125], v[168:171]
	v_mfma_f32_16x16x32_bf16 v[176:179], v[22:25], v[144:147], v[176:179]
	v_mfma_f32_16x16x32_bf16 v[20:23], v[26:29], v[66:69], 0
	v_mfma_f32_16x16x32_bf16 v[66:69], v[34:37], v[66:69], 0
	v_mfma_f32_16x16x32_bf16 v[20:23], v[30:33], v[114:117], v[20:23]
	v_mfma_f32_16x16x32_bf16 v[66:69], v[38:41], v[114:117], v[66:69]
	v_mfma_f32_16x16x32_bf16 v[114:117], v[26:29], v[118:121], 0
	v_mfma_f32_16x16x32_bf16 v[118:121], v[34:37], v[118:121], 0
	v_mfma_f32_16x16x32_bf16 v[114:117], v[30:33], v[122:125], v[114:117]
	v_mfma_f32_16x16x32_bf16 v[118:121], v[38:41], v[122:125], v[118:121]
	v_mfma_f32_16x16x32_bf16 v[122:125], v[26:29], v[126:129], 0
	v_mfma_f32_16x16x32_bf16 v[24:27], v[26:29], v[148:151], 0
	v_mfma_f32_16x16x32_bf16 v[122:125], v[30:33], v[144:147], v[122:125]
	v_mfma_f32_16x16x32_bf16 v[126:129], v[34:37], v[126:129], 0
	v_mfma_f32_16x16x32_bf16 v[24:27], v[30:33], v[152:155], v[24:27]
	v_mfma_f32_16x16x32_bf16 v[28:31], v[34:37], v[148:151], 0
	v_mfma_f32_16x16x32_bf16 v[126:129], v[38:41], v[144:147], v[126:129]
	v_mfma_f32_16x16x32_bf16 v[28:31], v[38:41], v[152:155], v[28:31]
	s_barrier
; #define PG8_STAGE(bufoff, gbase, voff) do { _Pragma("unroll") for (int _i = 0; _i < 2; ++_i) \
;         __builtin_amdgcn_global_load_lds((const unsigned*)((const char*)(gbase) + (voff)[_i]), (PG8_LAS unsigned*)(lds + (bufoff) + ldsw + _i * 8192), 16, 0, 0); } while (0)
; #define PG8_LDA(dst, b, h) do { _Pragma("unroll") for (int m = 0; m < 4; ++m) _Pragma("unroll") for (int k = 0; k < 2; ++k) dst[m][k] = *(const PG8_LAS bf16x8*)(lds + PG8_SA(b, h) + aoff + m * 2048 + k * 1024); } while (0)
; #define PG8_LDB(dst, b, h) do { _Pragma("unroll") for (int n = 0; n < 2; ++n) _Pragma("unroll") for (int k = 0; k < 2; ++k) dst[n][k] = *(const PG8_LAS bf16x8*)(lds + PG8_SB(b, h) + boff + n * 2048 + k * 1024); } while (0)
; #define PG8_MMA(ai, bj, At, Bt) do { __builtin_amdgcn_s_setprio(1); _Pragma("unroll") for (int m = 0; m < 4; ++m) _Pragma("unroll") for (int n = 0; n < 2; ++n) _Pragma("unroll") for (int k = 0; k < 2; ++k) \
;         acc[ai][bj][m][n] = __builtin_amdgcn_mfma_f32_16x16x32_bf16(Bt[n][k], At[m][k], acc[ai][bj][m][n], 0, 0, 0); __builtin_amdgcn_s_setprio(0); } while (0)
; #define PG8_WAIT_V(n) asm volatile("s_waitcnt vmcnt(" #n ")" ::: "memory")
; #define PG8_WAIT_L(n) asm volatile("s_waitcnt lgkmcnt(" #n ")" ::: "memory")
; #define PG8_BAR __builtin_amdgcn_s_barrier()
; #define PG8_SCHED __builtin_amdgcn_sched_barrier(0)
; template <class Epi, class Sched, bool ALIGN_EPI = false, bool SP2 = false>
; __device__ __forceinline__ void gemm_phase(PG8_LAS unsigned char* lds, const Gemm g, const Sched& S, const Epi& E, const int tid) {
;     ...
;             PG8_LDB(B0, 1, 0); PG8_LDB(B1, 1, 1); PG8_SCHED; PG8_LDA(At, 1, 0); PG8_STAGE(PG8_SA(0, 1), a2 + hstep, voffA);
;             PG8_WAIT_V(8); PG8_WAIT_L(0); PG8_BAR; PG8_MMA(0, 0, At, B0); PG8_MMA(0, 1, At, B1); PG8_BAR; PG8_SCHED;
;             PG8_LDA(At, 1, 1); PG8_STAGE(PG8_SB(1, 0), b3, voffB); PG8_STAGE(PG8_SB(1, 1), b3 + hstep, voffB); PG8_STAGE(PG8_SA(1, 0), a3, voffA);
	s_setprio 0
	s_add_i32 s52, 0, 0x18000
	s_add_i32 s51, 0, 0x1c000
	v_add_u32_e32 v10, s52, v141
	v_add_u32_e32 v11, s51, v141
	ds_read_b128 v[32:35], v10
	ds_read_b128 v[36:39], v10 offset:1024
	ds_read_b128 v[144:147], v10 offset:2048
	ds_read_b128 v[148:151], v10 offset:3072
	ds_read_b128 v[152:155], v11
	ds_read_b128 v[180:183], v11 offset:1024
	ds_read_b128 v[184:187], v11 offset:2048
	ds_read_b128 v[188:191], v11 offset:3072
	s_add_u32 s48, s14, 0x18100
	s_addc_u32 s49, s15, 0
	s_mov_b32 m0, s25
	v_lshl_add_u64 v[40:41], s[48:49], 0, v[136:137]
	ds_read_b128 v[192:195], v142 offset:32768
	ds_read_b128 v[196:199], v142 offset:33792
	ds_read_b128 v[214:217], v142 offset:34816
	ds_read_b128 v[218:221], v142 offset:35840
	ds_read_b128 v[222:225], v142 offset:36864
	ds_read_b128 v[226:229], v142 offset:37888
	ds_read_b128 v[248:251], v142 offset:38912
	ds_read_b128 v[206:209], v142 offset:39936
	global_load_lds_dwordx4 v[40:41], off
	s_mov_b32 m0, s26
	v_lshl_add_u64 v[40:41], s[48:49], 0, v[132:133]
	global_load_lds_dwordx4 v[40:41], off
	s_waitcnt vmcnt(8) lgkmcnt(0)
	s_setprio 1
	s_barrier
	v_mfma_f32_16x16x32_bf16 v[70:73], v[32:35], v[192:195], v[70:73]
	v_mfma_f32_16x16x32_bf16 v[74:77], v[144:147], v[192:195], v[74:77]
	v_mfma_f32_16x16x32_bf16 v[78:81], v[32:35], v[214:217], v[78:81]
	v_mfma_f32_16x16x32_bf16 v[82:85], v[144:147], v[214:217], v[82:85]
	v_mfma_f32_16x16x32_bf16 v[86:89], v[32:35], v[222:225], v[86:89]
	v_mfma_f32_16x16x32_bf16 v[90:93], v[144:147], v[222:225], v[90:93]
	v_mfma_f32_16x16x32_bf16 v[94:97], v[32:35], v[248:251], v[94:97]
	v_mfma_f32_16x16x32_bf16 v[98:101], v[144:147], v[248:251], v[98:101]
	v_mfma_f32_16x16x32_bf16 v[70:73], v[36:39], v[196:199], v[70:73]
	v_mfma_f32_16x16x32_bf16 v[74:77], v[148:151], v[196:199], v[74:77]
	v_mfma_f32_16x16x32_bf16 v[78:81], v[36:39], v[218:221], v[78:81]
	v_mfma_f32_16x16x32_bf16 v[82:85], v[148:151], v[218:221], v[82:85]
	v_mfma_f32_16x16x32_bf16 v[86:89], v[36:39], v[226:229], v[86:89]
	v_mfma_f32_16x16x32_bf16 v[90:93], v[148:151], v[226:229], v[90:93]
	v_mfma_f32_16x16x32_bf16 v[94:97], v[36:39], v[206:209], v[94:97]
	v_mfma_f32_16x16x32_bf16 v[98:101], v[148:151], v[206:209], v[98:101]
	v_mfma_f32_16x16x32_bf16 v[102:105], v[152:155], v[192:195], v[102:105]
	v_mfma_f32_16x16x32_bf16 v[106:109], v[184:187], v[192:195], v[106:109]
	v_mfma_f32_16x16x32_bf16 v[110:113], v[152:155], v[214:217], v[110:113]
	v_mfma_f32_16x16x32_bf16 v[40:43], v[184:187], v[214:217], v[42:45]
	v_mfma_f32_16x16x32_bf16 v[44:47], v[152:155], v[222:225], v[46:49]
	v_mfma_f32_16x16x32_bf16 v[48:51], v[184:187], v[222:225], v[50:53]
	v_mfma_f32_16x16x32_bf16 v[52:55], v[152:155], v[248:251], v[54:57]
	v_mfma_f32_16x16x32_bf16 v[56:59], v[184:187], v[248:251], v[58:61]
	v_mfma_f32_16x16x32_bf16 v[102:105], v[180:183], v[196:199], v[102:105]
	v_mfma_f32_16x16x32_bf16 v[106:109], v[188:191], v[196:199], v[106:109]
	v_mfma_f32_16x16x32_bf16 v[110:113], v[180:183], v[218:221], v[110:113]
	v_mfma_f32_16x16x32_bf16 v[40:43], v[188:191], v[218:221], v[40:43]
	v_mfma_f32_16x16x32_bf16 v[44:47], v[180:183], v[226:229], v[44:47]
	v_mfma_f32_16x16x32_bf16 v[48:51], v[188:191], v[226:229], v[48:51]
	v_mfma_f32_16x16x32_bf16 v[52:55], v[180:183], v[206:209], v[52:55]
	v_mfma_f32_16x16x32_bf16 v[56:59], v[188:191], v[206:209], v[56:59]
	s_barrier
	s_setprio 0
	s_add_i32 s52, s52, s22
	s_mov_b64 s[56:57], 0x180
	s_add_i32 s48, s52, 0x2000
	v_lshl_add_u64 v[138:139], v[0:1], 0, s[56:57]
	s_mov_b32 m0, s52
	s_add_u32 s54, s16, 0x18180
	ds_read_b128 v[60:63], v142 offset:49152
	ds_read_b128 v[192:195], v142 offset:50176
	ds_read_b128 v[196:199], v142 offset:51200
	ds_read_b128 v[206:209], v142 offset:52224
	ds_read_b128 v[214:217], v142 offset:53248
	ds_read_b128 v[218:221], v142 offset:54272
	ds_read_b128 v[222:225], v142 offset:55296
	ds_read_b128 v[226:229], v142 offset:56320
	global_load_lds_dwordx4 v[138:139], off
	v_lshl_add_u64 v[138:139], v[2:3], 0, s[56:57]
	s_mov_b32 m0, s48
	s_addc_u32 s55, s17, 0
	s_add_i32 s49, s51, s22
	global_load_lds_dwordx4 v[138:139], off
	v_lshl_add_u64 v[138:139], s[54:55], 0, v[134:135]
	s_mov_b32 m0, s49
	s_add_i32 s51, s49, 0x2000
	global_load_lds_dwordx4 v[138:139], off
	s_mov_b32 m0, s51
	v_lshl_add_u64 v[138:139], s[54:55], 0, v[130:131]
	global_load_lds_dwordx4 v[138:139], off
	s_mov_b32 m0, s28
	v_lshl_add_u64 v[138:139], v[4:5], 0, s[56:57]
	global_load_lds_dwordx4 v[138:139], off
	s_mov_b32 m0, s29
	v_lshl_add_u64 v[138:139], v[6:7], 0, s[56:57]
	global_load_lds_dwordx4 v[138:139], off
	s_waitcnt vmcnt(8) lgkmcnt(0)
	s_setprio 1
	s_barrier
; #define PG8_STAGE(bufoff, gbase, voff) do { _Pragma("unroll") for (int _i = 0; _i < 2; ++_i) \
;         __builtin_amdgcn_global_load_lds((const unsigned*)((const char*)(gbase) + (voff)[_i]), (PG8_LAS unsigned*)(lds + (bufoff) + ldsw + _i * 8192), 16, 0, 0); } while (0)
; #define PG8_LDA(dst, b, h) do { _Pragma("unroll") for (int m = 0; m < 4; ++m) _Pragma("unroll") for (int k = 0; k < 2; ++k) dst[m][k] = *(const PG8_LAS bf16x8*)(lds + PG8_SA(b, h) + aoff + m * 2048 + k * 1024); } while (0)
; #define PG8_LDB(dst, b, h) do { _Pragma("unroll") for (int n = 0; n < 2; ++n) _Pragma("unroll") for (int k = 0; k < 2; ++k) dst[n][k] = *(const PG8_LAS bf16x8*)(lds + PG8_SB(b, h) + boff + n * 2048 + k * 1024); } while (0)
; #define PG8_MMA(ai, bj, At, Bt) do { __builtin_amdgcn_s_setprio(1); _Pragma("unroll") for (int m = 0; m < 4; ++m) _Pragma("unroll") for (int n = 0; n < 2; ++n) _Pragma("unroll") for (int k = 0; k < 2; ++k) \
;         acc[ai][bj][m][n] = __builtin_amdgcn_mfma_f32_16x16x32_bf16(Bt[n][k], At[m][k], acc[ai][bj][m][n], 0, 0, 0); __builtin_amdgcn_s_setprio(0); } while (0)
; #define PG8_WAIT_V(n) asm volatile("s_waitcnt vmcnt(" #n ")" ::: "memory")
; #define PG8_WAIT_L(n) asm volatile("s_waitcnt lgkmcnt(" #n ")" ::: "memory")
; #define PG8_BAR __builtin_amdgcn_s_barrier()
; #define PG8_SCHED __builtin_amdgcn_sched_barrier(0)
; template <class Epi, class Sched, bool ALIGN_EPI = false, bool SP2 = false>
; __device__ __forceinline__ void gemm_phase(PG8_LAS unsigned char* lds, const Gemm g, const Sched& S, const Epi& E, const int tid) {
;     ...
;             PG8_LDB(B0, 0, 0); PG8_LDB(B1, 0, 1); PG8_SCHED; PG8_LDA(At, 0, 0); PG8_STAGE(PG8_SA(1, 1), a1 + hstep, voffA);
;             PG8_WAIT_V(8); PG8_WAIT_L(0); PG8_BAR; PG8_MMA(0, 0, At, B0); PG8_MMA(0, 1, At, B1); PG8_BAR; PG8_SCHED;
;     ...
;             PG8_WAIT_V(8); PG8_WAIT_L(0); PG8_BAR; PG8_MMA(1, 0, At, B0); PG8_MMA(1, 1, At, B1); PG8_BAR; PG8_SCHED;
	v_mfma_f32_16x16x32_bf16 v[12:15], v[32:35], v[222:225], v[12:15]
	v_mfma_f32_16x16x32_bf16 v[16:19], v[144:147], v[222:225], v[16:19]
	v_mfma_f32_16x16x32_bf16 v[156:159], v[32:35], v[60:63], v[156:159]
	v_mfma_f32_16x16x32_bf16 v[160:163], v[144:147], v[60:63], v[160:163]
	v_mfma_f32_16x16x32_bf16 v[164:167], v[32:35], v[196:199], v[164:167]
	v_mfma_f32_16x16x32_bf16 v[168:171], v[144:147], v[196:199], v[168:171]
	v_mfma_f32_16x16x32_bf16 v[172:175], v[32:35], v[214:217], v[172:175]
	v_mfma_f32_16x16x32_bf16 v[176:179], v[144:147], v[214:217], v[176:179]
	v_mfma_f32_16x16x32_bf16 v[12:15], v[36:39], v[226:229], v[12:15]
	v_mfma_f32_16x16x32_bf16 v[16:19], v[148:151], v[226:229], v[16:19]
	v_mfma_f32_16x16x32_bf16 v[156:159], v[36:39], v[192:195], v[156:159]
	v_mfma_f32_16x16x32_bf16 v[160:163], v[148:151], v[192:195], v[160:163]
	v_mfma_f32_16x16x32_bf16 v[164:167], v[36:39], v[206:209], v[164:167]
	v_mfma_f32_16x16x32_bf16 v[168:171], v[148:151], v[206:209], v[168:171]
	v_mfma_f32_16x16x32_bf16 v[172:175], v[36:39], v[218:221], v[172:175]
	v_mfma_f32_16x16x32_bf16 v[176:179], v[148:151], v[218:221], v[176:179]
	v_mfma_f32_16x16x32_bf16 v[20:23], v[152:155], v[60:63], v[20:23]
	v_mfma_f32_16x16x32_bf16 v[32:35], v[184:187], v[60:63], v[66:69]
	v_mfma_f32_16x16x32_bf16 v[36:39], v[152:155], v[196:199], v[114:117]
	v_mfma_f32_16x16x32_bf16 v[60:63], v[184:187], v[196:199], v[118:121]
	v_mfma_f32_16x16x32_bf16 v[66:69], v[152:155], v[214:217], v[122:125]
	v_mfma_f32_16x16x32_bf16 v[114:117], v[184:187], v[214:217], v[126:129]
	v_mfma_f32_16x16x32_bf16 v[24:27], v[152:155], v[222:225], v[24:27]
	v_mfma_f32_16x16x32_bf16 v[28:31], v[184:187], v[222:225], v[28:31]
	v_mfma_f32_16x16x32_bf16 v[20:23], v[180:183], v[192:195], v[20:23]
	v_mfma_f32_16x16x32_bf16 v[32:35], v[188:191], v[192:195], v[32:35]
	v_mfma_f32_16x16x32_bf16 v[36:39], v[180:183], v[206:209], v[36:39]
	v_mfma_f32_16x16x32_bf16 v[60:63], v[188:191], v[206:209], v[60:63]
	v_mfma_f32_16x16x32_bf16 v[66:69], v[180:183], v[218:221], v[66:69]
	v_mfma_f32_16x16x32_bf16 v[114:117], v[188:191], v[218:221], v[114:117]
	v_mfma_f32_16x16x32_bf16 v[24:27], v[180:183], v[226:229], v[24:27]
	v_mfma_f32_16x16x32_bf16 v[28:31], v[188:191], v[226:229], v[28:31]
	s_barrier
	s_setprio 0
	ds_read_b128 v[118:121], v8
	ds_read_b128 v[122:125], v8 offset:1024
	ds_read_b128 v[126:129], v8 offset:2048
	ds_read_b128 v[144:147], v8 offset:3072
	ds_read_b128 v[148:151], v9
	ds_read_b128 v[152:155], v9 offset:1024
	ds_read_b128 v[180:183], v9 offset:2048
	ds_read_b128 v[184:187], v9 offset:3072
	s_add_u32 s54, s14, 0x18180
	s_addc_u32 s55, s15, 0
	s_mov_b32 m0, s50
	v_lshl_add_u64 v[138:139], s[54:55], 0, v[136:137]
	ds_read_b128 v[188:191], v142
	ds_read_b128 v[192:195], v142 offset:1024
	ds_read_b128 v[196:199], v142 offset:2048
	ds_read_b128 v[206:209], v142 offset:3072
	ds_read_b128 v[214:217], v142 offset:4096
	ds_read_b128 v[218:221], v142 offset:5120
	ds_read_b128 v[222:225], v142 offset:6144
	ds_read_b128 v[226:229], v142 offset:7168
	global_load_lds_dwordx4 v[138:139], off
	s_mov_b32 m0, s2
	v_lshl_add_u64 v[138:139], s[54:55], 0, v[132:133]
	global_load_lds_dwordx4 v[138:139], off
	s_waitcnt vmcnt(8) lgkmcnt(0)
	s_setprio 1
	s_barrier
	v_mfma_f32_16x16x32_bf16 v[70:73], v[118:121], v[188:191], v[70:73]
	v_mfma_f32_16x16x32_bf16 v[74:77], v[126:129], v[188:191], v[74:77]
	v_mfma_f32_16x16x32_bf16 v[78:81], v[118:121], v[196:199], v[78:81]
	v_mfma_f32_16x16x32_bf16 v[82:85], v[126:129], v[196:199], v[82:85]
	v_mfma_f32_16x16x32_bf16 v[86:89], v[118:121], v[214:217], v[86:89]
	v_mfma_f32_16x16x32_bf16 v[90:93], v[126:129], v[214:217], v[90:93]
	v_mfma_f32_16x16x32_bf16 v[94:97], v[118:121], v[222:225], v[94:97]
	v_mfma_f32_16x16x32_bf16 v[98:101], v[126:129], v[222:225], v[98:101]
	v_mfma_f32_16x16x32_bf16 v[70:73], v[122:125], v[192:195], v[70:73]
	v_mfma_f32_16x16x32_bf16 v[74:77], v[144:147], v[192:195], v[74:77]
	v_mfma_f32_16x16x32_bf16 v[78:81], v[122:125], v[206:209], v[78:81]
	v_mfma_f32_16x16x32_bf16 v[82:85], v[144:147], v[206:209], v[82:85]
	v_mfma_f32_16x16x32_bf16 v[86:89], v[122:125], v[218:221], v[86:89]
	v_mfma_f32_16x16x32_bf16 v[90:93], v[144:147], v[218:221], v[90:93]
	v_mfma_f32_16x16x32_bf16 v[94:97], v[122:125], v[226:229], v[94:97]
	v_mfma_f32_16x16x32_bf16 v[98:101], v[144:147], v[226:229], v[98:101]
	v_mfma_f32_16x16x32_bf16 v[102:105], v[148:151], v[188:191], v[102:105]
	v_mfma_f32_16x16x32_bf16 v[106:109], v[180:183], v[188:191], v[106:109]
	v_mfma_f32_16x16x32_bf16 v[110:113], v[148:151], v[196:199], v[110:113]
	v_mfma_f32_16x16x32_bf16 v[40:43], v[180:183], v[196:199], v[40:43]
	v_mfma_f32_16x16x32_bf16 v[44:47], v[148:151], v[214:217], v[44:47]
	v_mfma_f32_16x16x32_bf16 v[48:51], v[180:183], v[214:217], v[48:51]
	v_mfma_f32_16x16x32_bf16 v[52:55], v[148:151], v[222:225], v[52:55]
	v_mfma_f32_16x16x32_bf16 v[56:59], v[180:183], v[222:225], v[56:59]
	v_mfma_f32_16x16x32_bf16 v[102:105], v[152:155], v[192:195], v[102:105]
	v_mfma_f32_16x16x32_bf16 v[106:109], v[184:187], v[192:195], v[106:109]
	v_mfma_f32_16x16x32_bf16 v[110:113], v[152:155], v[206:209], v[110:113]
	v_mfma_f32_16x16x32_bf16 v[40:43], v[184:187], v[206:209], v[40:43]
	v_mfma_f32_16x16x32_bf16 v[44:47], v[152:155], v[218:221], v[44:47]
	v_mfma_f32_16x16x32_bf16 v[48:51], v[184:187], v[218:221], v[48:51]
	v_mfma_f32_16x16x32_bf16 v[52:55], v[152:155], v[226:229], v[52:55]
	v_mfma_f32_16x16x32_bf16 v[56:59], v[184:187], v[226:229], v[56:59]
	s_barrier
; #define PG8_STAGE(bufoff, gbase, voff) do { _Pragma("unroll") for (int _i = 0; _i < 2; ++_i) \
;         __builtin_amdgcn_global_load_lds((const unsigned*)((const char*)(gbase) + (voff)[_i]), (PG8_LAS unsigned*)(lds + (bufoff) + ldsw + _i * 8192), 16, 0, 0); } while (0)
; #define PG8_LDA(dst, b, h) do { _Pragma("unroll") for (int m = 0; m < 4; ++m) _Pragma("unroll") for (int k = 0; k < 2; ++k) dst[m][k] = *(const PG8_LAS bf16x8*)(lds + PG8_SA(b, h) + aoff + m * 2048 + k * 1024); } while (0)
; #define PG8_LDB(dst, b, h) do { _Pragma("unroll") for (int n = 0; n < 2; ++n) _Pragma("unroll") for (int k = 0; k < 2; ++k) dst[n][k] = *(const PG8_LAS bf16x8*)(lds + PG8_SB(b, h) + boff + n * 2048 + k * 1024); } while (0)
; #define PG8_MMA(ai, bj, At, Bt) do { __builtin_amdgcn_s_setprio(1); _Pragma("unroll") for (int m = 0; m < 4; ++m) _Pragma("unroll") for (int n = 0; n < 2; ++n) _Pragma("unroll") for (int k = 0; k < 2; ++k) \
;         acc[ai][bj][m][n] = __builtin_amdgcn_mfma_f32_16x16x32_bf16(Bt[n][k], At[m][k], acc[ai][bj][m][n], 0, 0, 0); __builtin_amdgcn_s_setprio(0); } while (0)
; #define PG8_WAIT_V(n) asm volatile("s_waitcnt vmcnt(" #n ")" ::: "memory")
; #define PG8_WAIT_L(n) asm volatile("s_waitcnt lgkmcnt(" #n ")" ::: "memory")
; #define PG8_BAR __builtin_amdgcn_s_barrier()
; #define PG8_SCHED __builtin_amdgcn_sched_barrier(0)
; template <class Epi, class Sched, bool ALIGN_EPI = false, bool SP2 = false>
; __device__ __forceinline__ void gemm_phase(PG8_LAS unsigned char* lds, const Gemm g, const Sched& S, const Epi& E, const int tid) {
;     ...
;             PG8_LDA(At, 0, 1); PG8_STAGE(PG8_SB(0, 0), b2, voffB); PG8_STAGE(PG8_SB(0, 1), b2 + hstep, voffB); PG8_STAGE(PG8_SA(0, 0), a2, voffA);
;             PG8_WAIT_V(8); PG8_WAIT_L(0); PG8_BAR; PG8_MMA(1, 0, At, B0); PG8_MMA(1, 1, At, B1); PG8_BAR; PG8_SCHED;
;             PG8_LDB(B0, 1, 0); PG8_LDB(B1, 1, 1); PG8_SCHED; PG8_LDA(At, 1, 0); PG8_STAGE(PG8_SA(0, 1), a2 + hstep, voffA);
;             PG8_WAIT_V(8); PG8_WAIT_L(0); PG8_BAR; PG8_MMA(0, 0, At, B0); PG8_MMA(0, 1, At, B1); PG8_BAR; PG8_SCHED;
	s_setprio 0
	s_mov_b64 s[56:57], 0x200
	s_mov_b32 m0, s47
	v_lshl_add_u64 v[138:139], v[0:1], 0, s[56:57]
	s_add_u32 s54, s16, 0x18200
	ds_read_b128 v[188:191], v142 offset:16384
	ds_read_b128 v[192:195], v142 offset:17408
	ds_read_b128 v[196:199], v142 offset:18432
	ds_read_b128 v[206:209], v142 offset:19456
	ds_read_b128 v[214:217], v142 offset:20480
	ds_read_b128 v[218:221], v142 offset:21504
	ds_read_b128 v[222:225], v142 offset:22528
	ds_read_b128 v[226:229], v142 offset:23552
	global_load_lds_dwordx4 v[138:139], off
	v_lshl_add_u64 v[138:139], v[2:3], 0, s[56:57]
	s_mov_b32 m0, s3
	s_addc_u32 s55, s17, 0
	global_load_lds_dwordx4 v[138:139], off
	s_mov_b32 m0, s45
	v_lshl_add_u64 v[138:139], s[54:55], 0, v[134:135]
	global_load_lds_dwordx4 v[138:139], off
	s_mov_b32 m0, s46
	v_lshl_add_u64 v[138:139], s[54:55], 0, v[130:131]
	global_load_lds_dwordx4 v[138:139], off
	s_mov_b32 m0, s23
	v_lshl_add_u64 v[138:139], v[4:5], 0, s[56:57]
	global_load_lds_dwordx4 v[138:139], off
	s_mov_b32 m0, s24
	v_lshl_add_u64 v[138:139], v[6:7], 0, s[56:57]
	global_load_lds_dwordx4 v[138:139], off
	s_waitcnt vmcnt(8) lgkmcnt(0)
	s_setprio 1
	s_barrier
	v_mfma_f32_16x16x32_bf16 v[12:15], v[118:121], v[222:225], v[12:15]
	v_mfma_f32_16x16x32_bf16 v[16:19], v[126:129], v[222:225], v[16:19]
	v_mfma_f32_16x16x32_bf16 v[156:159], v[118:121], v[188:191], v[156:159]
	v_mfma_f32_16x16x32_bf16 v[160:163], v[126:129], v[188:191], v[160:163]
	v_mfma_f32_16x16x32_bf16 v[164:167], v[118:121], v[196:199], v[164:167]
	v_mfma_f32_16x16x32_bf16 v[168:171], v[126:129], v[196:199], v[168:171]
	v_mfma_f32_16x16x32_bf16 v[172:175], v[118:121], v[214:217], v[172:175]
	v_mfma_f32_16x16x32_bf16 v[176:179], v[126:129], v[214:217], v[176:179]
	v_mfma_f32_16x16x32_bf16 v[12:15], v[122:125], v[226:229], v[12:15]
	v_mfma_f32_16x16x32_bf16 v[16:19], v[144:147], v[226:229], v[16:19]
	v_mfma_f32_16x16x32_bf16 v[156:159], v[122:125], v[192:195], v[156:159]
	v_mfma_f32_16x16x32_bf16 v[160:163], v[144:147], v[192:195], v[160:163]
	v_mfma_f32_16x16x32_bf16 v[164:167], v[122:125], v[206:209], v[164:167]
	v_mfma_f32_16x16x32_bf16 v[168:171], v[144:147], v[206:209], v[168:171]
	v_mfma_f32_16x16x32_bf16 v[172:175], v[122:125], v[218:221], v[172:175]
	v_mfma_f32_16x16x32_bf16 v[176:179], v[144:147], v[218:221], v[176:179]
	v_mfma_f32_16x16x32_bf16 v[20:23], v[148:151], v[188:191], v[20:23]
	v_mfma_f32_16x16x32_bf16 v[32:35], v[180:183], v[188:191], v[32:35]
	v_mfma_f32_16x16x32_bf16 v[36:39], v[148:151], v[196:199], v[36:39]
	v_mfma_f32_16x16x32_bf16 v[60:63], v[180:183], v[196:199], v[60:63]
	v_mfma_f32_16x16x32_bf16 v[66:69], v[148:151], v[214:217], v[66:69]
	v_mfma_f32_16x16x32_bf16 v[114:117], v[180:183], v[214:217], v[114:117]
	v_mfma_f32_16x16x32_bf16 v[24:27], v[148:151], v[222:225], v[24:27]
	v_mfma_f32_16x16x32_bf16 v[28:31], v[180:183], v[222:225], v[28:31]
	v_mfma_f32_16x16x32_bf16 v[20:23], v[152:155], v[192:195], v[20:23]
	v_mfma_f32_16x16x32_bf16 v[32:35], v[184:187], v[192:195], v[32:35]
	v_mfma_f32_16x16x32_bf16 v[36:39], v[152:155], v[206:209], v[36:39]
	v_mfma_f32_16x16x32_bf16 v[60:63], v[184:187], v[206:209], v[60:63]
	v_mfma_f32_16x16x32_bf16 v[66:69], v[152:155], v[218:221], v[66:69]
	v_mfma_f32_16x16x32_bf16 v[114:117], v[184:187], v[218:221], v[114:117]
	v_mfma_f32_16x16x32_bf16 v[24:27], v[152:155], v[226:229], v[24:27]
	v_mfma_f32_16x16x32_bf16 v[28:31], v[184:187], v[226:229], v[28:31]
	s_barrier
	s_setprio 0
	ds_read_b128 v[118:121], v10
	ds_read_b128 v[122:125], v10 offset:1024
	ds_read_b128 v[126:129], v10 offset:2048
	ds_read_b128 v[144:147], v10 offset:3072
	ds_read_b128 v[148:151], v11
	ds_read_b128 v[152:155], v11 offset:1024
	ds_read_b128 v[180:183], v11 offset:2048
	ds_read_b128 v[184:187], v11 offset:3072
	s_add_u32 s54, s14, 0x18200
	s_addc_u32 s55, s15, 0
	s_mov_b32 m0, s25
	v_lshl_add_u64 v[138:139], s[54:55], 0, v[136:137]
	ds_read_b128 v[188:191], v142 offset:32768
	ds_read_b128 v[192:195], v142 offset:33792
	ds_read_b128 v[196:199], v142 offset:34816
	ds_read_b128 v[206:209], v142 offset:35840
	ds_read_b128 v[214:217], v142 offset:36864
	ds_read_b128 v[218:221], v142 offset:37888
	ds_read_b128 v[222:225], v142 offset:38912
	ds_read_b128 v[226:229], v142 offset:39936
	global_load_lds_dwordx4 v[138:139], off
	s_mov_b32 m0, s26
	v_lshl_add_u64 v[138:139], s[54:55], 0, v[132:133]
	global_load_lds_dwordx4 v[138:139], off
	s_waitcnt vmcnt(8) lgkmcnt(0)
	s_setprio 1
	s_barrier
	v_mfma_f32_16x16x32_bf16 v[70:73], v[118:121], v[188:191], v[70:73]
	v_mfma_f32_16x16x32_bf16 v[74:77], v[126:129], v[188:191], v[74:77]
	v_mfma_f32_16x16x32_bf16 v[78:81], v[118:121], v[196:199], v[78:81]
	v_mfma_f32_16x16x32_bf16 v[82:85], v[126:129], v[196:199], v[82:85]
	v_mfma_f32_16x16x32_bf16 v[86:89], v[118:121], v[214:217], v[86:89]
	v_mfma_f32_16x16x32_bf16 v[90:93], v[126:129], v[214:217], v[90:93]
	v_mfma_f32_16x16x32_bf16 v[94:97], v[118:121], v[222:225], v[94:97]
	v_mfma_f32_16x16x32_bf16 v[98:101], v[126:129], v[222:225], v[98:101]
	v_mfma_f32_16x16x32_bf16 v[70:73], v[122:125], v[192:195], v[70:73]
	v_mfma_f32_16x16x32_bf16 v[74:77], v[144:147], v[192:195], v[74:77]
	v_mfma_f32_16x16x32_bf16 v[78:81], v[122:125], v[206:209], v[78:81]
	v_mfma_f32_16x16x32_bf16 v[82:85], v[144:147], v[206:209], v[82:85]
	v_mfma_f32_16x16x32_bf16 v[86:89], v[122:125], v[218:221], v[86:89]
	v_mfma_f32_16x16x32_bf16 v[90:93], v[144:147], v[218:221], v[90:93]
	v_mfma_f32_16x16x32_bf16 v[94:97], v[122:125], v[226:229], v[94:97]
	v_mfma_f32_16x16x32_bf16 v[98:101], v[144:147], v[226:229], v[98:101]
	v_mfma_f32_16x16x32_bf16 v[102:105], v[148:151], v[188:191], v[102:105]
	v_mfma_f32_16x16x32_bf16 v[106:109], v[180:183], v[188:191], v[106:109]
	v_mfma_f32_16x16x32_bf16 v[110:113], v[148:151], v[196:199], v[110:113]
	v_mfma_f32_16x16x32_bf16 v[40:43], v[180:183], v[196:199], v[40:43]
	v_mfma_f32_16x16x32_bf16 v[44:47], v[148:151], v[214:217], v[44:47]
	v_mfma_f32_16x16x32_bf16 v[48:51], v[180:183], v[214:217], v[48:51]
	v_mfma_f32_16x16x32_bf16 v[52:55], v[148:151], v[222:225], v[52:55]
	v_mfma_f32_16x16x32_bf16 v[56:59], v[180:183], v[222:225], v[56:59]
	v_mfma_f32_16x16x32_bf16 v[102:105], v[152:155], v[192:195], v[102:105]
	v_mfma_f32_16x16x32_bf16 v[106:109], v[184:187], v[192:195], v[106:109]
	v_mfma_f32_16x16x32_bf16 v[110:113], v[152:155], v[206:209], v[110:113]
	v_mfma_f32_16x16x32_bf16 v[40:43], v[184:187], v[206:209], v[40:43]
	v_mfma_f32_16x16x32_bf16 v[44:47], v[152:155], v[218:221], v[44:47]
	v_mfma_f32_16x16x32_bf16 v[48:51], v[184:187], v[218:221], v[48:51]
	v_mfma_f32_16x16x32_bf16 v[52:55], v[152:155], v[226:229], v[52:55]
	v_mfma_f32_16x16x32_bf16 v[56:59], v[184:187], v[226:229], v[56:59]
	s_barrier
; #define PG8_STAGE(bufoff, gbase, voff) do { _Pragma("unroll") for (int _i = 0; _i < 2; ++_i) \
;         __builtin_amdgcn_global_load_lds((const unsigned*)((const char*)(gbase) + (voff)[_i]), (PG8_LAS unsigned*)(lds + (bufoff) + ldsw + _i * 8192), 16, 0, 0); } while (0)
; #define PG8_LDA(dst, b, h) do { _Pragma("unroll") for (int m = 0; m < 4; ++m) _Pragma("unroll") for (int k = 0; k < 2; ++k) dst[m][k] = *(const PG8_LAS bf16x8*)(lds + PG8_SA(b, h) + aoff + m * 2048 + k * 1024); } while (0)
; #define PG8_LDB(dst, b, h) do { _Pragma("unroll") for (int n = 0; n < 2; ++n) _Pragma("unroll") for (int k = 0; k < 2; ++k) dst[n][k] = *(const PG8_LAS bf16x8*)(lds + PG8_SB(b, h) + boff + n * 2048 + k * 1024); } while (0)
; #define PG8_MMA(ai, bj, At, Bt) do { __builtin_amdgcn_s_setprio(1); _Pragma("unroll") for (int m = 0; m < 4; ++m) _Pragma("unroll") for (int n = 0; n < 2; ++n) _Pragma("unroll") for (int k = 0; k < 2; ++k) \
;         acc[ai][bj][m][n] = __builtin_amdgcn_mfma_f32_16x16x32_bf16(Bt[n][k], At[m][k], acc[ai][bj][m][n], 0, 0, 0); __builtin_amdgcn_s_setprio(0); } while (0)
; #define PG8_WAIT_V(n) asm volatile("s_waitcnt vmcnt(" #n ")" ::: "memory")
; #define PG8_WAIT_L(n) asm volatile("s_waitcnt lgkmcnt(" #n ")" ::: "memory")
; #define PG8_BAR __builtin_amdgcn_s_barrier()
; #define PG8_SCHED __builtin_amdgcn_sched_barrier(0)
; template <class Epi, class Sched, bool ALIGN_EPI = false, bool SP2 = false>
; __device__ __forceinline__ void gemm_phase(PG8_LAS unsigned char* lds, const Gemm g, const Sched& S, const Epi& E, const int tid) {
;     ...
;             PG8_LDB(B0, 0, 0); PG8_LDB(B1, 0, 1); PG8_SCHED; PG8_LDA(At, 0, 0); PG8_STAGE(PG8_SA(1, 1), a1 + hstep, voffA);
;             PG8_WAIT_V(8); PG8_WAIT_L(0); PG8_BAR; PG8_MMA(0, 0, At, B0); PG8_MMA(0, 1, At, B1); PG8_BAR; PG8_SCHED;
;     ...
;             PG8_LDA(At, 1, 1); PG8_STAGE(PG8_SB(1, 0), b3, voffB); PG8_STAGE(PG8_SB(1, 1), b3 + hstep, voffB); PG8_STAGE(PG8_SA(1, 0), a3, voffA);
;             PG8_WAIT_V(8); PG8_WAIT_L(0); PG8_BAR; PG8_MMA(1, 0, At, B0); PG8_MMA(1, 1, At, B1); PG8_BAR; PG8_SCHED;
	s_setprio 0
	s_mov_b64 s[54:55], 0x280
	s_mov_b32 m0, s52
	v_lshl_add_u64 v[0:1], v[0:1], 0, s[54:55]
	s_add_u32 s16, s16, 0x18280
	ds_read_b128 v[188:191], v142 offset:49152
	ds_read_b128 v[192:195], v142 offset:50176
	ds_read_b128 v[196:199], v142 offset:51200
	ds_read_b128 v[206:209], v142 offset:52224
	ds_read_b128 v[214:217], v142 offset:53248
	ds_read_b128 v[218:221], v142 offset:54272
	ds_read_b128 v[222:225], v142 offset:55296
	ds_read_b128 v[226:229], v142 offset:56320
	global_load_lds_dwordx4 v[0:1], off
	v_lshl_add_u64 v[0:1], v[2:3], 0, s[54:55]
	s_mov_b32 m0, s48
	s_addc_u32 s17, s17, 0
	global_load_lds_dwordx4 v[0:1], off
	s_mov_b32 m0, s49
	v_lshl_add_u64 v[0:1], s[16:17], 0, v[134:135]
	global_load_lds_dwordx4 v[0:1], off
	s_mov_b32 m0, s51
	v_lshl_add_u64 v[0:1], s[16:17], 0, v[130:131]
	global_load_lds_dwordx4 v[0:1], off
	s_mov_b32 m0, s28
	v_lshl_add_u64 v[0:1], v[4:5], 0, s[54:55]
	global_load_lds_dwordx4 v[0:1], off
	s_mov_b32 m0, s29
	v_lshl_add_u64 v[0:1], v[6:7], 0, s[54:55]
	global_load_lds_dwordx4 v[0:1], off
	s_waitcnt vmcnt(8) lgkmcnt(0)
	s_setprio 1
	s_barrier
	v_mfma_f32_16x16x32_bf16 v[0:3], v[118:121], v[188:191], v[156:159]
	v_mfma_f32_16x16x32_bf16 v[4:7], v[126:129], v[188:191], v[160:163]
	v_mfma_f32_16x16x32_bf16 v[12:15], v[118:121], v[222:225], v[12:15]
	v_mfma_f32_16x16x32_bf16 v[16:19], v[126:129], v[222:225], v[16:19]
	v_mfma_f32_16x16x32_bf16 v[0:3], v[122:125], v[192:195], v[0:3]
	v_mfma_f32_16x16x32_bf16 v[4:7], v[144:147], v[192:195], v[4:7]
	v_mfma_f32_16x16x32_bf16 v[156:159], v[118:121], v[196:199], v[164:167]
	v_mfma_f32_16x16x32_bf16 v[160:163], v[126:129], v[196:199], v[168:171]
	v_mfma_f32_16x16x32_bf16 v[164:167], v[118:121], v[214:217], v[172:175]
	v_mfma_f32_16x16x32_bf16 v[168:171], v[126:129], v[214:217], v[176:179]
	v_mfma_f32_16x16x32_bf16 v[12:15], v[122:125], v[226:229], v[12:15]
	v_mfma_f32_16x16x32_bf16 v[16:19], v[144:147], v[226:229], v[16:19]
	v_mfma_f32_16x16x32_bf16 v[156:159], v[122:125], v[206:209], v[156:159]
	v_mfma_f32_16x16x32_bf16 v[160:163], v[144:147], v[206:209], v[160:163]
	v_mfma_f32_16x16x32_bf16 v[164:167], v[122:125], v[218:221], v[164:167]
	v_mfma_f32_16x16x32_bf16 v[168:171], v[144:147], v[218:221], v[168:171]
	v_mfma_f32_16x16x32_bf16 v[20:23], v[148:151], v[188:191], v[20:23]
	v_mfma_f32_16x16x32_bf16 v[32:35], v[180:183], v[188:191], v[32:35]
	v_mfma_f32_16x16x32_bf16 v[36:39], v[148:151], v[196:199], v[36:39]
	v_mfma_f32_16x16x32_bf16 v[60:63], v[180:183], v[196:199], v[60:63]
	v_mfma_f32_16x16x32_bf16 v[66:69], v[148:151], v[214:217], v[66:69]
	v_mfma_f32_16x16x32_bf16 v[114:117], v[180:183], v[214:217], v[114:117]
	v_mfma_f32_16x16x32_bf16 v[24:27], v[148:151], v[222:225], v[24:27]
	v_mfma_f32_16x16x32_bf16 v[28:31], v[180:183], v[222:225], v[28:31]
	v_mfma_f32_16x16x32_bf16 v[20:23], v[152:155], v[192:195], v[20:23]
	v_mfma_f32_16x16x32_bf16 v[32:35], v[184:187], v[192:195], v[32:35]
	v_mfma_f32_16x16x32_bf16 v[36:39], v[152:155], v[206:209], v[36:39]
	v_mfma_f32_16x16x32_bf16 v[60:63], v[184:187], v[206:209], v[60:63]
	v_mfma_f32_16x16x32_bf16 v[66:69], v[152:155], v[218:221], v[66:69]
	v_mfma_f32_16x16x32_bf16 v[114:117], v[184:187], v[218:221], v[114:117]
	v_mfma_f32_16x16x32_bf16 v[24:27], v[152:155], v[226:229], v[24:27]
	v_mfma_f32_16x16x32_bf16 v[28:31], v[184:187], v[226:229], v[28:31]
	s_barrier
	s_setprio 0
	ds_read_b128 v[118:121], v8
	ds_read_b128 v[122:125], v8 offset:1024
	ds_read_b128 v[126:129], v8 offset:2048
	ds_read_b128 v[144:147], v8 offset:3072
	ds_read_b128 v[148:151], v9
	ds_read_b128 v[152:155], v9 offset:1024
	ds_read_b128 v[172:175], v9 offset:2048
	ds_read_b128 v[176:179], v9 offset:3072
	s_add_u32 s14, s14, 0x18280
	s_addc_u32 s15, s15, 0
	s_mov_b32 m0, s50
	v_lshl_add_u64 v[8:9], s[14:15], 0, v[136:137]
	ds_read_b128 v[180:183], v142
	ds_read_b128 v[184:187], v142 offset:1024
	ds_read_b128 v[188:191], v142 offset:2048
	ds_read_b128 v[192:195], v142 offset:3072
	ds_read_b128 v[196:199], v142 offset:4096
	ds_read_b128 v[206:209], v142 offset:5120
	ds_read_b128 v[214:217], v142 offset:6144
	ds_read_b128 v[218:221], v142 offset:7168
	global_load_lds_dwordx4 v[8:9], off
	s_mov_b32 m0, s2
	v_lshl_add_u64 v[8:9], s[14:15], 0, v[132:133]
	global_load_lds_dwordx4 v[8:9], off
	s_waitcnt vmcnt(8) lgkmcnt(0)
	s_setprio 1
	s_barrier
	v_mfma_f32_16x16x32_bf16 v[94:97], v[118:121], v[214:217], v[94:97]
	v_mfma_f32_16x16x32_bf16 v[70:73], v[118:121], v[180:183], v[70:73]
	v_mfma_f32_16x16x32_bf16 v[74:77], v[126:129], v[180:183], v[74:77]
	v_mfma_f32_16x16x32_bf16 v[78:81], v[118:121], v[188:191], v[78:81]
	v_mfma_f32_16x16x32_bf16 v[82:85], v[126:129], v[188:191], v[82:85]
	v_mfma_f32_16x16x32_bf16 v[86:89], v[118:121], v[196:199], v[86:89]
	v_mfma_f32_16x16x32_bf16 v[90:93], v[126:129], v[196:199], v[90:93]
	v_mfma_f32_16x16x32_bf16 v[222:225], v[122:125], v[218:221], v[94:97]
	v_mfma_f32_16x16x32_bf16 v[94:97], v[126:129], v[214:217], v[98:101]
	v_mfma_f32_16x16x32_bf16 v[70:73], v[122:125], v[184:187], v[70:73]
	v_mfma_f32_16x16x32_bf16 v[74:77], v[144:147], v[184:187], v[74:77]
	v_mfma_f32_16x16x32_bf16 v[78:81], v[122:125], v[192:195], v[78:81]
	v_mfma_f32_16x16x32_bf16 v[82:85], v[144:147], v[192:195], v[82:85]
	v_mfma_f32_16x16x32_bf16 v[86:89], v[122:125], v[206:209], v[86:89]
	v_mfma_f32_16x16x32_bf16 v[90:93], v[144:147], v[206:209], v[90:93]
	v_mfma_f32_16x16x32_bf16 v[98:101], v[144:147], v[218:221], v[94:97]
	v_mfma_f32_16x16x32_bf16 v[94:97], v[148:151], v[180:183], v[102:105]
	v_mfma_f32_16x16x32_bf16 v[102:105], v[152:155], v[184:187], v[94:97]
	v_mfma_f32_16x16x32_bf16 v[94:97], v[172:175], v[180:183], v[106:109]
	v_mfma_f32_16x16x32_bf16 v[40:43], v[172:175], v[188:191], v[40:43]
	v_mfma_f32_16x16x32_bf16 v[44:47], v[148:151], v[196:199], v[44:47]
	v_mfma_f32_16x16x32_bf16 v[48:51], v[172:175], v[196:199], v[48:51]
	v_mfma_f32_16x16x32_bf16 v[52:55], v[148:151], v[214:217], v[52:55]
	v_mfma_f32_16x16x32_bf16 v[56:59], v[172:175], v[214:217], v[56:59]
	v_mfma_f32_16x16x32_bf16 v[180:183], v[176:179], v[184:187], v[94:97]
	v_mfma_f32_16x16x32_bf16 v[94:97], v[148:151], v[188:191], v[110:113]
	v_mfma_f32_16x16x32_bf16 v[40:43], v[176:179], v[192:195], v[40:43]
	v_mfma_f32_16x16x32_bf16 v[44:47], v[152:155], v[206:209], v[44:47]
	v_mfma_f32_16x16x32_bf16 v[48:51], v[176:179], v[206:209], v[48:51]
	v_mfma_f32_16x16x32_bf16 v[52:55], v[152:155], v[218:221], v[52:55]
	v_mfma_f32_16x16x32_bf16 v[56:59], v[176:179], v[218:221], v[56:59]
	v_mfma_f32_16x16x32_bf16 v[184:187], v[152:155], v[192:195], v[94:97]
	s_barrier
; #define PG8_STAGE(bufoff, gbase, voff) do { _Pragma("unroll") for (int _i = 0; _i < 2; ++_i) \
;         __builtin_amdgcn_global_load_lds((const unsigned*)((const char*)(gbase) + (voff)[_i]), (PG8_LAS unsigned*)(lds + (bufoff) + ldsw + _i * 8192), 16, 0, 0); } while (0)
; #define PG8_LDA(dst, b, h) do { _Pragma("unroll") for (int m = 0; m < 4; ++m) _Pragma("unroll") for (int k = 0; k < 2; ++k) dst[m][k] = *(const PG8_LAS bf16x8*)(lds + PG8_SA(b, h) + aoff + m * 2048 + k * 1024); } while (0)
; #define PG8_LDB(dst, b, h) do { _Pragma("unroll") for (int n = 0; n < 2; ++n) _Pragma("unroll") for (int k = 0; k < 2; ++k) dst[n][k] = *(const PG8_LAS bf16x8*)(lds + PG8_SB(b, h) + boff + n * 2048 + k * 1024); } while (0)
; #define PG8_MMA(ai, bj, At, Bt) do { __builtin_amdgcn_s_setprio(1); _Pragma("unroll") for (int m = 0; m < 4; ++m) _Pragma("unroll") for (int n = 0; n < 2; ++n) _Pragma("unroll") for (int k = 0; k < 2; ++k) \
;         acc[ai][bj][m][n] = __builtin_amdgcn_mfma_f32_16x16x32_bf16(Bt[n][k], At[m][k], acc[ai][bj][m][n], 0, 0, 0); __builtin_amdgcn_s_setprio(0); } while (0)
; #define PG8_WAIT_V(n) asm volatile("s_waitcnt vmcnt(" #n ")" ::: "memory")
; #define PG8_WAIT_L(n) asm volatile("s_waitcnt lgkmcnt(" #n ")" ::: "memory")
; #define PG8_BAR __builtin_amdgcn_s_barrier()
; #define PG8_SCHED __builtin_amdgcn_sched_barrier(0)
; template <class Epi, class Sched, bool ALIGN_EPI = false, bool SP2 = false>
; __device__ __forceinline__ void gemm_phase(PG8_LAS unsigned char* lds, const Gemm g, const Sched& S, const Epi& E, const int tid) {
;     ...
;             PG8_LDA(At, 0, 1); PG8_STAGE(PG8_SB(0, 0), b2, voffB); PG8_STAGE(PG8_SB(0, 1), b2 + hstep, voffB); PG8_STAGE(PG8_SA(0, 0), a2, voffA);
;             PG8_WAIT_V(8); PG8_WAIT_L(0); PG8_BAR; PG8_MMA(1, 0, At, B0); PG8_MMA(1, 1, At, B1); PG8_BAR; PG8_SCHED;
;             PG8_LDB(B0, 1, 0); PG8_LDB(B1, 1, 1); PG8_SCHED; PG8_LDA(At, 1, 0); PG8_STAGE(PG8_SA(0, 1), a2 + hstep, voffA);
;             PG8_WAIT_V(8); PG8_WAIT_L(0); PG8_BAR; PG8_MMA(0, 0, At, B0); PG8_MMA(0, 1, At, B1); PG8_BAR; PG8_SCHED;
	s_setprio 0
	s_mov_b32 m0, s47
	v_lshl_add_u64 v[138:139], s[12:13], 0, v[134:135]
	s_add_u32 s2, s12, 0x18000
	ds_read_b128 v[94:97], v142 offset:16384
	ds_read_b128 v[106:109], v142 offset:17408
	ds_read_b128 v[110:113], v142 offset:18432
	ds_read_b128 v[188:191], v142 offset:19456
	ds_read_b128 v[192:195], v142 offset:20480
	ds_read_b128 v[196:199], v142 offset:21504
	ds_read_b128 v[206:209], v142 offset:22528
	ds_read_b128 v[214:217], v142 offset:23552
	global_load_lds_dwordx4 v[138:139], off
	v_lshl_add_u64 v[252:253], s[12:13], 0, v[130:131]
	s_mov_b32 m0, s3
	s_addc_u32 s3, s13, 0
	global_load_lds_dwordx4 v[252:253], off
	v_lshl_add_u64 v[8:9], s[2:3], 0, v[134:135]
	s_mov_b32 m0, s45
	v_lshl_add_u64 v[246:247], s[10:11], 0, v[136:137]
	global_load_lds_dwordx4 v[8:9], off
	v_lshl_add_u64 v[8:9], s[2:3], 0, v[130:131]
	s_mov_b32 m0, s46
	v_lshl_add_u64 v[210:211], s[10:11], 0, v[132:133]
	global_load_lds_dwordx4 v[8:9], off
	s_mov_b32 m0, s23
	s_nop 0
	global_load_lds_dwordx4 v[246:247], off
	s_mov_b32 m0, s24
	s_nop 0
	global_load_lds_dwordx4 v[210:211], off
	s_waitcnt vmcnt(8) lgkmcnt(0)
	s_setprio 1
	s_barrier
	v_mfma_f32_16x16x32_bf16 v[0:3], v[118:121], v[94:97], v[0:3]
	v_mfma_f32_16x16x32_bf16 v[4:7], v[126:129], v[94:97], v[4:7]
	v_mfma_f32_16x16x32_bf16 v[12:15], v[118:121], v[206:209], v[12:15]
	v_mfma_f32_16x16x32_bf16 v[16:19], v[126:129], v[206:209], v[16:19]
	v_mfma_f32_16x16x32_bf16 v[0:3], v[122:125], v[106:109], v[0:3]
	v_mfma_f32_16x16x32_bf16 v[4:7], v[144:147], v[106:109], v[4:7]
	v_mfma_f32_16x16x32_bf16 v[156:159], v[118:121], v[110:113], v[156:159]
	v_mfma_f32_16x16x32_bf16 v[160:163], v[126:129], v[110:113], v[160:163]
	v_mfma_f32_16x16x32_bf16 v[164:167], v[118:121], v[192:195], v[164:167]
	v_mfma_f32_16x16x32_bf16 v[168:171], v[126:129], v[192:195], v[168:171]
	v_mfma_f32_16x16x32_bf16 v[12:15], v[122:125], v[214:217], v[12:15]
	v_mfma_f32_16x16x32_bf16 v[16:19], v[144:147], v[214:217], v[16:19]
	v_mfma_f32_16x16x32_bf16 v[156:159], v[122:125], v[188:191], v[156:159]
	v_mfma_f32_16x16x32_bf16 v[160:163], v[144:147], v[188:191], v[160:163]
	v_mfma_f32_16x16x32_bf16 v[164:167], v[122:125], v[196:199], v[164:167]
	v_mfma_f32_16x16x32_bf16 v[168:171], v[144:147], v[196:199], v[168:171]
	v_mfma_f32_16x16x32_bf16 v[60:63], v[172:175], v[110:113], v[60:63]
	v_mfma_f32_16x16x32_bf16 v[20:23], v[148:151], v[94:97], v[20:23]
	v_mfma_f32_16x16x32_bf16 v[32:35], v[172:175], v[94:97], v[32:35]
	v_mfma_f32_16x16x32_bf16 v[36:39], v[148:151], v[110:113], v[36:39]
	v_mfma_f32_16x16x32_bf16 v[144:147], v[176:179], v[188:191], v[60:63]
	v_mfma_f32_16x16x32_bf16 v[60:63], v[148:151], v[192:195], v[66:69]
	v_mfma_f32_16x16x32_bf16 v[24:27], v[148:151], v[206:209], v[24:27]
	v_mfma_f32_16x16x32_bf16 v[20:23], v[152:155], v[106:109], v[20:23]
	v_mfma_f32_16x16x32_bf16 v[32:35], v[176:179], v[106:109], v[32:35]
	v_mfma_f32_16x16x32_bf16 v[36:39], v[152:155], v[188:191], v[36:39]
	v_mfma_f32_16x16x32_bf16 v[188:191], v[152:155], v[196:199], v[60:63]
	v_mfma_f32_16x16x32_bf16 v[60:63], v[172:175], v[192:195], v[114:117]
	v_mfma_f32_16x16x32_bf16 v[148:151], v[152:155], v[214:217], v[24:27]
	v_mfma_f32_16x16x32_bf16 v[24:27], v[172:175], v[206:209], v[28:31]
	v_mfma_f32_16x16x32_bf16 v[192:195], v[176:179], v[196:199], v[60:63]
	v_mfma_f32_16x16x32_bf16 v[152:155], v[176:179], v[214:217], v[24:27]
	s_barrier
	s_setprio 0
	ds_read_b128 v[172:175], v10
	ds_read_b128 v[176:179], v10 offset:1024
	ds_read_b128 v[196:199], v10 offset:2048
	ds_read_b128 v[206:209], v10 offset:3072
	ds_read_b128 v[214:217], v11
	ds_read_b128 v[218:221], v11 offset:1024
	ds_read_b128 v[226:229], v11 offset:2048
	ds_read_b128 v[248:251], v11 offset:3072
	s_add_u32 s2, s10, 0x18000
	s_addc_u32 s3, s11, 0
	s_mov_b32 m0, s25
	v_lshl_add_u64 v[94:95], s[2:3], 0, v[136:137]
	ds_read_b128 v[8:11], v142 offset:32768
	ds_read_b128 v[24:27], v142 offset:33792
	ds_read_b128 v[28:31], v142 offset:34816
	ds_read_b128 v[60:63], v142 offset:35840
	ds_read_b128 v[66:69], v142 offset:36864
	ds_read_b128 v[234:237], v142 offset:37888
	ds_read_b128 v[238:241], v142 offset:38912
	ds_read_b128 v[230:233], v142 offset:39936
	global_load_lds_dwordx4 v[94:95], off
	s_mov_b32 m0, s26
	v_lshl_add_u64 v[94:95], s[2:3], 0, v[132:133]
	global_load_lds_dwordx4 v[94:95], off
	s_waitcnt vmcnt(8) lgkmcnt(0)
	s_setprio 1
	s_barrier
; #define PG8_STAGE(bufoff, gbase, voff) do { _Pragma("unroll") for (int _i = 0; _i < 2; ++_i) \
;         __builtin_amdgcn_global_load_lds((const unsigned*)((const char*)(gbase) + (voff)[_i]), (PG8_LAS unsigned*)(lds + (bufoff) + ldsw + _i * 8192), 16, 0, 0); } while (0)
; #define PG8_LDA(dst, b, h) do { _Pragma("unroll") for (int m = 0; m < 4; ++m) _Pragma("unroll") for (int k = 0; k < 2; ++k) dst[m][k] = *(const PG8_LAS bf16x8*)(lds + PG8_SA(b, h) + aoff + m * 2048 + k * 1024); } while (0)
; #define PG8_MMA(ai, bj, At, Bt) do { __builtin_amdgcn_s_setprio(1); _Pragma("unroll") for (int m = 0; m < 4; ++m) _Pragma("unroll") for (int n = 0; n < 2; ++n) _Pragma("unroll") for (int k = 0; k < 2; ++k) \
;         acc[ai][bj][m][n] = __builtin_amdgcn_mfma_f32_16x16x32_bf16(Bt[n][k], At[m][k], acc[ai][bj][m][n], 0, 0, 0); __builtin_amdgcn_s_setprio(0); } while (0)
; #define PG8_WAIT_V(n) asm volatile("s_waitcnt vmcnt(" #n ")" ::: "memory")
; #define PG8_WAIT_L(n) asm volatile("s_waitcnt lgkmcnt(" #n ")" ::: "memory")
; #define PG8_BAR __builtin_amdgcn_s_barrier()
; #define PG8_SCHED __builtin_amdgcn_sched_barrier(0)
; template <class Epi, class Sched, bool ALIGN_EPI = false, bool SP2 = false>
; __device__ __forceinline__ void gemm_phase(PG8_LAS unsigned char* lds, const Gemm g, const Sched& S, const Epi& E, const int tid) {
;     ...
;             PG8_WAIT_V(8); PG8_WAIT_L(0); PG8_BAR; PG8_MMA(0, 0, At, B0); PG8_MMA(0, 1, At, B1); PG8_BAR; PG8_SCHED;
;             PG8_LDA(At, 1, 1); PG8_STAGE(PG8_SB(1, 0), b3, voffB); PG8_STAGE(PG8_SB(1, 1), b3 + hstep, voffB); PG8_STAGE(PG8_SA(1, 0), a3, voffA);
;             PG8_WAIT_V(8); PG8_WAIT_L(0); PG8_BAR; PG8_MMA(1, 0, At, B0); PG8_MMA(1, 1, At, B1); PG8_BAR; PG8_SCHED;
;     ...
;         if constexpr (ALIGN_EPI) { if (wr == 0) PG8_BAR; }
	v_mfma_f32_16x16x32_bf16 v[70:73], v[172:175], v[8:11], v[70:73]
	v_mfma_f32_16x16x32_bf16 v[126:129], v[176:179], v[24:27], v[70:73]
	v_mfma_f32_16x16x32_bf16 v[70:73], v[196:199], v[8:11], v[74:77]
	v_mfma_f32_16x16x32_bf16 v[122:125], v[206:209], v[24:27], v[70:73]
	v_mfma_f32_16x16x32_bf16 v[70:73], v[172:175], v[28:31], v[78:81]
	v_mfma_f32_16x16x32_bf16 v[110:113], v[176:179], v[60:63], v[70:73]
	v_mfma_f32_16x16x32_bf16 v[70:73], v[196:199], v[28:31], v[82:85]
	v_mfma_f32_16x16x32_bf16 v[106:109], v[206:209], v[60:63], v[70:73]
	v_mfma_f32_16x16x32_bf16 v[70:73], v[172:175], v[66:69], v[86:89]
	v_mfma_f32_16x16x32_bf16 v[94:97], v[176:179], v[234:237], v[70:73]
	v_mfma_f32_16x16x32_bf16 v[70:73], v[196:199], v[66:69], v[90:93]
	v_mfma_f32_16x16x32_bf16 v[90:93], v[206:209], v[234:237], v[70:73]
	v_mfma_f32_16x16x32_bf16 v[70:73], v[172:175], v[238:241], v[222:225]
	v_mfma_f32_16x16x32_bf16 v[78:81], v[176:179], v[230:233], v[70:73]
	v_mfma_f32_16x16x32_bf16 v[70:73], v[196:199], v[238:241], v[98:101]
	v_mfma_f32_16x16x32_bf16 v[74:77], v[206:209], v[230:233], v[70:73]
	v_mfma_f32_16x16x32_bf16 v[70:73], v[214:217], v[8:11], v[102:105]
	v_mfma_f32_16x16x32_bf16 v[8:11], v[226:229], v[8:11], v[180:183]
	v_mfma_f32_16x16x32_bf16 v[118:121], v[248:251], v[24:27], v[8:11]
	v_mfma_f32_16x16x32_bf16 v[8:11], v[214:217], v[28:31], v[184:187]
	v_mfma_f32_16x16x32_bf16 v[98:101], v[218:221], v[60:63], v[8:11]
	v_mfma_f32_16x16x32_bf16 v[8:11], v[226:229], v[28:31], v[40:43]
	v_mfma_f32_16x16x32_bf16 v[102:105], v[248:251], v[60:63], v[8:11]
	v_mfma_f32_16x16x32_bf16 v[8:11], v[214:217], v[66:69], v[44:47]
	v_mfma_f32_16x16x32_bf16 v[82:85], v[218:221], v[234:237], v[8:11]
	v_mfma_f32_16x16x32_bf16 v[8:11], v[226:229], v[66:69], v[48:51]
	v_mfma_f32_16x16x32_bf16 v[86:89], v[248:251], v[234:237], v[8:11]
	v_mfma_f32_16x16x32_bf16 v[8:11], v[214:217], v[238:241], v[52:55]
	v_mfma_f32_16x16x32_bf16 v[66:69], v[218:221], v[230:233], v[8:11]
	v_mfma_f32_16x16x32_bf16 v[8:11], v[226:229], v[238:241], v[56:59]
	v_mfma_f32_16x16x32_bf16 v[114:117], v[218:221], v[24:27], v[70:73]
	v_mfma_f32_16x16x32_bf16 v[70:73], v[248:251], v[230:233], v[8:11]
	s_barrier
	s_setprio 0
	s_mov_b32 m0, s52
	s_nop 2
	v_lshl_add_u64 v[8:9], v[138:139], 0, s[94:95]
	s_add_u32 s2, s12, 0x18080
	ds_read_b128 v[52:55], v142 offset:49152
	ds_read_b128 v[180:183], v142 offset:50176
	ds_read_b128 v[184:187], v142 offset:51200
	ds_read_b128 v[222:225], v142 offset:52224
	ds_read_b128 v[230:233], v142 offset:53248
	ds_read_b128 v[234:237], v142 offset:54272
	ds_read_b128 v[238:241], v142 offset:55296
	ds_read_b128 v[200:203], v142 offset:56320
	global_load_lds_dwordx4 v[8:9], off
	v_lshl_add_u64 v[8:9], v[252:253], 0, s[94:95]
	s_mov_b32 m0, s48
	s_addc_u32 s3, s13, 0
	global_load_lds_dwordx4 v[8:9], off
	s_mov_b32 m0, s49
	v_lshl_add_u64 v[8:9], s[2:3], 0, v[134:135]
	global_load_lds_dwordx4 v[8:9], off
	s_mov_b32 m0, s51
	v_lshl_add_u64 v[8:9], s[2:3], 0, v[130:131]
	global_load_lds_dwordx4 v[8:9], off
	s_mov_b32 m0, s28
	v_lshl_add_u64 v[8:9], v[246:247], 0, s[94:95]
	global_load_lds_dwordx4 v[8:9], off
	s_mov_b32 m0, s29
	v_lshl_add_u64 v[8:9], v[210:211], 0, s[94:95]
	global_load_lds_dwordx4 v[8:9], off
	s_waitcnt vmcnt(8) lgkmcnt(0)
	s_setprio 1
	s_barrier
	v_mfma_f32_16x16x32_bf16 v[0:3], v[172:175], v[52:55], v[0:3]
	v_mfma_f32_16x16x32_bf16 v[60:63], v[176:179], v[180:183], v[0:3]
	v_mfma_f32_16x16x32_bf16 v[0:3], v[196:199], v[52:55], v[4:7]
	v_mfma_f32_16x16x32_bf16 v[56:59], v[206:209], v[180:183], v[0:3]
	v_mfma_f32_16x16x32_bf16 v[0:3], v[172:175], v[184:187], v[156:159]
	v_mfma_f32_16x16x32_bf16 v[44:47], v[176:179], v[222:225], v[0:3]
	v_mfma_f32_16x16x32_bf16 v[0:3], v[196:199], v[184:187], v[160:163]
	v_mfma_f32_16x16x32_bf16 v[40:43], v[206:209], v[222:225], v[0:3]
	v_mfma_f32_16x16x32_bf16 v[0:3], v[172:175], v[230:233], v[164:167]
	v_mfma_f32_16x16x32_bf16 v[28:31], v[176:179], v[234:237], v[0:3]
	v_mfma_f32_16x16x32_bf16 v[0:3], v[196:199], v[230:233], v[168:171]
	v_mfma_f32_16x16x32_bf16 v[24:27], v[206:209], v[234:237], v[0:3]
	v_mfma_f32_16x16x32_bf16 v[0:3], v[172:175], v[238:241], v[12:15]
	v_mfma_f32_16x16x32_bf16 v[8:11], v[176:179], v[200:203], v[0:3]
	v_mfma_f32_16x16x32_bf16 v[0:3], v[196:199], v[238:241], v[16:19]
	v_mfma_f32_16x16x32_bf16 v[12:15], v[206:209], v[200:203], v[0:3]
	v_mfma_f32_16x16x32_bf16 v[0:3], v[214:217], v[52:55], v[20:23]
	v_mfma_f32_16x16x32_bf16 v[48:51], v[218:221], v[180:183], v[0:3]
	v_mfma_f32_16x16x32_bf16 v[0:3], v[226:229], v[52:55], v[32:35]
	v_mfma_f32_16x16x32_bf16 v[52:55], v[248:251], v[180:183], v[0:3]
	v_mfma_f32_16x16x32_bf16 v[0:3], v[214:217], v[184:187], v[36:39]
	v_mfma_f32_16x16x32_bf16 v[32:35], v[218:221], v[222:225], v[0:3]
	v_mfma_f32_16x16x32_bf16 v[0:3], v[226:229], v[184:187], v[144:147]
	v_mfma_f32_16x16x32_bf16 v[36:39], v[248:251], v[222:225], v[0:3]
	v_mfma_f32_16x16x32_bf16 v[0:3], v[214:217], v[230:233], v[188:191]
	v_mfma_f32_16x16x32_bf16 v[16:19], v[218:221], v[234:237], v[0:3]
	v_mfma_f32_16x16x32_bf16 v[0:3], v[226:229], v[230:233], v[192:195]
	v_mfma_f32_16x16x32_bf16 v[20:23], v[248:251], v[234:237], v[0:3]
	v_mfma_f32_16x16x32_bf16 v[0:3], v[214:217], v[238:241], v[148:151]
	v_mfma_f32_16x16x32_bf16 v[4:7], v[226:229], v[238:241], v[152:155]
	v_mfma_f32_16x16x32_bf16 v[0:3], v[218:221], v[200:203], v[0:3]
	v_mfma_f32_16x16x32_bf16 v[4:7], v[248:251], v[200:203], v[4:7]
	s_barrier
	s_setprio 0
	s_andn2_b64 vcc, exec, s[8:9]
	s_cbranch_vccnz .LBB0_350
	s_barrier

; #define PG8_STAGE(bufoff, gbase, voff) do { _Pragma("unroll") for (int _i = 0; _i < 2; ++_i) \
;         __builtin_amdgcn_global_load_lds((const unsigned*)((const char*)(gbase) + (voff)[_i]), (PG8_LAS unsigned*)(lds + (bufoff) + ldsw + _i * 8192), 16, 0, 0); } while (0)
; #define PG8_LDA(dst, b, h) do { _Pragma("unroll") for (int m = 0; m < 4; ++m) _Pragma("unroll") for (int k = 0; k < 2; ++k) dst[m][k] = *(const PG8_LAS bf16x8*)(lds + PG8_SA(b, h) + aoff + m * 2048 + k * 1024); } while (0)
; #define PG8_LDB(dst, b, h) do { _Pragma("unroll") for (int n = 0; n < 2; ++n) _Pragma("unroll") for (int k = 0; k < 2; ++k) dst[n][k] = *(const PG8_LAS bf16x8*)(lds + PG8_SB(b, h) + boff + n * 2048 + k * 1024); } while (0)
; #define PG8_MMA(ai, bj, At, Bt) do { __builtin_amdgcn_s_setprio(1); _Pragma("unroll") for (int m = 0; m < 4; ++m) _Pragma("unroll") for (int n = 0; n < 2; ++n) _Pragma("unroll") for (int k = 0; k < 2; ++k) \
;         acc[ai][bj][m][n] = __builtin_amdgcn_mfma_f32_16x16x32_bf16(Bt[n][k], At[m][k], acc[ai][bj][m][n], 0, 0, 0); __builtin_amdgcn_s_setprio(0); } while (0)
; #define PG8_WAIT_V(n) asm volatile("s_waitcnt vmcnt(" #n ")" ::: "memory")
; #define PG8_BAR __builtin_amdgcn_s_barrier()
; template <class Epi, class Sched, bool ALIGN_EPI = false, bool SP2 = false>
; __device__ __forceinline__ void gemm_phase(PG8_LAS unsigned char* lds, const Gemm g, const Sched& S, const Epi& E, const int tid) {
;     ...
;         for (int t = 0; t < nt; t += 2) {
;             const bool last = (t == nt - 2);
;             const char* a1 = cA + (size_t)(t + 1) * kstep;
;             const char* a2 = last ? nA : cA + (size_t)(t + 2) * kstep; const char* b2 = last ? nB : cB + (size_t)(t + 2) * kstep;
;             const char* a3 = a2 + kstep; const char* b3 = b2 + kstep;
;             if (last && has_next) S.a_ready(nxt);
;             if constexpr (SP2) {
;             PG8_LDB(B0, 0, 0); PG8_LDB(B1, 0, 1); PG8_SCHED; PG8_LDA(At, 0, 0); PG8_STAGE(PG8_SA(1, 1), a1 + hstep, voffA);
;             PG8_WAIT_V(8); PG8_WAIT_L(0); PG8_BAR; PG8_MMA(0, 0, At, B0); PG8_MMA(0, 1, At, B1); PG8_BAR; PG8_SCHED;
;             PG8_LDA(At, 0, 1); PG8_STAGE(PG8_SB(0, 0), b2, voffB); PG8_STAGE(PG8_SB(0, 1), b2 + hstep, voffB); PG8_STAGE(PG8_SA(0, 0), a2, voffA);
;             PG8_WAIT_V(8); PG8_WAIT_L(0); PG8_BAR; PG8_MMA(1, 0, At, B0); PG8_MMA(1, 1, At, B1); PG8_BAR; PG8_SCHED;
.LBB0_511:
	s_add_u32 s6, s24, s4
	s_addc_u32 s7, s25, s5
	s_add_u32 s6, s6, 0x2c00100
	s_addc_u32 s7, s7, 0
	s_add_u32 s27, s22, s4
	s_addc_u32 s28, s23, s5
	s_add_i32 s29, 0, 0x10000
	s_cmpk_eq_i32 s4, 0x700
	s_cselect_b32 s9, s3, s7
	s_cselect_b32 s8, s2, s6
	v_add_u32_e32 v149, s29, v142
	s_cselect_b32 s7, s1, s28
	s_cselect_b32 s6, s0, s27
	s_add_i32 s27, 0, 0x14000
	ds_read_b128 v[144:147], v149
	ds_read_b128 v[150:153], v149 offset:1024
	ds_read_b128 v[154:157], v149 offset:2048
	ds_read_b128 v[158:161], v149 offset:3072
	v_add_u32_e32 v149, s27, v142
	ds_read_b128 v[162:165], v149
	ds_read_b128 v[166:169], v149 offset:1024
	ds_read_b128 v[170:173], v149 offset:2048
	ds_read_b128 v[174:177], v149 offset:3072
	v_lshl_add_u64 v[202:203], v[138:139], 0, s[4:5]
	s_add_i32 m0, s13, 0xc000
	ds_read_b128 v[178:181], v143
	ds_read_b128 v[182:185], v143 offset:1024
	ds_read_b128 v[186:189], v143 offset:2048
	ds_read_b128 v[190:193], v143 offset:3072
	ds_read_b128 v[194:197], v143 offset:4096
	ds_read_b128 v[198:201], v143 offset:5120
	ds_read_b128 v[214:217], v143 offset:6144
	ds_read_b128 v[218:221], v143 offset:7168
	global_load_lds_dwordx4 v[202:203], off
	s_add_i32 m0, s13, 0xe000
	v_lshl_add_u64 v[202:203], v[136:137], 0, s[4:5]
	global_load_lds_dwordx4 v[202:203], off
	s_waitcnt vmcnt(8) lgkmcnt(0)
	s_setprio 1
	s_barrier
	v_mfma_f32_16x16x32_bf16 v[126:129], v[144:147], v[178:181], v[126:129]
	v_mfma_f32_16x16x32_bf16 v[122:125], v[154:157], v[178:181], v[122:125]
	v_mfma_f32_16x16x32_bf16 v[118:121], v[144:147], v[186:189], v[118:121]
	v_mfma_f32_16x16x32_bf16 v[114:117], v[154:157], v[186:189], v[114:117]
	v_mfma_f32_16x16x32_bf16 v[110:113], v[144:147], v[194:197], v[110:113]
	v_mfma_f32_16x16x32_bf16 v[106:109], v[154:157], v[194:197], v[106:109]
	v_mfma_f32_16x16x32_bf16 v[102:105], v[144:147], v[214:217], v[102:105]
	v_mfma_f32_16x16x32_bf16 v[98:101], v[154:157], v[214:217], v[98:101]
	v_mfma_f32_16x16x32_bf16 v[126:129], v[150:153], v[182:185], v[126:129]
	v_mfma_f32_16x16x32_bf16 v[122:125], v[158:161], v[182:185], v[122:125]
	v_mfma_f32_16x16x32_bf16 v[118:121], v[150:153], v[190:193], v[118:121]
	v_mfma_f32_16x16x32_bf16 v[114:117], v[158:161], v[190:193], v[114:117]
	v_mfma_f32_16x16x32_bf16 v[110:113], v[150:153], v[198:201], v[110:113]
	v_mfma_f32_16x16x32_bf16 v[106:109], v[158:161], v[198:201], v[106:109]
	v_mfma_f32_16x16x32_bf16 v[102:105], v[150:153], v[218:221], v[102:105]
	v_mfma_f32_16x16x32_bf16 v[98:101], v[158:161], v[218:221], v[98:101]
	v_mfma_f32_16x16x32_bf16 v[60:63], v[162:165], v[178:181], v[60:63]
	v_mfma_f32_16x16x32_bf16 v[56:59], v[170:173], v[178:181], v[56:59]
	v_mfma_f32_16x16x32_bf16 v[52:55], v[162:165], v[186:189], v[52:55]
	v_mfma_f32_16x16x32_bf16 v[48:51], v[170:173], v[186:189], v[48:51]
	v_mfma_f32_16x16x32_bf16 v[44:47], v[162:165], v[194:197], v[44:47]
	v_mfma_f32_16x16x32_bf16 v[40:43], v[170:173], v[194:197], v[40:43]
	v_mfma_f32_16x16x32_bf16 v[36:39], v[162:165], v[214:217], v[36:39]
	v_mfma_f32_16x16x32_bf16 v[32:35], v[170:173], v[214:217], v[32:35]
	v_mfma_f32_16x16x32_bf16 v[60:63], v[166:169], v[182:185], v[60:63]
	v_mfma_f32_16x16x32_bf16 v[56:59], v[174:177], v[182:185], v[56:59]
	v_mfma_f32_16x16x32_bf16 v[52:55], v[166:169], v[190:193], v[52:55]
	v_mfma_f32_16x16x32_bf16 v[48:51], v[174:177], v[190:193], v[48:51]
	v_mfma_f32_16x16x32_bf16 v[44:47], v[166:169], v[198:201], v[44:47]
	v_mfma_f32_16x16x32_bf16 v[40:43], v[174:177], v[198:201], v[40:43]
	v_mfma_f32_16x16x32_bf16 v[36:39], v[166:169], v[218:221], v[36:39]
	v_mfma_f32_16x16x32_bf16 v[32:35], v[174:177], v[218:221], v[32:35]
	s_barrier
	s_setprio 0
	s_add_i32 s28, s29, s12
	v_lshl_add_u64 v[202:203], s[6:7], 0, v[64:65]
	s_mov_b32 m0, s28
	ds_read_b128 v[178:181], v143 offset:16384
	ds_read_b128 v[182:185], v143 offset:17408
	ds_read_b128 v[186:189], v143 offset:18432
	ds_read_b128 v[190:193], v143 offset:19456
	ds_read_b128 v[194:197], v143 offset:20480
	ds_read_b128 v[198:201], v143 offset:21504
	ds_read_b128 v[214:217], v143 offset:22528
	ds_read_b128 v[218:221], v143 offset:23552
	global_load_lds_dwordx4 v[202:203], off
	s_add_i32 m0, s28, 0x2000
	s_add_u32 s28, s6, 0x40000
	v_lshl_add_u64 v[206:207], s[6:7], 0, v[134:135]
	s_addc_u32 s29, s7, 0
	s_add_i32 s27, s27, s12
	global_load_lds_dwordx4 v[206:207], off
	v_lshl_add_u64 v[208:209], s[28:29], 0, v[64:65]
	s_mov_b32 m0, s27
	v_lshl_add_u64 v[222:223], s[8:9], 0, v[132:133]
	global_load_lds_dwordx4 v[208:209], off
	s_add_i32 m0, s27, 0x2000
	v_lshl_add_u64 v[208:209], s[28:29], 0, v[134:135]
	global_load_lds_dwordx4 v[208:209], off
	s_mov_b32 m0, s13
	v_lshl_add_u64 v[208:209], s[8:9], 0, v[130:131]
	global_load_lds_dwordx4 v[208:209], off
	s_mov_b32 m0, s16
	s_nop 0
	global_load_lds_dwordx4 v[222:223], off
	s_waitcnt vmcnt(8) lgkmcnt(0)
	s_setprio 1
	s_barrier
; #define PG8_STAGE(bufoff, gbase, voff) do { _Pragma("unroll") for (int _i = 0; _i < 2; ++_i) \
;         __builtin_amdgcn_global_load_lds((const unsigned*)((const char*)(gbase) + (voff)[_i]), (PG8_LAS unsigned*)(lds + (bufoff) + ldsw + _i * 8192), 16, 0, 0); } while (0)
; #define PG8_LDA(dst, b, h) do { _Pragma("unroll") for (int m = 0; m < 4; ++m) _Pragma("unroll") for (int k = 0; k < 2; ++k) dst[m][k] = *(const PG8_LAS bf16x8*)(lds + PG8_SA(b, h) + aoff + m * 2048 + k * 1024); } while (0)
; #define PG8_LDB(dst, b, h) do { _Pragma("unroll") for (int n = 0; n < 2; ++n) _Pragma("unroll") for (int k = 0; k < 2; ++k) dst[n][k] = *(const PG8_LAS bf16x8*)(lds + PG8_SB(b, h) + boff + n * 2048 + k * 1024); } while (0)
; #define PG8_MMA(ai, bj, At, Bt) do { __builtin_amdgcn_s_setprio(1); _Pragma("unroll") for (int m = 0; m < 4; ++m) _Pragma("unroll") for (int n = 0; n < 2; ++n) _Pragma("unroll") for (int k = 0; k < 2; ++k) \
;         acc[ai][bj][m][n] = __builtin_amdgcn_mfma_f32_16x16x32_bf16(Bt[n][k], At[m][k], acc[ai][bj][m][n], 0, 0, 0); __builtin_amdgcn_s_setprio(0); } while (0)
; #define PG8_WAIT_V(n) asm volatile("s_waitcnt vmcnt(" #n ")" ::: "memory")
; #define PG8_WAIT_L(n) asm volatile("s_waitcnt lgkmcnt(" #n ")" ::: "memory")
; #define PG8_BAR __builtin_amdgcn_s_barrier()
; #define PG8_SCHED __builtin_amdgcn_sched_barrier(0)
; template <class Epi, class Sched, bool ALIGN_EPI = false, bool SP2 = false>
; __device__ __forceinline__ void gemm_phase(PG8_LAS unsigned char* lds, const Gemm g, const Sched& S, const Epi& E, const int tid) {
;     ...
;             PG8_WAIT_V(8); PG8_WAIT_L(0); PG8_BAR; PG8_MMA(1, 0, At, B0); PG8_MMA(1, 1, At, B1); PG8_BAR; PG8_SCHED;
;             PG8_LDB(B0, 1, 0); PG8_LDB(B1, 1, 1); PG8_SCHED; PG8_LDA(At, 1, 0); PG8_STAGE(PG8_SA(0, 1), a2 + hstep, voffA);
;             PG8_WAIT_V(8); PG8_WAIT_L(0); PG8_BAR; PG8_MMA(0, 0, At, B0); PG8_MMA(0, 1, At, B1); PG8_BAR; PG8_SCHED;
	v_mfma_f32_16x16x32_bf16 v[94:97], v[144:147], v[178:181], v[94:97]
	v_mfma_f32_16x16x32_bf16 v[90:93], v[154:157], v[178:181], v[90:93]
	v_mfma_f32_16x16x32_bf16 v[86:89], v[144:147], v[186:189], v[86:89]
	v_mfma_f32_16x16x32_bf16 v[82:85], v[154:157], v[186:189], v[82:85]
	v_mfma_f32_16x16x32_bf16 v[78:81], v[144:147], v[194:197], v[78:81]
	v_mfma_f32_16x16x32_bf16 v[74:77], v[154:157], v[194:197], v[74:77]
	v_mfma_f32_16x16x32_bf16 v[70:73], v[144:147], v[214:217], v[70:73]
	v_mfma_f32_16x16x32_bf16 v[66:69], v[154:157], v[214:217], v[66:69]
	v_mfma_f32_16x16x32_bf16 v[94:97], v[150:153], v[182:185], v[94:97]
	v_mfma_f32_16x16x32_bf16 v[90:93], v[158:161], v[182:185], v[90:93]
	v_mfma_f32_16x16x32_bf16 v[86:89], v[150:153], v[190:193], v[86:89]
	v_mfma_f32_16x16x32_bf16 v[82:85], v[158:161], v[190:193], v[82:85]
	v_mfma_f32_16x16x32_bf16 v[78:81], v[150:153], v[198:201], v[78:81]
	v_mfma_f32_16x16x32_bf16 v[74:77], v[158:161], v[198:201], v[74:77]
	v_mfma_f32_16x16x32_bf16 v[70:73], v[150:153], v[218:221], v[70:73]
	v_mfma_f32_16x16x32_bf16 v[66:69], v[158:161], v[218:221], v[66:69]
	v_mfma_f32_16x16x32_bf16 v[28:31], v[162:165], v[178:181], v[28:31]
	v_mfma_f32_16x16x32_bf16 v[24:27], v[170:173], v[178:181], v[24:27]
	v_mfma_f32_16x16x32_bf16 v[20:23], v[162:165], v[186:189], v[20:23]
	v_mfma_f32_16x16x32_bf16 v[16:19], v[170:173], v[186:189], v[16:19]
	v_mfma_f32_16x16x32_bf16 v[12:15], v[162:165], v[194:197], v[12:15]
	v_mfma_f32_16x16x32_bf16 v[8:11], v[170:173], v[194:197], v[8:11]
	v_mfma_f32_16x16x32_bf16 v[4:7], v[162:165], v[214:217], v[4:7]
	v_mfma_f32_16x16x32_bf16 v[0:3], v[170:173], v[214:217], v[0:3]
	v_mfma_f32_16x16x32_bf16 v[28:31], v[166:169], v[182:185], v[28:31]
	v_mfma_f32_16x16x32_bf16 v[24:27], v[174:177], v[182:185], v[24:27]
	v_mfma_f32_16x16x32_bf16 v[20:23], v[166:169], v[190:193], v[20:23]
	v_mfma_f32_16x16x32_bf16 v[16:19], v[174:177], v[190:193], v[16:19]
	v_mfma_f32_16x16x32_bf16 v[12:15], v[166:169], v[198:201], v[12:15]
	v_mfma_f32_16x16x32_bf16 v[8:11], v[174:177], v[198:201], v[8:11]
	v_mfma_f32_16x16x32_bf16 v[4:7], v[166:169], v[218:221], v[4:7]
	v_mfma_f32_16x16x32_bf16 v[0:3], v[174:177], v[218:221], v[0:3]
	s_barrier
	s_setprio 0
	s_add_i32 s27, 0, 0x18000
	v_add_u32_e32 v149, s27, v142
	s_add_i32 s28, 0, 0x1c000
	ds_read_b128 v[144:147], v149
	ds_read_b128 v[150:153], v149 offset:1024
	ds_read_b128 v[154:157], v149 offset:2048
	ds_read_b128 v[158:161], v149 offset:3072
	v_add_u32_e32 v149, s28, v142
	ds_read_b128 v[162:165], v149
	ds_read_b128 v[166:169], v149 offset:1024
	ds_read_b128 v[170:173], v149 offset:2048
	ds_read_b128 v[174:177], v149 offset:3072
	s_add_u32 s8, s8, 0x40000
	s_addc_u32 s9, s9, 0
	s_mov_b32 m0, s17
	v_lshl_add_u64 v[224:225], s[8:9], 0, v[130:131]
	ds_read_b128 v[178:181], v143 offset:32768
	ds_read_b128 v[182:185], v143 offset:33792
	ds_read_b128 v[186:189], v143 offset:34816
	ds_read_b128 v[190:193], v143 offset:35840
	ds_read_b128 v[194:197], v143 offset:36864
	ds_read_b128 v[198:201], v143 offset:37888
	ds_read_b128 v[214:217], v143 offset:38912
	ds_read_b128 v[218:221], v143 offset:39936
	global_load_lds_dwordx4 v[224:225], off
	s_mov_b32 m0, s18
	v_lshl_add_u64 v[224:225], s[8:9], 0, v[132:133]
	global_load_lds_dwordx4 v[224:225], off
	s_waitcnt vmcnt(8) lgkmcnt(0)
	s_setprio 1
	s_barrier
	v_mfma_f32_16x16x32_bf16 v[126:129], v[144:147], v[178:181], v[126:129]
	v_mfma_f32_16x16x32_bf16 v[122:125], v[154:157], v[178:181], v[122:125]
	v_mfma_f32_16x16x32_bf16 v[118:121], v[144:147], v[186:189], v[118:121]
	v_mfma_f32_16x16x32_bf16 v[114:117], v[154:157], v[186:189], v[114:117]
	v_mfma_f32_16x16x32_bf16 v[110:113], v[144:147], v[194:197], v[110:113]
	v_mfma_f32_16x16x32_bf16 v[106:109], v[154:157], v[194:197], v[106:109]
	v_mfma_f32_16x16x32_bf16 v[102:105], v[144:147], v[214:217], v[102:105]
	v_mfma_f32_16x16x32_bf16 v[98:101], v[154:157], v[214:217], v[98:101]
	v_mfma_f32_16x16x32_bf16 v[126:129], v[150:153], v[182:185], v[126:129]
	v_mfma_f32_16x16x32_bf16 v[122:125], v[158:161], v[182:185], v[122:125]
	v_mfma_f32_16x16x32_bf16 v[118:121], v[150:153], v[190:193], v[118:121]
	v_mfma_f32_16x16x32_bf16 v[114:117], v[158:161], v[190:193], v[114:117]
	v_mfma_f32_16x16x32_bf16 v[110:113], v[150:153], v[198:201], v[110:113]
	v_mfma_f32_16x16x32_bf16 v[106:109], v[158:161], v[198:201], v[106:109]
	v_mfma_f32_16x16x32_bf16 v[102:105], v[150:153], v[218:221], v[102:105]
	v_mfma_f32_16x16x32_bf16 v[98:101], v[158:161], v[218:221], v[98:101]
	v_mfma_f32_16x16x32_bf16 v[60:63], v[162:165], v[178:181], v[60:63]
	v_mfma_f32_16x16x32_bf16 v[56:59], v[170:173], v[178:181], v[56:59]
	v_mfma_f32_16x16x32_bf16 v[52:55], v[162:165], v[186:189], v[52:55]
	v_mfma_f32_16x16x32_bf16 v[48:51], v[170:173], v[186:189], v[48:51]
	v_mfma_f32_16x16x32_bf16 v[44:47], v[162:165], v[194:197], v[44:47]
	v_mfma_f32_16x16x32_bf16 v[40:43], v[170:173], v[194:197], v[40:43]
	v_mfma_f32_16x16x32_bf16 v[36:39], v[162:165], v[214:217], v[36:39]
	v_mfma_f32_16x16x32_bf16 v[32:35], v[170:173], v[214:217], v[32:35]
	v_mfma_f32_16x16x32_bf16 v[60:63], v[166:169], v[182:185], v[60:63]
	v_mfma_f32_16x16x32_bf16 v[56:59], v[174:177], v[182:185], v[56:59]
	v_mfma_f32_16x16x32_bf16 v[52:55], v[166:169], v[190:193], v[52:55]
	v_mfma_f32_16x16x32_bf16 v[48:51], v[174:177], v[190:193], v[48:51]
	v_mfma_f32_16x16x32_bf16 v[44:47], v[166:169], v[198:201], v[44:47]
	v_mfma_f32_16x16x32_bf16 v[40:43], v[174:177], v[198:201], v[40:43]
	v_mfma_f32_16x16x32_bf16 v[36:39], v[166:169], v[218:221], v[36:39]
	v_mfma_f32_16x16x32_bf16 v[32:35], v[174:177], v[218:221], v[32:35]
	s_barrier
; #define PG8_STAGE(bufoff, gbase, voff) do { _Pragma("unroll") for (int _i = 0; _i < 2; ++_i) \
;         __builtin_amdgcn_global_load_lds((const unsigned*)((const char*)(gbase) + (voff)[_i]), (PG8_LAS unsigned*)(lds + (bufoff) + ldsw + _i * 8192), 16, 0, 0); } while (0)
; #define PG8_LDA(dst, b, h) do { _Pragma("unroll") for (int m = 0; m < 4; ++m) _Pragma("unroll") for (int k = 0; k < 2; ++k) dst[m][k] = *(const PG8_LAS bf16x8*)(lds + PG8_SA(b, h) + aoff + m * 2048 + k * 1024); } while (0)
; #define PG8_MMA(ai, bj, At, Bt) do { __builtin_amdgcn_s_setprio(1); _Pragma("unroll") for (int m = 0; m < 4; ++m) _Pragma("unroll") for (int n = 0; n < 2; ++n) _Pragma("unroll") for (int k = 0; k < 2; ++k) \
;         acc[ai][bj][m][n] = __builtin_amdgcn_mfma_f32_16x16x32_bf16(Bt[n][k], At[m][k], acc[ai][bj][m][n], 0, 0, 0); __builtin_amdgcn_s_setprio(0); } while (0)
; #define PG8_WAIT_V(n) asm volatile("s_waitcnt vmcnt(" #n ")" ::: "memory")
; template <class Epi, class Sched, bool ALIGN_EPI = false, bool SP2 = false>
; __device__ __forceinline__ void gemm_phase(PG8_LAS unsigned char* lds, const Gemm g, const Sched& S, const Epi& E, const int tid) {
;     ...
;             PG8_LDA(At, 1, 1); PG8_STAGE(PG8_SB(1, 0), b3, voffB); PG8_STAGE(PG8_SB(1, 1), b3 + hstep, voffB); PG8_STAGE(PG8_SA(1, 0), a3, voffA);
;             PG8_WAIT_V(8); PG8_WAIT_L(0); PG8_BAR; PG8_MMA(1, 0, At, B0); PG8_MMA(1, 1, At, B1); PG8_BAR; PG8_SCHED;
;     __device__ __forceinline__ void operator()(const f32x4 (&acc)[2][2][4][2], const Unit& u, int wr, int wc, int fr, int fq) const {
;     ...
;                 const int gcol = col - LDQ;
;                 const f32x4 b0 = *(const f32x4*)(bgate + gcol), b1 = *(const f32x4*)(bgate + gcol + 4);
; #pragma unroll
;                 for (int ai = 0; ai < 2; ++ai)
; #pragma unroll
;                     for (int m = 0; m < 4; ++m) {
;                         const int row = row0 + ai * 128 + m * 16;
;                         const f32x4 v0 = acc[ai][bj][m][0] + b0, v1 = acc[ai][bj][m][1] + b1;
;                         u32x4 w; w.x = pk2(sigmoidf_(v0[0]), sigmoidf_(v0[1])); w.y = pk2(sigmoidf_(v0[2]), sigmoidf_(v0[3]));
;                         w.z = pk2(sigmoidf_(v1[0]), sigmoidf_(v1[1])); w.w = pk2(sigmoidf_(v1[2]), sigmoidf_(v1[3]));
;                         __builtin_nontemporal_store(w, (u32x4*)(gates + (unsigned)(row * NG + gcol)));
	s_setprio 0
	s_add_i32 s8, s27, s12
	v_lshl_add_u64 v[202:203], v[202:203], 0, s[94:95]
	s_mov_b32 m0, s8
	ds_read_b128 v[178:181], v143 offset:49152
	ds_read_b128 v[182:185], v143 offset:50176
	ds_read_b128 v[186:189], v143 offset:51200
	ds_read_b128 v[190:193], v143 offset:52224
	ds_read_b128 v[194:197], v143 offset:53248
	ds_read_b128 v[198:201], v143 offset:54272
	ds_read_b128 v[214:217], v143 offset:55296
	ds_read_b128 v[218:221], v143 offset:56320
	global_load_lds_dwordx4 v[202:203], off
	s_add_i32 m0, s8, 0x2000
	s_add_u32 s6, s6, 0x40080
	v_lshl_add_u64 v[202:203], v[206:207], 0, s[94:95]
	s_addc_u32 s7, s7, 0
	s_add_i32 s8, s28, s12
	global_load_lds_dwordx4 v[202:203], off
	s_mov_b32 m0, s8
	v_lshl_add_u64 v[202:203], s[6:7], 0, v[64:65]
	global_load_lds_dwordx4 v[202:203], off
	s_add_i32 m0, s8, 0x2000
	v_lshl_add_u64 v[202:203], s[6:7], 0, v[134:135]
	global_load_lds_dwordx4 v[202:203], off
	s_mov_b32 m0, s20
	v_lshl_add_u64 v[202:203], v[208:209], 0, s[94:95]
	global_load_lds_dwordx4 v[202:203], off
	s_mov_b32 m0, s21
	v_lshl_add_u64 v[202:203], v[222:223], 0, s[94:95]
	global_load_lds_dwordx4 v[202:203], off
	s_waitcnt vmcnt(8) lgkmcnt(0)
	s_setprio 1
	s_barrier
	v_mfma_f32_16x16x32_bf16 v[94:97], v[144:147], v[178:181], v[94:97]
	v_mfma_f32_16x16x32_bf16 v[90:93], v[154:157], v[178:181], v[90:93]
	v_mfma_f32_16x16x32_bf16 v[86:89], v[144:147], v[186:189], v[86:89]
	v_mfma_f32_16x16x32_bf16 v[82:85], v[154:157], v[186:189], v[82:85]
	v_mfma_f32_16x16x32_bf16 v[78:81], v[144:147], v[194:197], v[78:81]
	v_mfma_f32_16x16x32_bf16 v[74:77], v[154:157], v[194:197], v[74:77]
	v_mfma_f32_16x16x32_bf16 v[70:73], v[144:147], v[214:217], v[70:73]
	v_mfma_f32_16x16x32_bf16 v[66:69], v[154:157], v[214:217], v[66:69]
	v_mfma_f32_16x16x32_bf16 v[94:97], v[150:153], v[182:185], v[94:97]
	v_mfma_f32_16x16x32_bf16 v[90:93], v[158:161], v[182:185], v[90:93]
	v_mfma_f32_16x16x32_bf16 v[86:89], v[150:153], v[190:193], v[86:89]
	v_mfma_f32_16x16x32_bf16 v[82:85], v[158:161], v[190:193], v[82:85]
	v_mfma_f32_16x16x32_bf16 v[78:81], v[150:153], v[198:201], v[78:81]
	v_mfma_f32_16x16x32_bf16 v[74:77], v[158:161], v[198:201], v[74:77]
	v_mfma_f32_16x16x32_bf16 v[70:73], v[150:153], v[218:221], v[70:73]
	v_mfma_f32_16x16x32_bf16 v[66:69], v[158:161], v[218:221], v[66:69]
	v_mfma_f32_16x16x32_bf16 v[28:31], v[162:165], v[178:181], v[28:31]
	v_mfma_f32_16x16x32_bf16 v[24:27], v[170:173], v[178:181], v[24:27]
	v_mfma_f32_16x16x32_bf16 v[20:23], v[162:165], v[186:189], v[20:23]
	v_mfma_f32_16x16x32_bf16 v[16:19], v[170:173], v[186:189], v[16:19]
	v_mfma_f32_16x16x32_bf16 v[12:15], v[162:165], v[194:197], v[12:15]
	v_mfma_f32_16x16x32_bf16 v[8:11], v[170:173], v[194:197], v[8:11]
	v_mfma_f32_16x16x32_bf16 v[4:7], v[162:165], v[214:217], v[4:7]
	v_mfma_f32_16x16x32_bf16 v[0:3], v[170:173], v[214:217], v[0:3]
	v_mfma_f32_16x16x32_bf16 v[28:31], v[166:169], v[182:185], v[28:31]
	v_mfma_f32_16x16x32_bf16 v[24:27], v[174:177], v[182:185], v[24:27]
	v_mfma_f32_16x16x32_bf16 v[20:23], v[166:169], v[190:193], v[20:23]
	v_mfma_f32_16x16x32_bf16 v[16:19], v[174:177], v[190:193], v[16:19]
	v_mfma_f32_16x16x32_bf16 v[12:15], v[166:169], v[198:201], v[12:15]
	v_mfma_f32_16x16x32_bf16 v[8:11], v[174:177], v[198:201], v[8:11]
	v_mfma_f32_16x16x32_bf16 v[4:7], v[166:169], v[218:221], v[4:7]
	v_mfma_f32_16x16x32_bf16 v[0:3], v[174:177], v[218:221], v[0:3]
	s_barrier
	s_setprio 0
	s_add_i32 s26, s26, 2
	s_add_u32 s4, s4, 0x100
	s_addc_u32 s5, s5, 0
	s_cmp_gt_u32 s26, 13
	s_cbranch_scc0 .LBB0_511
	s_and_b32 s12, 0xffff, s11
	s_lshl_b32 s13, s19, 8
	s_lshl_b32 s11, s12, 8
	s_and_b32 s2, s13, 0xff00
	s_and_b32 s14, 0xffff, s14
	v_or_b32_e32 v64, s15, v148
	s_cmpk_gt_u32 s14, 0x8f
	v_or_b32_e32 v186, s2, v64
	s_cselect_b64 s[2:3], -1, 0
	v_cmp_eq_u32_e64 s[0:1], 0, v141
	v_add_u32_e32 v187, s11, v140
	s_mov_b64 s[4:5], -1
	s_and_b64 vcc, exec, s[2:3]
	s_cbranch_vccz .LBB0_514
	v_add_u32_e32 v138, 0xffffee00, v186
	v_ashrrev_i32_e32 v139, 31, v138
	v_lshl_add_u64 v[134:135], v[138:139], 2, s[52:53]
	global_load_dwordx4 v[130:133], v[134:135], off offset:16
	s_nop 0
	global_load_dwordx4 v[134:137], v[134:135], off
	s_waitcnt vmcnt(0)
	v_pk_add_f32 v[146:147], v[122:123], v[130:131]
	v_pk_add_f32 v[140:141], v[126:127], v[134:135]
	v_pk_add_f32 v[142:143], v[128:129], v[136:137]
	v_mul_f32_e32 v64, 0xbfb8aa3b, v140
	v_mul_f32_e32 v139, 0xbfb8aa3b, v141
	v_exp_f32_e32 v64, v64
	v_exp_f32_e32 v139, v139
	v_pk_add_f32 v[144:145], v[124:125], v[132:133]
	v_add_f32_e32 v64, 1.0, v64
	v_add_f32_e32 v139, 1.0, v139
	v_rcp_f32_e32 v64, v64
	v_rcp_f32_e32 v139, v139
	s_nop 0
	v_cvt_pk_bf16_f32 v140, v64, v139
	v_mul_f32_e32 v64, 0xbfb8aa3b, v142
	v_mul_f32_e32 v139, 0xbfb8aa3b, v143
	v_exp_f32_e32 v64, v64
	v_exp_f32_e32 v139, v139
	v_add_f32_e32 v64, 1.0, v64
	v_add_f32_e32 v139, 1.0, v139
	v_rcp_f32_e32 v64, v64
	v_rcp_f32_e32 v139, v139
	s_nop 0
	v_cvt_pk_bf16_f32 v141, v64, v139
	v_mul_f32_e32 v64, 0xbfb8aa3b, v146
	v_mul_f32_e32 v139, 0xbfb8aa3b, v147
	v_exp_f32_e32 v64, v64
	v_exp_f32_e32 v139, v139
	v_pk_add_f32 v[146:147], v[114:115], v[130:131]
	v_add_f32_e32 v64, 1.0, v64
	v_add_f32_e32 v139, 1.0, v139
	v_rcp_f32_e32 v64, v64
	v_rcp_f32_e32 v139, v139
	s_nop 0
	v_cvt_pk_bf16_f32 v142, v64, v139
	v_mul_f32_e32 v64, 0xbfb8aa3b, v144
	v_mul_f32_e32 v139, 0xbfb8aa3b, v145
	v_exp_f32_e32 v64, v64
	v_exp_f32_e32 v139, v139
	v_add_f32_e32 v64, 1.0, v64
	v_add_f32_e32 v139, 1.0, v139
	v_rcp_f32_e32 v64, v64
	v_rcp_f32_e32 v139, v139
	s_nop 0
	v_cvt_pk_bf16_f32 v143, v64, v139
	v_mad_u64_u32 v[138:139], s[4:5], v187, s76, v[138:139]
	v_mov_b32_e32 v139, v65
	v_lshl_add_u64 v[144:145], v[138:139], 1, s[36:37]
; __device__ __forceinline__ unsigned pk2(float lo, float hi) { f32x2_t v = {lo, hi}; bf16x2_t b = __builtin_convertvector(v, bf16x2_t); return __builtin_bit_cast(unsigned, b); }
; __device__ __forceinline__ float sigmoidf_(float x) { return __builtin_amdgcn_rcpf(1.0f + __expf(-x)); }
;     __device__ __forceinline__ void operator()(const f32x4 (&acc)[2][2][4][2], const Unit& u, int wr, int wc, int fr, int fq) const {
;     ...
;                 const f32x4 b0 = *(const f32x4*)(bgate + gcol), b1 = *(const f32x4*)(bgate + gcol + 4);
; #pragma unroll
;                 for (int ai = 0; ai < 2; ++ai)
; #pragma unroll
;                     for (int m = 0; m < 4; ++m) {
;                         const int row = row0 + ai * 128 + m * 16;
;                         const f32x4 v0 = acc[ai][bj][m][0] + b0, v1 = acc[ai][bj][m][1] + b1;
;                         u32x4 w; w.x = pk2(sigmoidf_(v0[0]), sigmoidf_(v0[1])); w.y = pk2(sigmoidf_(v0[2]), sigmoidf_(v0[3]));
;                         w.z = pk2(sigmoidf_(v1[0]), sigmoidf_(v1[1])); w.w = pk2(sigmoidf_(v1[2]), sigmoidf_(v1[3]));
;                         __builtin_nontemporal_store(w, (u32x4*)(gates + (unsigned)(row * NG + gcol)));
	flat_store_dwordx4 v[144:145], v[140:143] nt
	v_pk_add_f32 v[144:145], v[116:117], v[132:133]
	s_mov_b64 s[4:5], 0
	v_pk_add_f32 v[140:141], v[118:119], v[134:135]
	v_pk_add_f32 v[142:143], v[120:121], v[136:137]
	v_mul_f32_e32 v64, 0xbfb8aa3b, v140
	v_mul_f32_e32 v139, 0xbfb8aa3b, v141
	v_exp_f32_e32 v64, v64
	v_exp_f32_e32 v139, v139
	v_add_f32_e32 v64, 1.0, v64
	v_add_f32_e32 v139, 1.0, v139
	v_rcp_f32_e32 v64, v64
	v_rcp_f32_e32 v139, v139
	s_nop 0
	v_cvt_pk_bf16_f32 v140, v64, v139
	v_mul_f32_e32 v64, 0xbfb8aa3b, v142
	v_mul_f32_e32 v139, 0xbfb8aa3b, v143
	v_exp_f32_e32 v64, v64
	v_exp_f32_e32 v139, v139
	v_add_f32_e32 v64, 1.0, v64
	v_add_f32_e32 v139, 1.0, v139
	v_rcp_f32_e32 v64, v64
	v_rcp_f32_e32 v139, v139
	s_nop 0
	v_cvt_pk_bf16_f32 v141, v64, v139
	v_mul_f32_e32 v64, 0xbfb8aa3b, v146
	v_mul_f32_e32 v139, 0xbfb8aa3b, v147
	v_exp_f32_e32 v64, v64
	v_exp_f32_e32 v139, v139
	v_pk_add_f32 v[146:147], v[110:111], v[134:135]
	v_add_f32_e32 v64, 1.0, v64
	v_add_f32_e32 v139, 1.0, v139
	v_rcp_f32_e32 v64, v64
	v_rcp_f32_e32 v139, v139
	s_nop 0
	v_cvt_pk_bf16_f32 v142, v64, v139
	v_mul_f32_e32 v64, 0xbfb8aa3b, v144
	v_mul_f32_e32 v139, 0xbfb8aa3b, v145
	v_exp_f32_e32 v64, v64
	v_exp_f32_e32 v139, v139
	v_add_f32_e32 v64, 1.0, v64
	v_add_f32_e32 v139, 1.0, v139
	v_rcp_f32_e32 v64, v64
	v_rcp_f32_e32 v139, v139
	s_nop 0
	v_cvt_pk_bf16_f32 v143, v64, v139
	v_add_u32_e32 v64, 0xc000, v138
	v_lshl_add_u64 v[144:145], v[64:65], 1, s[36:37]
	v_mul_f32_e32 v64, 0xbfb8aa3b, v146
	v_mul_f32_e32 v139, 0xbfb8aa3b, v147
	v_exp_f32_e32 v64, v64
	v_exp_f32_e32 v139, v139
	flat_store_dwordx4 v[144:145], v[140:143] nt
	v_pk_add_f32 v[144:145], v[112:113], v[136:137]
	v_add_f32_e32 v64, 1.0, v64
	v_add_f32_e32 v139, 1.0, v139
	v_rcp_f32_e32 v64, v64
	v_rcp_f32_e32 v139, v139
	v_pk_add_f32 v[142:143], v[106:107], v[130:131]
	v_pk_add_f32 v[140:141], v[108:109], v[132:133]
	v_pk_add_f32 v[146:147], v[98:99], v[130:131]
	v_cvt_pk_bf16_f32 v150, v64, v139
	v_mul_f32_e32 v64, 0xbfb8aa3b, v144
	v_mul_f32_e32 v139, 0xbfb8aa3b, v145
	v_exp_f32_e32 v64, v64
	v_exp_f32_e32 v139, v139
	v_pk_add_f32 v[144:145], v[100:101], v[132:133]
	v_add_f32_e32 v64, 1.0, v64
	v_add_f32_e32 v139, 1.0, v139
	v_rcp_f32_e32 v64, v64
	v_rcp_f32_e32 v139, v139
	s_nop 0
	v_cvt_pk_bf16_f32 v151, v64, v139
	v_mul_f32_e32 v64, 0xbfb8aa3b, v142
	v_mul_f32_e32 v139, 0xbfb8aa3b, v143
	v_exp_f32_e32 v64, v64
	v_exp_f32_e32 v139, v139
	v_pk_add_f32 v[142:143], v[104:105], v[136:137]
	v_add_f32_e32 v64, 1.0, v64
	v_add_f32_e32 v139, 1.0, v139
	v_rcp_f32_e32 v64, v64
	v_rcp_f32_e32 v139, v139
	s_nop 0
	v_cvt_pk_bf16_f32 v152, v64, v139
	v_mul_f32_e32 v64, 0xbfb8aa3b, v140
	v_mul_f32_e32 v139, 0xbfb8aa3b, v141
	v_exp_f32_e32 v64, v64
	v_exp_f32_e32 v139, v139
	v_add_f32_e32 v64, 1.0, v64
	v_add_f32_e32 v139, 1.0, v139
	v_rcp_f32_e32 v64, v64
	v_rcp_f32_e32 v139, v139
	s_nop 0
	v_cvt_pk_bf16_f32 v153, v64, v139
	v_add_u32_e32 v64, 0x18000, v138
	v_lshl_add_u64 v[140:141], v[64:65], 1, s[36:37]
	flat_store_dwordx4 v[140:141], v[150:153] nt
	v_pk_add_f32 v[140:141], v[102:103], v[134:135]
	s_nop 0
	v_mul_f32_e32 v64, 0xbfb8aa3b, v140
	v_mul_f32_e32 v139, 0xbfb8aa3b, v141
	v_exp_f32_e32 v64, v64
	v_exp_f32_e32 v139, v139
	v_add_f32_e32 v64, 1.0, v64
	v_add_f32_e32 v139, 1.0, v139
	v_rcp_f32_e32 v64, v64
	v_rcp_f32_e32 v139, v139
	s_nop 0
	v_cvt_pk_bf16_f32 v140, v64, v139
	v_mul_f32_e32 v64, 0xbfb8aa3b, v142
	v_mul_f32_e32 v139, 0xbfb8aa3b, v143
	v_exp_f32_e32 v64, v64
	v_exp_f32_e32 v139, v139
	v_add_f32_e32 v64, 1.0, v64
	v_add_f32_e32 v139, 1.0, v139
	v_rcp_f32_e32 v64, v64
	v_rcp_f32_e32 v139, v139
	s_nop 0
	v_cvt_pk_bf16_f32 v141, v64, v139
	v_mul_f32_e32 v64, 0xbfb8aa3b, v146
	v_mul_f32_e32 v139, 0xbfb8aa3b, v147
	v_exp_f32_e32 v64, v64
	v_exp_f32_e32 v139, v139
	v_pk_add_f32 v[146:147], v[90:91], v[130:131]
	v_add_f32_e32 v64, 1.0, v64
	v_add_f32_e32 v139, 1.0, v139
	v_rcp_f32_e32 v64, v64
	v_rcp_f32_e32 v139, v139
	s_nop 0
	v_cvt_pk_bf16_f32 v142, v64, v139
	v_mul_f32_e32 v64, 0xbfb8aa3b, v144
	v_mul_f32_e32 v139, 0xbfb8aa3b, v145
	v_exp_f32_e32 v64, v64
	v_exp_f32_e32 v139, v139
	v_add_f32_e32 v64, 1.0, v64
	v_add_f32_e32 v139, 1.0, v139
	v_rcp_f32_e32 v64, v64
	v_rcp_f32_e32 v139, v139
	s_nop 0
	v_cvt_pk_bf16_f32 v143, v64, v139
	v_add_u32_e32 v64, 0x24000, v138
	v_lshl_add_u64 v[144:145], v[64:65], 1, s[36:37]
	flat_store_dwordx4 v[144:145], v[140:143] nt
	v_pk_add_f32 v[144:145], v[92:93], v[132:133]
	s_nop 0
	v_pk_add_f32 v[140:141], v[94:95], v[134:135]
	v_pk_add_f32 v[142:143], v[96:97], v[136:137]
	v_mul_f32_e32 v64, 0xbfb8aa3b, v140
	v_mul_f32_e32 v139, 0xbfb8aa3b, v141
	v_exp_f32_e32 v64, v64
	v_exp_f32_e32 v139, v139
	v_add_f32_e32 v64, 1.0, v64
	v_add_f32_e32 v139, 1.0, v139
	v_rcp_f32_e32 v64, v64
	v_rcp_f32_e32 v139, v139
	s_nop 0
	v_cvt_pk_bf16_f32 v140, v64, v139
	v_mul_f32_e32 v64, 0xbfb8aa3b, v142
	v_mul_f32_e32 v139, 0xbfb8aa3b, v143
	v_exp_f32_e32 v64, v64
	v_exp_f32_e32 v139, v139
	v_add_f32_e32 v64, 1.0, v64
	v_add_f32_e32 v139, 1.0, v139
	v_rcp_f32_e32 v64, v64
	v_rcp_f32_e32 v139, v139
; __device__ __forceinline__ unsigned pk2(float lo, float hi) { f32x2_t v = {lo, hi}; bf16x2_t b = __builtin_convertvector(v, bf16x2_t); return __builtin_bit_cast(unsigned, b); }
; __device__ __forceinline__ float sigmoidf_(float x) { return __builtin_amdgcn_rcpf(1.0f + __expf(-x)); }
;     __device__ __forceinline__ void operator()(const f32x4 (&acc)[2][2][4][2], const Unit& u, int wr, int wc, int fr, int fq) const {
;     ...
;                 const f32x4 b0 = *(const f32x4*)(bgate + gcol), b1 = *(const f32x4*)(bgate + gcol + 4);
; #pragma unroll
;                 for (int ai = 0; ai < 2; ++ai)
; #pragma unroll
;                     for (int m = 0; m < 4; ++m) {
;                         const int row = row0 + ai * 128 + m * 16;
;                         const f32x4 v0 = acc[ai][bj][m][0] + b0, v1 = acc[ai][bj][m][1] + b1;
;                         u32x4 w; w.x = pk2(sigmoidf_(v0[0]), sigmoidf_(v0[1])); w.y = pk2(sigmoidf_(v0[2]), sigmoidf_(v0[3]));
;                         w.z = pk2(sigmoidf_(v1[0]), sigmoidf_(v1[1])); w.w = pk2(sigmoidf_(v1[2]), sigmoidf_(v1[3]));
;                         __builtin_nontemporal_store(w, (u32x4*)(gates + (unsigned)(row * NG + gcol)));
	s_nop 0
	v_cvt_pk_bf16_f32 v141, v64, v139
	v_mul_f32_e32 v64, 0xbfb8aa3b, v146
	v_mul_f32_e32 v139, 0xbfb8aa3b, v147
	v_exp_f32_e32 v64, v64
	v_exp_f32_e32 v139, v139
	v_pk_add_f32 v[146:147], v[82:83], v[130:131]
	v_add_f32_e32 v64, 1.0, v64
	v_add_f32_e32 v139, 1.0, v139
	v_rcp_f32_e32 v64, v64
	v_rcp_f32_e32 v139, v139
	s_nop 0
	v_cvt_pk_bf16_f32 v142, v64, v139
	v_mul_f32_e32 v64, 0xbfb8aa3b, v144
	v_mul_f32_e32 v139, 0xbfb8aa3b, v145
	v_exp_f32_e32 v64, v64
	v_exp_f32_e32 v139, v139
	v_add_f32_e32 v64, 1.0, v64
	v_add_f32_e32 v139, 1.0, v139
	v_rcp_f32_e32 v64, v64
	v_rcp_f32_e32 v139, v139
	s_nop 0
	v_cvt_pk_bf16_f32 v143, v64, v139
	v_add_u32_e32 v64, 0x60000, v138
	v_lshl_add_u64 v[144:145], v[64:65], 1, s[36:37]
	flat_store_dwordx4 v[144:145], v[140:143] nt
	v_pk_add_f32 v[144:145], v[84:85], v[132:133]
	s_nop 0
	v_pk_add_f32 v[140:141], v[86:87], v[134:135]
	v_pk_add_f32 v[142:143], v[88:89], v[136:137]
	v_mul_f32_e32 v64, 0xbfb8aa3b, v140
	v_mul_f32_e32 v139, 0xbfb8aa3b, v141
	v_exp_f32_e32 v64, v64
	v_exp_f32_e32 v139, v139
	v_add_f32_e32 v64, 1.0, v64
	v_add_f32_e32 v139, 1.0, v139
	v_rcp_f32_e32 v64, v64
	v_rcp_f32_e32 v139, v139
	s_nop 0
	v_cvt_pk_bf16_f32 v140, v64, v139
	v_mul_f32_e32 v64, 0xbfb8aa3b, v142
	v_mul_f32_e32 v139, 0xbfb8aa3b, v143
	v_exp_f32_e32 v64, v64
	v_exp_f32_e32 v139, v139
	v_add_f32_e32 v64, 1.0, v64
	v_add_f32_e32 v139, 1.0, v139
	v_rcp_f32_e32 v64, v64
	v_rcp_f32_e32 v139, v139
	s_nop 0
	v_cvt_pk_bf16_f32 v141, v64, v139
	v_mul_f32_e32 v64, 0xbfb8aa3b, v146
	v_mul_f32_e32 v139, 0xbfb8aa3b, v147
	v_exp_f32_e32 v64, v64
	v_exp_f32_e32 v139, v139
	v_pk_add_f32 v[146:147], v[74:75], v[130:131]
	v_add_f32_e32 v64, 1.0, v64
	v_add_f32_e32 v139, 1.0, v139
	v_rcp_f32_e32 v64, v64
	v_rcp_f32_e32 v139, v139
	s_nop 0
	v_cvt_pk_bf16_f32 v142, v64, v139
	v_mul_f32_e32 v64, 0xbfb8aa3b, v144
	v_mul_f32_e32 v139, 0xbfb8aa3b, v145
	v_exp_f32_e32 v64, v64
	v_exp_f32_e32 v139, v139
	v_add_f32_e32 v64, 1.0, v64
	v_add_f32_e32 v139, 1.0, v139
	v_rcp_f32_e32 v64, v64
	v_rcp_f32_e32 v139, v139
	s_nop 0
	v_cvt_pk_bf16_f32 v143, v64, v139
	v_add_u32_e32 v64, 0x6c000, v138
	v_lshl_add_u64 v[144:145], v[64:65], 1, s[36:37]
	flat_store_dwordx4 v[144:145], v[140:143] nt
	v_pk_add_f32 v[144:145], v[76:77], v[132:133]
	s_nop 0
	v_pk_add_f32 v[140:141], v[78:79], v[134:135]
	v_pk_add_f32 v[142:143], v[80:81], v[136:137]
	v_mul_f32_e32 v64, 0xbfb8aa3b, v140
	v_mul_f32_e32 v139, 0xbfb8aa3b, v141
	v_exp_f32_e32 v64, v64
	v_exp_f32_e32 v139, v139
	v_pk_add_f32 v[134:135], v[70:71], v[134:135]
	v_pk_add_f32 v[136:137], v[72:73], v[136:137]
	v_add_f32_e32 v64, 1.0, v64
	v_add_f32_e32 v139, 1.0, v139
	v_rcp_f32_e32 v64, v64
	v_rcp_f32_e32 v139, v139
	s_nop 0
	v_cvt_pk_bf16_f32 v140, v64, v139
	v_mul_f32_e32 v64, 0xbfb8aa3b, v142
	v_mul_f32_e32 v139, 0xbfb8aa3b, v143
	v_exp_f32_e32 v64, v64
	v_exp_f32_e32 v139, v139
	v_add_f32_e32 v64, 1.0, v64
	v_add_f32_e32 v139, 1.0, v139
	v_rcp_f32_e32 v64, v64
	v_rcp_f32_e32 v139, v139
	s_nop 0
	v_cvt_pk_bf16_f32 v141, v64, v139
	v_mul_f32_e32 v64, 0xbfb8aa3b, v146
	v_mul_f32_e32 v139, 0xbfb8aa3b, v147
	v_exp_f32_e32 v64, v64
	v_exp_f32_e32 v139, v139
	v_add_f32_e32 v64, 1.0, v64
	v_add_f32_e32 v139, 1.0, v139
	v_rcp_f32_e32 v64, v64
	v_rcp_f32_e32 v139, v139
	s_nop 0
	v_cvt_pk_bf16_f32 v142, v64, v139
	v_mul_f32_e32 v64, 0xbfb8aa3b, v144
	v_mul_f32_e32 v139, 0xbfb8aa3b, v145
	v_exp_f32_e32 v64, v64
	v_exp_f32_e32 v139, v139
	v_add_f32_e32 v64, 1.0, v64
	v_add_f32_e32 v139, 1.0, v139
	v_rcp_f32_e32 v64, v64
	v_rcp_f32_e32 v139, v139
	s_nop 0
	v_cvt_pk_bf16_f32 v143, v64, v139
	v_add_u32_e32 v64, 0x78000, v138
	v_lshl_add_u64 v[144:145], v[64:65], 1, s[36:37]
	flat_store_dwordx4 v[144:145], v[140:143] nt
	v_mul_f32_e32 v64, 0xbfb8aa3b, v134
	v_exp_f32_e32 v64, v64
	v_pk_add_f32 v[140:141], v[68:69], v[132:133]
	v_pk_add_f32 v[132:133], v[66:67], v[130:131]
	v_mul_f32_e32 v130, 0xbfb8aa3b, v135
	v_exp_f32_e32 v130, v130
	v_add_f32_e32 v64, 1.0, v64
	v_rcp_f32_e32 v64, v64
	v_mul_f32_e32 v131, 0xbfb8aa3b, v137
	v_add_f32_e32 v130, 1.0, v130
	v_rcp_f32_e32 v130, v130
	v_exp_f32_e32 v131, v131
	v_cvt_pk_bf16_f32 v130, v64, v130
	v_mul_f32_e32 v64, 0xbfb8aa3b, v136
	v_exp_f32_e32 v64, v64
	v_add_f32_e32 v131, 1.0, v131
	v_rcp_f32_e32 v131, v131
	v_add_f32_e32 v64, 1.0, v64
	v_rcp_f32_e32 v64, v64
	s_nop 0
	v_cvt_pk_bf16_f32 v131, v64, v131
	v_mul_f32_e32 v64, 0xbfb8aa3b, v132
	v_mul_f32_e32 v132, 0xbfb8aa3b, v133
	v_exp_f32_e32 v64, v64
	v_exp_f32_e32 v132, v132
	v_mul_f32_e32 v133, 0xbfb8aa3b, v141
	v_exp_f32_e32 v133, v133
	v_add_f32_e32 v64, 1.0, v64
	v_add_f32_e32 v132, 1.0, v132
	v_rcp_f32_e32 v64, v64
	v_rcp_f32_e32 v132, v132
	v_add_f32_e32 v133, 1.0, v133
	v_rcp_f32_e32 v133, v133
	v_cvt_pk_bf16_f32 v132, v64, v132
	v_mul_f32_e32 v64, 0xbfb8aa3b, v140
	v_exp_f32_e32 v64, v64
	s_nop 0
	v_add_f32_e32 v64, 1.0, v64
	v_rcp_f32_e32 v64, v64
	s_nop 0
	v_cvt_pk_bf16_f32 v133, v64, v133
	v_add_u32_e32 v64, 0x84000, v138
	v_lshl_add_u64 v[134:135], v[64:65], 1, s[36:37]
	flat_store_dwordx4 v[134:135], v[130:133] nt

; #define PG8_STAGE(bufoff, gbase, voff) do { _Pragma("unroll") for (int _i = 0; _i < 2; ++_i) \
;         __builtin_amdgcn_global_load_lds((const unsigned*)((const char*)(gbase) + (voff)[_i]), (PG8_LAS unsigned*)(lds + (bufoff) + ldsw + _i * 8192), 16, 0, 0); } while (0)
; #define PG8_LDA(dst, b, h) do { _Pragma("unroll") for (int m = 0; m < 4; ++m) _Pragma("unroll") for (int k = 0; k < 2; ++k) dst[m][k] = *(const PG8_LAS bf16x8*)(lds + PG8_SA(b, h) + aoff + m * 2048 + k * 1024); } while (0)
; #define PG8_LDB(dst, b, h) do { _Pragma("unroll") for (int n = 0; n < 2; ++n) _Pragma("unroll") for (int k = 0; k < 2; ++k) dst[n][k] = *(const PG8_LAS bf16x8*)(lds + PG8_SB(b, h) + boff + n * 2048 + k * 1024); } while (0)
; #define PG8_MMA(ai, bj, At, Bt) do { __builtin_amdgcn_s_setprio(1); _Pragma("unroll") for (int m = 0; m < 4; ++m) _Pragma("unroll") for (int n = 0; n < 2; ++n) _Pragma("unroll") for (int k = 0; k < 2; ++k) \
;         acc[ai][bj][m][n] = __builtin_amdgcn_mfma_f32_16x16x32_bf16(Bt[n][k], At[m][k], acc[ai][bj][m][n], 0, 0, 0); __builtin_amdgcn_s_setprio(0); } while (0)
; #define PG8_WAIT_V(n) asm volatile("s_waitcnt vmcnt(" #n ")" ::: "memory")
; #define PG8_WAIT_L(n) asm volatile("s_waitcnt lgkmcnt(" #n ")" ::: "memory")
; #define PG8_BAR __builtin_amdgcn_s_barrier()
; #define PG8_SCHED __builtin_amdgcn_sched_barrier(0)
; template <class Epi, class Sched, bool ALIGN_EPI = false, bool SP2 = false>
; __device__ __forceinline__ void gemm_phase(PG8_LAS unsigned char* lds, const Gemm g, const Sched& S, const Epi& E, const int tid) {
;     ...
;             PG8_LDB(B0, 0, 0); PG8_LDB(B1, 0, 1); PG8_SCHED; PG8_LDA(At, 0, 0); PG8_STAGE(PG8_SA(1, 1), a1 + hstep, voffA);
;             PG8_WAIT_V(8); PG8_WAIT_L(0); PG8_BAR; PG8_MMA(0, 0, At, B0); PG8_MMA(0, 1, At, B1); PG8_BAR; PG8_SCHED;
;             PG8_LDA(At, 0, 1); PG8_STAGE(PG8_SB(0, 0), b2, voffB); PG8_STAGE(PG8_SB(0, 1), b2 + hstep, voffB); PG8_STAGE(PG8_SA(0, 0), a2, voffA);
;             PG8_WAIT_V(8); PG8_WAIT_L(0); PG8_BAR; PG8_MMA(1, 0, At, B0); PG8_MMA(1, 1, At, B1); PG8_BAR; PG8_SCHED;
.LBB0_704:
	s_add_u32 s24, s2, 0xfffc0080
	s_addc_u32 s25, s3, -1
	s_add_i32 s51, 0, 0x10000
	s_cmp_eq_u32 s50, 12
	s_cselect_b32 s27, s17, s25
	s_cselect_b32 s26, s29, s24
	v_add_u32_e32 v64, s51, v213
	s_cselect_b32 s25, s15, s49
	s_cselect_b32 s24, s47, s48
	s_add_i32 s54, 0, 0x14000
	ds_read_b128 v[130:133], v64
	ds_read_b128 v[134:137], v64 offset:1024
	ds_read_b128 v[138:141], v64 offset:2048
	ds_read_b128 v[142:145], v64 offset:3072
	v_add_u32_e32 v64, s54, v213
	ds_read_b128 v[146:149], v64
	ds_read_b128 v[150:153], v64 offset:1024
	ds_read_b128 v[154:157], v64 offset:2048
	ds_read_b128 v[158:161], v64 offset:3072
	v_lshl_add_u64 v[202:203], s[2:3], 0, v[198:199]
	s_add_i32 m0, s35, 0xc000
	ds_read_b128 v[162:165], v227
	ds_read_b128 v[166:169], v227 offset:1024
	ds_read_b128 v[170:173], v227 offset:2048
	ds_read_b128 v[174:177], v227 offset:3072
	ds_read_b128 v[178:181], v227 offset:4096
	ds_read_b128 v[182:185], v227 offset:5120
	ds_read_b128 v[218:221], v227 offset:6144
	ds_read_b128 v[222:225], v227 offset:7168
	global_load_lds_dwordx4 v[202:203], off
	s_add_i32 m0, s35, 0xe000
	v_lshl_add_u64 v[202:203], s[2:3], 0, v[196:197]
	global_load_lds_dwordx4 v[202:203], off
	s_waitcnt vmcnt(8) lgkmcnt(0)
	s_setprio 1
	s_barrier
	v_mfma_f32_16x16x32_bf16 v[126:129], v[130:133], v[162:165], v[126:129]
	v_mfma_f32_16x16x32_bf16 v[122:125], v[138:141], v[162:165], v[122:125]
	v_mfma_f32_16x16x32_bf16 v[118:121], v[130:133], v[170:173], v[118:121]
	v_mfma_f32_16x16x32_bf16 v[114:117], v[138:141], v[170:173], v[114:117]
	v_mfma_f32_16x16x32_bf16 v[110:113], v[130:133], v[178:181], v[110:113]
	v_mfma_f32_16x16x32_bf16 v[106:109], v[138:141], v[178:181], v[106:109]
	v_mfma_f32_16x16x32_bf16 v[102:105], v[130:133], v[218:221], v[102:105]
	v_mfma_f32_16x16x32_bf16 v[98:101], v[138:141], v[218:221], v[98:101]
	v_mfma_f32_16x16x32_bf16 v[126:129], v[134:137], v[166:169], v[126:129]
	v_mfma_f32_16x16x32_bf16 v[122:125], v[142:145], v[166:169], v[122:125]
	v_mfma_f32_16x16x32_bf16 v[118:121], v[134:137], v[174:177], v[118:121]
	v_mfma_f32_16x16x32_bf16 v[114:117], v[142:145], v[174:177], v[114:117]
	v_mfma_f32_16x16x32_bf16 v[110:113], v[134:137], v[182:185], v[110:113]
	v_mfma_f32_16x16x32_bf16 v[106:109], v[142:145], v[182:185], v[106:109]
	v_mfma_f32_16x16x32_bf16 v[102:105], v[134:137], v[222:225], v[102:105]
	v_mfma_f32_16x16x32_bf16 v[98:101], v[142:145], v[222:225], v[98:101]
	v_mfma_f32_16x16x32_bf16 v[60:63], v[146:149], v[162:165], v[60:63]
	v_mfma_f32_16x16x32_bf16 v[56:59], v[154:157], v[162:165], v[56:59]
	v_mfma_f32_16x16x32_bf16 v[52:55], v[146:149], v[170:173], v[52:55]
	v_mfma_f32_16x16x32_bf16 v[48:51], v[154:157], v[170:173], v[48:51]
	v_mfma_f32_16x16x32_bf16 v[44:47], v[146:149], v[178:181], v[44:47]
	v_mfma_f32_16x16x32_bf16 v[40:43], v[154:157], v[178:181], v[40:43]
	v_mfma_f32_16x16x32_bf16 v[36:39], v[146:149], v[218:221], v[36:39]
	v_mfma_f32_16x16x32_bf16 v[32:35], v[154:157], v[218:221], v[32:35]
	v_mfma_f32_16x16x32_bf16 v[60:63], v[150:153], v[166:169], v[60:63]
	v_mfma_f32_16x16x32_bf16 v[56:59], v[158:161], v[166:169], v[56:59]
	v_mfma_f32_16x16x32_bf16 v[52:55], v[150:153], v[174:177], v[52:55]
	v_mfma_f32_16x16x32_bf16 v[48:51], v[158:161], v[174:177], v[48:51]
	v_mfma_f32_16x16x32_bf16 v[44:47], v[150:153], v[182:185], v[44:47]
	v_mfma_f32_16x16x32_bf16 v[40:43], v[158:161], v[182:185], v[40:43]
	v_mfma_f32_16x16x32_bf16 v[36:39], v[150:153], v[222:225], v[36:39]
	v_mfma_f32_16x16x32_bf16 v[32:35], v[158:161], v[222:225], v[32:35]
	s_barrier
	s_setprio 0
	s_add_i32 s51, s51, s34
	v_lshl_add_u64 v[202:203], s[24:25], 0, v[190:191]
	s_mov_b32 m0, s51
	ds_read_b128 v[162:165], v227 offset:16384
	ds_read_b128 v[166:169], v227 offset:17408
	ds_read_b128 v[170:173], v227 offset:18432
	ds_read_b128 v[174:177], v227 offset:19456
	ds_read_b128 v[178:181], v227 offset:20480
	ds_read_b128 v[182:185], v227 offset:21504
	ds_read_b128 v[218:221], v227 offset:22528
	ds_read_b128 v[222:225], v227 offset:23552
	global_load_lds_dwordx4 v[202:203], off
	s_add_i32 m0, s51, 0x2000
	s_add_u32 s52, s24, 0x40000
	v_lshl_add_u64 v[206:207], s[24:25], 0, v[186:187]
	s_addc_u32 s53, s25, 0
	s_add_i32 s51, s54, s34
	global_load_lds_dwordx4 v[206:207], off
	v_lshl_add_u64 v[208:209], s[52:53], 0, v[190:191]
	s_mov_b32 m0, s51
	v_lshl_add_u64 v[214:215], s[26:27], 0, v[188:189]
	global_load_lds_dwordx4 v[208:209], off
	s_add_i32 m0, s51, 0x2000
	v_lshl_add_u64 v[208:209], s[52:53], 0, v[186:187]
	global_load_lds_dwordx4 v[208:209], off
	s_mov_b32 m0, s35
	v_lshl_add_u64 v[208:209], s[26:27], 0, v[192:193]
	global_load_lds_dwordx4 v[208:209], off
	s_mov_b32 m0, s39
	s_nop 0
	global_load_lds_dwordx4 v[214:215], off
	s_waitcnt vmcnt(8) lgkmcnt(0)
	s_setprio 1
	s_barrier
; #define PG8_STAGE(bufoff, gbase, voff) do { _Pragma("unroll") for (int _i = 0; _i < 2; ++_i) \
;         __builtin_amdgcn_global_load_lds((const unsigned*)((const char*)(gbase) + (voff)[_i]), (PG8_LAS unsigned*)(lds + (bufoff) + ldsw + _i * 8192), 16, 0, 0); } while (0)
; #define PG8_LDA(dst, b, h) do { _Pragma("unroll") for (int m = 0; m < 4; ++m) _Pragma("unroll") for (int k = 0; k < 2; ++k) dst[m][k] = *(const PG8_LAS bf16x8*)(lds + PG8_SA(b, h) + aoff + m * 2048 + k * 1024); } while (0)
; #define PG8_LDB(dst, b, h) do { _Pragma("unroll") for (int n = 0; n < 2; ++n) _Pragma("unroll") for (int k = 0; k < 2; ++k) dst[n][k] = *(const PG8_LAS bf16x8*)(lds + PG8_SB(b, h) + boff + n * 2048 + k * 1024); } while (0)
; #define PG8_MMA(ai, bj, At, Bt) do { __builtin_amdgcn_s_setprio(1); _Pragma("unroll") for (int m = 0; m < 4; ++m) _Pragma("unroll") for (int n = 0; n < 2; ++n) _Pragma("unroll") for (int k = 0; k < 2; ++k) \
;         acc[ai][bj][m][n] = __builtin_amdgcn_mfma_f32_16x16x32_bf16(Bt[n][k], At[m][k], acc[ai][bj][m][n], 0, 0, 0); __builtin_amdgcn_s_setprio(0); } while (0)
; #define PG8_WAIT_V(n) asm volatile("s_waitcnt vmcnt(" #n ")" ::: "memory")
; #define PG8_WAIT_L(n) asm volatile("s_waitcnt lgkmcnt(" #n ")" ::: "memory")
; #define PG8_BAR __builtin_amdgcn_s_barrier()
; #define PG8_SCHED __builtin_amdgcn_sched_barrier(0)
; template <class Epi, class Sched, bool ALIGN_EPI = false, bool SP2 = false>
; __device__ __forceinline__ void gemm_phase(PG8_LAS unsigned char* lds, const Gemm g, const Sched& S, const Epi& E, const int tid) {
;     ...
;             PG8_WAIT_V(8); PG8_WAIT_L(0); PG8_BAR; PG8_MMA(1, 0, At, B0); PG8_MMA(1, 1, At, B1); PG8_BAR; PG8_SCHED;
;             PG8_LDB(B0, 1, 0); PG8_LDB(B1, 1, 1); PG8_SCHED; PG8_LDA(At, 1, 0); PG8_STAGE(PG8_SA(0, 1), a2 + hstep, voffA);
;             PG8_WAIT_V(8); PG8_WAIT_L(0); PG8_BAR; PG8_MMA(0, 0, At, B0); PG8_MMA(0, 1, At, B1); PG8_BAR; PG8_SCHED;
	v_mfma_f32_16x16x32_bf16 v[94:97], v[130:133], v[162:165], v[94:97]
	v_mfma_f32_16x16x32_bf16 v[90:93], v[138:141], v[162:165], v[90:93]
	v_mfma_f32_16x16x32_bf16 v[86:89], v[130:133], v[170:173], v[86:89]
	v_mfma_f32_16x16x32_bf16 v[82:85], v[138:141], v[170:173], v[82:85]
	v_mfma_f32_16x16x32_bf16 v[78:81], v[130:133], v[178:181], v[78:81]
	v_mfma_f32_16x16x32_bf16 v[74:77], v[138:141], v[178:181], v[74:77]
	v_mfma_f32_16x16x32_bf16 v[70:73], v[130:133], v[218:221], v[70:73]
	v_mfma_f32_16x16x32_bf16 v[66:69], v[138:141], v[218:221], v[66:69]
	v_mfma_f32_16x16x32_bf16 v[94:97], v[134:137], v[166:169], v[94:97]
	v_mfma_f32_16x16x32_bf16 v[90:93], v[142:145], v[166:169], v[90:93]
	v_mfma_f32_16x16x32_bf16 v[86:89], v[134:137], v[174:177], v[86:89]
	v_mfma_f32_16x16x32_bf16 v[82:85], v[142:145], v[174:177], v[82:85]
	v_mfma_f32_16x16x32_bf16 v[78:81], v[134:137], v[182:185], v[78:81]
	v_mfma_f32_16x16x32_bf16 v[74:77], v[142:145], v[182:185], v[74:77]
	v_mfma_f32_16x16x32_bf16 v[70:73], v[134:137], v[222:225], v[70:73]
	v_mfma_f32_16x16x32_bf16 v[66:69], v[142:145], v[222:225], v[66:69]
	v_mfma_f32_16x16x32_bf16 v[28:31], v[146:149], v[162:165], v[28:31]
	v_mfma_f32_16x16x32_bf16 v[24:27], v[154:157], v[162:165], v[24:27]
	v_mfma_f32_16x16x32_bf16 v[20:23], v[146:149], v[170:173], v[20:23]
	v_mfma_f32_16x16x32_bf16 v[16:19], v[154:157], v[170:173], v[16:19]
	v_mfma_f32_16x16x32_bf16 v[12:15], v[146:149], v[178:181], v[12:15]
	v_mfma_f32_16x16x32_bf16 v[8:11], v[154:157], v[178:181], v[8:11]
	v_mfma_f32_16x16x32_bf16 v[4:7], v[146:149], v[218:221], v[4:7]
	v_mfma_f32_16x16x32_bf16 v[0:3], v[154:157], v[218:221], v[0:3]
	v_mfma_f32_16x16x32_bf16 v[28:31], v[150:153], v[166:169], v[28:31]
	v_mfma_f32_16x16x32_bf16 v[24:27], v[158:161], v[166:169], v[24:27]
	v_mfma_f32_16x16x32_bf16 v[20:23], v[150:153], v[174:177], v[20:23]
	v_mfma_f32_16x16x32_bf16 v[16:19], v[158:161], v[174:177], v[16:19]
	v_mfma_f32_16x16x32_bf16 v[12:15], v[150:153], v[182:185], v[12:15]
	v_mfma_f32_16x16x32_bf16 v[8:11], v[158:161], v[182:185], v[8:11]
	v_mfma_f32_16x16x32_bf16 v[4:7], v[150:153], v[222:225], v[4:7]
	v_mfma_f32_16x16x32_bf16 v[0:3], v[158:161], v[222:225], v[0:3]
	s_barrier
	s_setprio 0
	s_add_i32 s51, 0, 0x18000
	v_add_u32_e32 v64, s51, v213
	s_add_i32 s52, 0, 0x1c000
	ds_read_b128 v[130:133], v64
	ds_read_b128 v[134:137], v64 offset:1024
	ds_read_b128 v[138:141], v64 offset:2048
	ds_read_b128 v[142:145], v64 offset:3072
	v_add_u32_e32 v64, s52, v213
	ds_read_b128 v[146:149], v64
	ds_read_b128 v[150:153], v64 offset:1024
	ds_read_b128 v[154:157], v64 offset:2048
	ds_read_b128 v[158:161], v64 offset:3072
	s_add_u32 s26, s26, 0x40000
	s_addc_u32 s27, s27, 0
	s_mov_b32 m0, s42
	v_lshl_add_u64 v[228:229], s[26:27], 0, v[192:193]
	ds_read_b128 v[162:165], v227 offset:32768
	ds_read_b128 v[166:169], v227 offset:33792
	ds_read_b128 v[170:173], v227 offset:34816
	ds_read_b128 v[174:177], v227 offset:35840
	ds_read_b128 v[178:181], v227 offset:36864
	ds_read_b128 v[182:185], v227 offset:37888
	ds_read_b128 v[218:221], v227 offset:38912
	ds_read_b128 v[222:225], v227 offset:39936
	global_load_lds_dwordx4 v[228:229], off
	s_mov_b32 m0, s43
	v_lshl_add_u64 v[228:229], s[26:27], 0, v[188:189]
	global_load_lds_dwordx4 v[228:229], off
	s_waitcnt vmcnt(8) lgkmcnt(0)
	s_setprio 1
	s_barrier
	v_mfma_f32_16x16x32_bf16 v[126:129], v[130:133], v[162:165], v[126:129]
	v_mfma_f32_16x16x32_bf16 v[122:125], v[138:141], v[162:165], v[122:125]
	v_mfma_f32_16x16x32_bf16 v[118:121], v[130:133], v[170:173], v[118:121]
	v_mfma_f32_16x16x32_bf16 v[114:117], v[138:141], v[170:173], v[114:117]
	v_mfma_f32_16x16x32_bf16 v[110:113], v[130:133], v[178:181], v[110:113]
	v_mfma_f32_16x16x32_bf16 v[106:109], v[138:141], v[178:181], v[106:109]
	v_mfma_f32_16x16x32_bf16 v[102:105], v[130:133], v[218:221], v[102:105]
	v_mfma_f32_16x16x32_bf16 v[98:101], v[138:141], v[218:221], v[98:101]
	v_mfma_f32_16x16x32_bf16 v[126:129], v[134:137], v[166:169], v[126:129]
	v_mfma_f32_16x16x32_bf16 v[122:125], v[142:145], v[166:169], v[122:125]
	v_mfma_f32_16x16x32_bf16 v[118:121], v[134:137], v[174:177], v[118:121]
	v_mfma_f32_16x16x32_bf16 v[114:117], v[142:145], v[174:177], v[114:117]
	v_mfma_f32_16x16x32_bf16 v[110:113], v[134:137], v[182:185], v[110:113]
	v_mfma_f32_16x16x32_bf16 v[106:109], v[142:145], v[182:185], v[106:109]
	v_mfma_f32_16x16x32_bf16 v[102:105], v[134:137], v[222:225], v[102:105]
	v_mfma_f32_16x16x32_bf16 v[98:101], v[142:145], v[222:225], v[98:101]
	v_mfma_f32_16x16x32_bf16 v[60:63], v[146:149], v[162:165], v[60:63]
	v_mfma_f32_16x16x32_bf16 v[56:59], v[154:157], v[162:165], v[56:59]
	v_mfma_f32_16x16x32_bf16 v[52:55], v[146:149], v[170:173], v[52:55]
	v_mfma_f32_16x16x32_bf16 v[48:51], v[154:157], v[170:173], v[48:51]
	v_mfma_f32_16x16x32_bf16 v[44:47], v[146:149], v[178:181], v[44:47]
	v_mfma_f32_16x16x32_bf16 v[40:43], v[154:157], v[178:181], v[40:43]
	v_mfma_f32_16x16x32_bf16 v[36:39], v[146:149], v[218:221], v[36:39]
	v_mfma_f32_16x16x32_bf16 v[32:35], v[154:157], v[218:221], v[32:35]
	v_mfma_f32_16x16x32_bf16 v[60:63], v[150:153], v[166:169], v[60:63]
	v_mfma_f32_16x16x32_bf16 v[56:59], v[158:161], v[166:169], v[56:59]
	v_mfma_f32_16x16x32_bf16 v[52:55], v[150:153], v[174:177], v[52:55]
	v_mfma_f32_16x16x32_bf16 v[48:51], v[158:161], v[174:177], v[48:51]
	v_mfma_f32_16x16x32_bf16 v[44:47], v[150:153], v[182:185], v[44:47]
	v_mfma_f32_16x16x32_bf16 v[40:43], v[158:161], v[182:185], v[40:43]
	v_mfma_f32_16x16x32_bf16 v[36:39], v[150:153], v[222:225], v[36:39]
	v_mfma_f32_16x16x32_bf16 v[32:35], v[158:161], v[222:225], v[32:35]
	s_barrier
; #define PG8_STAGE(bufoff, gbase, voff) do { _Pragma("unroll") for (int _i = 0; _i < 2; ++_i) \
;         __builtin_amdgcn_global_load_lds((const unsigned*)((const char*)(gbase) + (voff)[_i]), (PG8_LAS unsigned*)(lds + (bufoff) + ldsw + _i * 8192), 16, 0, 0); } while (0)
; #define PG8_LDA(dst, b, h) do { _Pragma("unroll") for (int m = 0; m < 4; ++m) _Pragma("unroll") for (int k = 0; k < 2; ++k) dst[m][k] = *(const PG8_LAS bf16x8*)(lds + PG8_SA(b, h) + aoff + m * 2048 + k * 1024); } while (0)
; #define PG8_MMA(ai, bj, At, Bt) do { __builtin_amdgcn_s_setprio(1); _Pragma("unroll") for (int m = 0; m < 4; ++m) _Pragma("unroll") for (int n = 0; n < 2; ++n) _Pragma("unroll") for (int k = 0; k < 2; ++k) \
;         acc[ai][bj][m][n] = __builtin_amdgcn_mfma_f32_16x16x32_bf16(Bt[n][k], At[m][k], acc[ai][bj][m][n], 0, 0, 0); __builtin_amdgcn_s_setprio(0); } while (0)
; #define PG8_WAIT_V(n) asm volatile("s_waitcnt vmcnt(" #n ")" ::: "memory")
; #define PG8_WAIT_L(n) asm volatile("s_waitcnt lgkmcnt(" #n ")" ::: "memory")
; #define PG8_BAR __builtin_amdgcn_s_barrier()
; #define PG8_SCHED __builtin_amdgcn_sched_barrier(0)
; template <class Epi, class Sched, bool ALIGN_EPI = false, bool SP2 = false>
; __device__ __forceinline__ void gemm_phase(PG8_LAS unsigned char* lds, const Gemm g, const Sched& S, const Epi& E, const int tid) {
;     ...
;             PG8_LDA(At, 1, 1); PG8_STAGE(PG8_SB(1, 0), b3, voffB); PG8_STAGE(PG8_SB(1, 1), b3 + hstep, voffB); PG8_STAGE(PG8_SA(1, 0), a3, voffA);
;             PG8_WAIT_V(8); PG8_WAIT_L(0); PG8_BAR; PG8_MMA(1, 0, At, B0); PG8_MMA(1, 1, At, B1); PG8_BAR; PG8_SCHED;
	s_setprio 0
	s_add_i32 s26, s51, s34
	v_lshl_add_u64 v[202:203], v[202:203], 0, s[94:95]
	s_mov_b32 m0, s26
	ds_read_b128 v[162:165], v227 offset:49152
	ds_read_b128 v[166:169], v227 offset:50176
	ds_read_b128 v[170:173], v227 offset:51200
	ds_read_b128 v[174:177], v227 offset:52224
	ds_read_b128 v[178:181], v227 offset:53248
	ds_read_b128 v[182:185], v227 offset:54272
	ds_read_b128 v[218:221], v227 offset:55296
	ds_read_b128 v[222:225], v227 offset:56320
	global_load_lds_dwordx4 v[202:203], off
	s_add_i32 m0, s26, 0x2000
	s_add_u32 s24, s24, 0x40080
	v_lshl_add_u64 v[202:203], v[206:207], 0, s[94:95]
	s_addc_u32 s25, s25, 0
	s_add_i32 s26, s52, s34
	global_load_lds_dwordx4 v[202:203], off
	s_mov_b32 m0, s26
	v_lshl_add_u64 v[202:203], s[24:25], 0, v[190:191]
	global_load_lds_dwordx4 v[202:203], off
	s_add_i32 m0, s26, 0x2000
	v_lshl_add_u64 v[202:203], s[24:25], 0, v[186:187]
	global_load_lds_dwordx4 v[202:203], off
	s_mov_b32 m0, s38
	v_lshl_add_u64 v[202:203], v[208:209], 0, s[94:95]
	global_load_lds_dwordx4 v[202:203], off
	s_mov_b32 m0, s44
	v_lshl_add_u64 v[202:203], v[214:215], 0, s[94:95]
	global_load_lds_dwordx4 v[202:203], off
	s_waitcnt vmcnt(8) lgkmcnt(0)
	s_setprio 1
	s_barrier
	v_mfma_f32_16x16x32_bf16 v[94:97], v[130:133], v[162:165], v[94:97]
	v_mfma_f32_16x16x32_bf16 v[90:93], v[138:141], v[162:165], v[90:93]
	v_mfma_f32_16x16x32_bf16 v[86:89], v[130:133], v[170:173], v[86:89]
	v_mfma_f32_16x16x32_bf16 v[82:85], v[138:141], v[170:173], v[82:85]
	v_mfma_f32_16x16x32_bf16 v[78:81], v[130:133], v[178:181], v[78:81]
	v_mfma_f32_16x16x32_bf16 v[74:77], v[138:141], v[178:181], v[74:77]
	v_mfma_f32_16x16x32_bf16 v[70:73], v[130:133], v[218:221], v[70:73]
	v_mfma_f32_16x16x32_bf16 v[66:69], v[138:141], v[218:221], v[66:69]
	v_mfma_f32_16x16x32_bf16 v[94:97], v[134:137], v[166:169], v[94:97]
	v_mfma_f32_16x16x32_bf16 v[90:93], v[142:145], v[166:169], v[90:93]
	v_mfma_f32_16x16x32_bf16 v[86:89], v[134:137], v[174:177], v[86:89]
	v_mfma_f32_16x16x32_bf16 v[82:85], v[142:145], v[174:177], v[82:85]
	v_mfma_f32_16x16x32_bf16 v[78:81], v[134:137], v[182:185], v[78:81]
	v_mfma_f32_16x16x32_bf16 v[74:77], v[142:145], v[182:185], v[74:77]
	v_mfma_f32_16x16x32_bf16 v[70:73], v[134:137], v[222:225], v[70:73]
	v_mfma_f32_16x16x32_bf16 v[66:69], v[142:145], v[222:225], v[66:69]
	v_mfma_f32_16x16x32_bf16 v[28:31], v[146:149], v[162:165], v[28:31]
	v_mfma_f32_16x16x32_bf16 v[24:27], v[154:157], v[162:165], v[24:27]
	v_mfma_f32_16x16x32_bf16 v[20:23], v[146:149], v[170:173], v[20:23]
	v_mfma_f32_16x16x32_bf16 v[16:19], v[154:157], v[170:173], v[16:19]
	v_mfma_f32_16x16x32_bf16 v[12:15], v[146:149], v[178:181], v[12:15]
	v_mfma_f32_16x16x32_bf16 v[8:11], v[154:157], v[178:181], v[8:11]
	v_mfma_f32_16x16x32_bf16 v[4:7], v[146:149], v[218:221], v[4:7]
	v_mfma_f32_16x16x32_bf16 v[0:3], v[154:157], v[218:221], v[0:3]
	v_mfma_f32_16x16x32_bf16 v[28:31], v[150:153], v[166:169], v[28:31]
	v_mfma_f32_16x16x32_bf16 v[24:27], v[158:161], v[166:169], v[24:27]
	v_mfma_f32_16x16x32_bf16 v[20:23], v[150:153], v[174:177], v[20:23]
	v_mfma_f32_16x16x32_bf16 v[16:19], v[158:161], v[174:177], v[16:19]
	v_mfma_f32_16x16x32_bf16 v[12:15], v[150:153], v[182:185], v[12:15]
	v_mfma_f32_16x16x32_bf16 v[8:11], v[158:161], v[182:185], v[8:11]
	v_mfma_f32_16x16x32_bf16 v[4:7], v[150:153], v[222:225], v[4:7]
	v_mfma_f32_16x16x32_bf16 v[0:3], v[158:161], v[222:225], v[0:3]
	s_barrier
	s_setprio 0
	s_add_i32 s50, s50, 2
	s_add_u32 s48, s48, 0x100
	s_addc_u32 s49, s49, 0
	s_add_u32 s2, s2, 0x100
	s_addc_u32 s3, s3, 0
	s_cmp_gt_u32 s50, 13
	s_cbranch_scc0 .LBB0_704
	s_and_b64 vcc, exec, s[12:13]
	s_cbranch_vccz .LBB0_707
	s_barrier
